# speedup vs baseline: 1.0676x; 1.0287x over previous
; #define ARGMAX_STEP(CTRL) { const float ov = dppf<CTRL>(best); const int oc = dppi<CTRL>(bc);                \
;           const bool take = ov > best || (ov == best && oc < bc); best = take ? ov : best; bc = take ? oc : bc; }
; static __device__ __forceinline__ void phase_peer(const Params& p, char* smraw) {
;     ...
;   for (int t = blockIdx.x * 4 + w; t < T; t += gridDim.x * 4) {
;     const float* x1 = X1 + (size_t)t * 1024;
;     const float rs = ((const float*)(p.ws + WS_RSQQ))[t];
;     {
;       const int head = lane >> 3, g = lane & 7;
;       const float* tvp = TV + ((size_t)t * 16 + head * 2) * 16;
;       float cand[7]; int ccode[7];
; #pragma unroll
;       for (int m = 0; m < 7; ++m) {
;         ccode[m] = pkc[m];
;         cand[m] = ccode[m] == 255 ? -3.0e38f : tvp[ccode[m] >> 4] + tvp[16 + (ccode[m] & 15)];
;       }
;       float myv[2] = {0.f, 0.f}; int myc[2] = {0, 0}; float vmax = 0.f;
; #pragma unroll
;       for (int round = 0; round < 16; ++round) {
;         float best = cand[0]; int bc = ccode[0];
; #pragma unroll
;         for (int m = 1; m < 7; ++m) if (cand[m] > best) { best = cand[m]; bc = ccode[m]; }
;     ...
;         ARGMAX_STEP(0xB1) ARGMAX_STEP(0x4E) ARGMAX_STEP(0x141)
.LBB0_754:
	v_readlane_b32 s36, v224, 33
	v_ashrrev_i32_e32 v57, 31, v56
	v_readlane_b32 s37, v224, 34
	v_mov_b32_e32 v4, 0xff61b1e6
	s_nop 0
	v_lshl_add_u64 v[0:1], v[56:57], 2, s[36:37]
	global_load_dword v36, v[0:1], off
	v_lshlrev_b64 v[0:1], 8, v[56:57]
	v_or_b32_e32 v0, v0, v60
	v_lshlrev_b32_e32 v2, 2, v0
	v_add_u32_e32 v12, v2, v72
	v_add_u32_e32 v19, v2, v70
	v_add_u32_e32 v13, v2, v76
	v_add_u32_e32 v20, v2, v74
	v_add_u32_e32 v14, v2, v80
	v_add_u32_e32 v21, v2, v78
	v_add_u32_e32 v15, v2, v84
	v_add_u32_e32 v22, v2, v82
	v_add_u32_e32 v16, v2, v88
	v_add_u32_e32 v23, v2, v86
	v_add_u32_e32 v17, v2, v92
	v_add_u32_e32 v24, v2, v90
	v_add_u32_e32 v18, v2, v96
	v_add_u32_e32 v25, v2, v94
	global_load_dword v12, v12, s[44:45]
	global_load_dword v19, v19, s[44:45] offset:64
	global_load_dword v13, v13, s[44:45]
	global_load_dword v20, v20, s[44:45] offset:64
	global_load_dword v14, v14, s[44:45]
	global_load_dword v21, v21, s[44:45] offset:64
	global_load_dword v15, v15, s[44:45]
	global_load_dword v22, v22, s[44:45] offset:64
	global_load_dword v16, v16, s[44:45]
	global_load_dword v23, v23, s[44:45] offset:64
	global_load_dword v17, v17, s[44:45]
	global_load_dword v24, v24, s[44:45] offset:64
	global_load_dword v18, v18, s[44:45]
	global_load_dword v25, v25, s[44:45] offset:64
	s_waitcnt vmcnt(0)
	v_add_f32_e32 v4, v12, v19
	v_add_f32_e32 v5, v13, v20
	v_add_f32_e32 v8, v14, v21
	v_add_f32_e32 v7, v15, v22
	v_add_f32_e32 v10, v16, v23
	v_add_f32_e32 v9, v17, v24
	v_add_f32_e32 v11, v18, v25
	v_cndmask_b32_e64 v4, v201, v4, s[20:21]
	v_cndmask_b32_e64 v5, v201, v5, s[22:23]
	v_cndmask_b32_e64 v8, v201, v8, s[24:25]
	v_cndmask_b32_e64 v7, v201, v7, s[26:27]
	v_cndmask_b32_e64 v10, v201, v10, s[28:29]
	v_cndmask_b32_e64 v9, v201, v9, s[30:31]
	v_cndmask_b32_e64 v11, v201, v11, s[34:35]
	v_sub_u32_e32 v12, 0xff, v61
	v_ashrrev_i32_e32 v30, 31, v4
	v_or_b32_e32 v30, 0x80000000, v30
	v_xor_b32_e32 v13, v4, v30
	v_sub_u32_e32 v14, 0xff, v175
	v_ashrrev_i32_e32 v30, 31, v5
	v_or_b32_e32 v30, 0x80000000, v30
	v_xor_b32_e32 v15, v5, v30
	v_sub_u32_e32 v16, 0xff, v180
	v_ashrrev_i32_e32 v30, 31, v8
	v_or_b32_e32 v30, 0x80000000, v30
	v_xor_b32_e32 v17, v8, v30
	v_sub_u32_e32 v18, 0xff, v181
	v_ashrrev_i32_e32 v30, 31, v7
	v_or_b32_e32 v30, 0x80000000, v30
	v_xor_b32_e32 v19, v7, v30
	v_sub_u32_e32 v20, 0xff, v182
	v_ashrrev_i32_e32 v30, 31, v10
	v_or_b32_e32 v30, 0x80000000, v30
	v_xor_b32_e32 v21, v10, v30
	v_sub_u32_e32 v22, 0xff, v183
	v_ashrrev_i32_e32 v30, 31, v9
	v_or_b32_e32 v30, 0x80000000, v30
	v_xor_b32_e32 v23, v9, v30
	v_sub_u32_e32 v24, 0xff, v184
	v_ashrrev_i32_e32 v30, 31, v11
	v_or_b32_e32 v30, 0x80000000, v30
	v_xor_b32_e32 v25, v11, v30
	v_cmp_gt_u64_e32 vcc, v[24:25], v[12:13]
	s_and_saveexec_b64 s[36:37], vcc
	v_swap_b32 v12, v24
	v_swap_b32 v13, v25
	s_mov_b64 exec, s[36:37]
	v_cmp_gt_u64_e32 vcc, v[18:19], v[16:17]
	s_and_saveexec_b64 s[36:37], vcc
	v_swap_b32 v16, v18
	v_swap_b32 v17, v19
	s_mov_b64 exec, s[36:37]
	v_cmp_gt_u64_e32 vcc, v[22:23], v[20:21]
	s_and_saveexec_b64 s[36:37], vcc
	v_swap_b32 v20, v22
	v_swap_b32 v21, v23
	s_mov_b64 exec, s[36:37]
	v_cmp_gt_u64_e32 vcc, v[16:17], v[12:13]
	s_and_saveexec_b64 s[36:37], vcc
	v_swap_b32 v12, v16
	v_swap_b32 v13, v17
	s_mov_b64 exec, s[36:37]
	v_cmp_gt_u64_e32 vcc, v[20:21], v[14:15]
	s_and_saveexec_b64 s[36:37], vcc
	v_swap_b32 v14, v20
	v_swap_b32 v15, v21
	s_mov_b64 exec, s[36:37]
	v_cmp_gt_u64_e32 vcc, v[24:25], v[18:19]
	s_and_saveexec_b64 s[36:37], vcc
	v_swap_b32 v18, v24
	v_swap_b32 v19, v25
	s_mov_b64 exec, s[36:37]
	v_cmp_gt_u64_e32 vcc, v[14:15], v[12:13]
	s_and_saveexec_b64 s[36:37], vcc
	v_swap_b32 v12, v14
	v_swap_b32 v13, v15
	s_mov_b64 exec, s[36:37]
	v_cmp_gt_u64_e32 vcc, v[22:23], v[16:17]
	s_and_saveexec_b64 s[36:37], vcc
	v_swap_b32 v16, v22
	v_swap_b32 v17, v23
	s_mov_b64 exec, s[36:37]
	v_cmp_gt_u64_e32 vcc, v[20:21], v[18:19]
	s_and_saveexec_b64 s[36:37], vcc
	v_swap_b32 v18, v20
	v_swap_b32 v19, v21
	s_mov_b64 exec, s[36:37]
	v_cmp_gt_u64_e32 vcc, v[16:17], v[14:15]
	s_and_saveexec_b64 s[36:37], vcc
	v_swap_b32 v14, v16
	v_swap_b32 v15, v17
	s_mov_b64 exec, s[36:37]
	v_cmp_gt_u64_e32 vcc, v[24:25], v[20:21]
	s_and_saveexec_b64 s[36:37], vcc
	v_swap_b32 v20, v24
	v_swap_b32 v21, v25
	s_mov_b64 exec, s[36:37]
	v_cmp_gt_u64_e32 vcc, v[18:19], v[16:17]
	s_and_saveexec_b64 s[36:37], vcc
	v_swap_b32 v16, v18
	v_swap_b32 v17, v19
	s_mov_b64 exec, s[36:37]
	v_cmp_gt_u64_e32 vcc, v[22:23], v[20:21]
	s_and_saveexec_b64 s[36:37], vcc
	v_swap_b32 v20, v22
	v_swap_b32 v21, v23
	s_mov_b64 exec, s[36:37]
	v_cmp_gt_u64_e32 vcc, v[16:17], v[14:15]
	s_and_saveexec_b64 s[36:37], vcc
	v_swap_b32 v14, v16
	v_swap_b32 v15, v17
	s_mov_b64 exec, s[36:37]
	v_cmp_gt_u64_e32 vcc, v[20:21], v[18:19]
	s_and_saveexec_b64 s[36:37], vcc
	v_swap_b32 v18, v20
	v_swap_b32 v19, v21
	s_mov_b64 exec, s[36:37]
	v_cmp_gt_u64_e32 vcc, v[24:25], v[22:23]
	s_and_saveexec_b64 s[36:37], vcc
	v_swap_b32 v22, v24
	v_swap_b32 v23, v25
	s_mov_b64 exec, s[36:37]
	s_nop 1
	v_mov_b32_dpp v28, v12 quad_perm:[1,0,3,2] row_mask:0xf bank_mask:0xf bound_ctrl:1
	v_mov_b32_dpp v29, v13 quad_perm:[1,0,3,2] row_mask:0xf bank_mask:0xf bound_ctrl:1
	v_cmp_gt_u64_e32 vcc, v[28:29], v[12:13]
	s_nop 1
	v_cndmask_b32_e32 v26, v12, v28, vcc
	v_cndmask_b32_e32 v27, v13, v29, vcc
	s_nop 1
	v_mov_b32_dpp v28, v26 quad_perm:[2,3,0,1] row_mask:0xf bank_mask:0xf bound_ctrl:1
	v_mov_b32_dpp v29, v27 quad_perm:[2,3,0,1] row_mask:0xf bank_mask:0xf bound_ctrl:1
	v_cmp_gt_u64_e32 vcc, v[28:29], v[26:27]
	s_nop 1
	v_cndmask_b32_e32 v26, v26, v28, vcc
	v_cndmask_b32_e32 v27, v27, v29, vcc
	s_nop 1
; #define ARGMAX_STEP(CTRL) { const float ov = dppf<CTRL>(best); const int oc = dppi<CTRL>(bc);                \
;           const bool take = ov > best || (ov == best && oc < bc); best = take ? ov : best; bc = take ? oc : bc; }
; static __device__ __forceinline__ void phase_peer(const Params& p, char* smraw) {
;     ...
;       for (int round = 0; round < 16; ++round) {
;         float best = cand[0]; int bc = ccode[0];
; #pragma unroll
;         for (int m = 1; m < 7; ++m) if (cand[m] > best) { best = cand[m]; bc = ccode[m]; }
;     ...
;         ARGMAX_STEP(0xB1) ARGMAX_STEP(0x4E) ARGMAX_STEP(0x141)
;     ...
; #pragma unroll
;         for (int m = 0; m < 7; ++m) cand[m] = ccode[m] == bc ? -3.0e38f : cand[m];
;         if (round == 0) vmax = best;
;         if ((round & 7) == g) { myv[round >> 3] = best; myc[round >> 3] = bc; }
;       }
	v_mov_b32_dpp v28, v26 row_half_mirror row_mask:0xf bank_mask:0xf bound_ctrl:1
	v_mov_b32_dpp v29, v27 row_half_mirror row_mask:0xf bank_mask:0xf bound_ctrl:1
	v_cmp_gt_u64_e32 vcc, v[28:29], v[26:27]
	s_nop 1
	v_cndmask_b32_e32 v26, v26, v28, vcc
	v_cndmask_b32_e32 v27, v27, v29, vcc
	v_mov_b32_e32 v38, v27
	v_cndmask_b32_e64 v32, v32, v26, s[2:3]
	v_cndmask_b32_e64 v33, v33, v27, s[2:3]
	v_cmp_eq_u64_e32 vcc, v[12:13], v[26:27]
	s_and_saveexec_b64 s[36:37], vcc
	v_mov_b64_e32 v[12:13], v[14:15]
	v_mov_b64_e32 v[14:15], v[16:17]
	v_mov_b64_e32 v[16:17], v[18:19]
	v_mov_b64_e32 v[18:19], v[20:21]
	v_mov_b64_e32 v[20:21], v[22:23]
	v_mov_b64_e32 v[22:23], v[24:25]
	v_mov_b64_e32 v[24:25], 0
	s_mov_b64 exec, s[36:37]
	v_mov_b32_dpp v28, v12 quad_perm:[1,0,3,2] row_mask:0xf bank_mask:0xf bound_ctrl:1
	v_mov_b32_dpp v29, v13 quad_perm:[1,0,3,2] row_mask:0xf bank_mask:0xf bound_ctrl:1
	v_cmp_gt_u64_e32 vcc, v[28:29], v[12:13]
	s_nop 1
	v_cndmask_b32_e32 v26, v12, v28, vcc
	v_cndmask_b32_e32 v27, v13, v29, vcc
	s_nop 1
	v_mov_b32_dpp v28, v26 quad_perm:[2,3,0,1] row_mask:0xf bank_mask:0xf bound_ctrl:1
	v_mov_b32_dpp v29, v27 quad_perm:[2,3,0,1] row_mask:0xf bank_mask:0xf bound_ctrl:1
	v_cmp_gt_u64_e32 vcc, v[28:29], v[26:27]
	s_nop 1
	v_cndmask_b32_e32 v26, v26, v28, vcc
	v_cndmask_b32_e32 v27, v27, v29, vcc
	s_nop 1
	v_mov_b32_dpp v28, v26 row_half_mirror row_mask:0xf bank_mask:0xf bound_ctrl:1
	v_mov_b32_dpp v29, v27 row_half_mirror row_mask:0xf bank_mask:0xf bound_ctrl:1
	v_cmp_gt_u64_e32 vcc, v[28:29], v[26:27]
	s_nop 1
	v_cndmask_b32_e32 v26, v26, v28, vcc
	v_cndmask_b32_e32 v27, v27, v29, vcc
	v_cndmask_b32_e64 v32, v32, v26, s[4:5]
	v_cndmask_b32_e64 v33, v33, v27, s[4:5]
	v_cmp_eq_u64_e32 vcc, v[12:13], v[26:27]
	s_and_saveexec_b64 s[36:37], vcc
	v_mov_b64_e32 v[12:13], v[14:15]
	v_mov_b64_e32 v[14:15], v[16:17]
	v_mov_b64_e32 v[16:17], v[18:19]
	v_mov_b64_e32 v[18:19], v[20:21]
	v_mov_b64_e32 v[20:21], v[22:23]
	v_mov_b64_e32 v[22:23], v[24:25]
	v_mov_b64_e32 v[24:25], 0
	s_mov_b64 exec, s[36:37]
	v_mov_b32_dpp v28, v12 quad_perm:[1,0,3,2] row_mask:0xf bank_mask:0xf bound_ctrl:1
	v_mov_b32_dpp v29, v13 quad_perm:[1,0,3,2] row_mask:0xf bank_mask:0xf bound_ctrl:1
	v_cmp_gt_u64_e32 vcc, v[28:29], v[12:13]
	s_nop 1
	v_cndmask_b32_e32 v26, v12, v28, vcc
	v_cndmask_b32_e32 v27, v13, v29, vcc
	s_nop 1
	v_mov_b32_dpp v28, v26 quad_perm:[2,3,0,1] row_mask:0xf bank_mask:0xf bound_ctrl:1
	v_mov_b32_dpp v29, v27 quad_perm:[2,3,0,1] row_mask:0xf bank_mask:0xf bound_ctrl:1
	v_cmp_gt_u64_e32 vcc, v[28:29], v[26:27]
	s_nop 1
	v_cndmask_b32_e32 v26, v26, v28, vcc
	v_cndmask_b32_e32 v27, v27, v29, vcc
	s_nop 1
	v_mov_b32_dpp v28, v26 row_half_mirror row_mask:0xf bank_mask:0xf bound_ctrl:1
	v_mov_b32_dpp v29, v27 row_half_mirror row_mask:0xf bank_mask:0xf bound_ctrl:1
	v_cmp_gt_u64_e32 vcc, v[28:29], v[26:27]
	s_nop 1
	v_cndmask_b32_e32 v26, v26, v28, vcc
	v_cndmask_b32_e32 v27, v27, v29, vcc
	v_cndmask_b32_e64 v32, v32, v26, s[6:7]
	v_cndmask_b32_e64 v33, v33, v27, s[6:7]
	v_cmp_eq_u64_e32 vcc, v[12:13], v[26:27]
	s_and_saveexec_b64 s[36:37], vcc
	v_mov_b64_e32 v[12:13], v[14:15]
	v_mov_b64_e32 v[14:15], v[16:17]
	v_mov_b64_e32 v[16:17], v[18:19]
	v_mov_b64_e32 v[18:19], v[20:21]
	v_mov_b64_e32 v[20:21], v[22:23]
	v_mov_b64_e32 v[22:23], v[24:25]
	v_mov_b64_e32 v[24:25], 0
	s_mov_b64 exec, s[36:37]
	v_mov_b32_dpp v28, v12 quad_perm:[1,0,3,2] row_mask:0xf bank_mask:0xf bound_ctrl:1
	v_mov_b32_dpp v29, v13 quad_perm:[1,0,3,2] row_mask:0xf bank_mask:0xf bound_ctrl:1
	v_cmp_gt_u64_e32 vcc, v[28:29], v[12:13]
	s_nop 1
	v_cndmask_b32_e32 v26, v12, v28, vcc
	v_cndmask_b32_e32 v27, v13, v29, vcc
	s_nop 1
	v_mov_b32_dpp v28, v26 quad_perm:[2,3,0,1] row_mask:0xf bank_mask:0xf bound_ctrl:1
	v_mov_b32_dpp v29, v27 quad_perm:[2,3,0,1] row_mask:0xf bank_mask:0xf bound_ctrl:1
	v_cmp_gt_u64_e32 vcc, v[28:29], v[26:27]
	s_nop 1
	v_cndmask_b32_e32 v26, v26, v28, vcc
	v_cndmask_b32_e32 v27, v27, v29, vcc
	s_nop 1
	v_mov_b32_dpp v28, v26 row_half_mirror row_mask:0xf bank_mask:0xf bound_ctrl:1
	v_mov_b32_dpp v29, v27 row_half_mirror row_mask:0xf bank_mask:0xf bound_ctrl:1
	v_cmp_gt_u64_e32 vcc, v[28:29], v[26:27]
	s_nop 1
	v_cndmask_b32_e32 v26, v26, v28, vcc
	v_cndmask_b32_e32 v27, v27, v29, vcc
	v_cndmask_b32_e64 v32, v32, v26, s[8:9]
	v_cndmask_b32_e64 v33, v33, v27, s[8:9]
	v_cmp_eq_u64_e32 vcc, v[12:13], v[26:27]
	s_and_saveexec_b64 s[36:37], vcc
	v_mov_b64_e32 v[12:13], v[14:15]
	v_mov_b64_e32 v[14:15], v[16:17]
	v_mov_b64_e32 v[16:17], v[18:19]
	v_mov_b64_e32 v[18:19], v[20:21]
	v_mov_b64_e32 v[20:21], v[22:23]
	v_mov_b64_e32 v[22:23], v[24:25]
	v_mov_b64_e32 v[24:25], 0
	s_mov_b64 exec, s[36:37]
	v_mov_b32_dpp v28, v12 quad_perm:[1,0,3,2] row_mask:0xf bank_mask:0xf bound_ctrl:1
	v_mov_b32_dpp v29, v13 quad_perm:[1,0,3,2] row_mask:0xf bank_mask:0xf bound_ctrl:1
	v_cmp_gt_u64_e32 vcc, v[28:29], v[12:13]
	s_nop 1
	v_cndmask_b32_e32 v26, v12, v28, vcc
	v_cndmask_b32_e32 v27, v13, v29, vcc
	s_nop 1
	v_mov_b32_dpp v28, v26 quad_perm:[2,3,0,1] row_mask:0xf bank_mask:0xf bound_ctrl:1
	v_mov_b32_dpp v29, v27 quad_perm:[2,3,0,1] row_mask:0xf bank_mask:0xf bound_ctrl:1
	v_cmp_gt_u64_e32 vcc, v[28:29], v[26:27]
	s_nop 1
	v_cndmask_b32_e32 v26, v26, v28, vcc
	v_cndmask_b32_e32 v27, v27, v29, vcc
	s_nop 1
	v_mov_b32_dpp v28, v26 row_half_mirror row_mask:0xf bank_mask:0xf bound_ctrl:1
	v_mov_b32_dpp v29, v27 row_half_mirror row_mask:0xf bank_mask:0xf bound_ctrl:1
	v_cmp_gt_u64_e32 vcc, v[28:29], v[26:27]
	s_nop 1
	v_cndmask_b32_e32 v26, v26, v28, vcc
	v_cndmask_b32_e32 v27, v27, v29, vcc
	v_cndmask_b32_e64 v32, v32, v26, s[10:11]
	v_cndmask_b32_e64 v33, v33, v27, s[10:11]
; #define ARGMAX_STEP(CTRL) { const float ov = dppf<CTRL>(best); const int oc = dppi<CTRL>(bc);                \
;           const bool take = ov > best || (ov == best && oc < bc); best = take ? ov : best; bc = take ? oc : bc; }
; static __device__ __forceinline__ void phase_peer(const Params& p, char* smraw) {
;     ...
;       for (int round = 0; round < 16; ++round) {
;         float best = cand[0]; int bc = ccode[0];
; #pragma unroll
;         for (int m = 1; m < 7; ++m) if (cand[m] > best) { best = cand[m]; bc = ccode[m]; }
;     ...
;         ARGMAX_STEP(0xB1) ARGMAX_STEP(0x4E) ARGMAX_STEP(0x141)
;     ...
; #pragma unroll
;         for (int m = 0; m < 7; ++m) cand[m] = ccode[m] == bc ? -3.0e38f : cand[m];
;         if (round == 0) vmax = best;
;         if ((round & 7) == g) { myv[round >> 3] = best; myc[round >> 3] = bc; }
;       }
	v_cmp_eq_u64_e32 vcc, v[12:13], v[26:27]
	s_and_saveexec_b64 s[36:37], vcc
	v_mov_b64_e32 v[12:13], v[14:15]
	v_mov_b64_e32 v[14:15], v[16:17]
	v_mov_b64_e32 v[16:17], v[18:19]
	v_mov_b64_e32 v[18:19], v[20:21]
	v_mov_b64_e32 v[20:21], v[22:23]
	v_mov_b64_e32 v[22:23], v[24:25]
	v_mov_b64_e32 v[24:25], 0
	s_mov_b64 exec, s[36:37]
	v_mov_b32_dpp v28, v12 quad_perm:[1,0,3,2] row_mask:0xf bank_mask:0xf bound_ctrl:1
	v_mov_b32_dpp v29, v13 quad_perm:[1,0,3,2] row_mask:0xf bank_mask:0xf bound_ctrl:1
	v_cmp_gt_u64_e32 vcc, v[28:29], v[12:13]
	s_nop 1
	v_cndmask_b32_e32 v26, v12, v28, vcc
	v_cndmask_b32_e32 v27, v13, v29, vcc
	s_nop 1
	v_mov_b32_dpp v28, v26 quad_perm:[2,3,0,1] row_mask:0xf bank_mask:0xf bound_ctrl:1
	v_mov_b32_dpp v29, v27 quad_perm:[2,3,0,1] row_mask:0xf bank_mask:0xf bound_ctrl:1
	v_cmp_gt_u64_e32 vcc, v[28:29], v[26:27]
	s_nop 1
	v_cndmask_b32_e32 v26, v26, v28, vcc
	v_cndmask_b32_e32 v27, v27, v29, vcc
	s_nop 1
	v_mov_b32_dpp v28, v26 row_half_mirror row_mask:0xf bank_mask:0xf bound_ctrl:1
	v_mov_b32_dpp v29, v27 row_half_mirror row_mask:0xf bank_mask:0xf bound_ctrl:1
	v_cmp_gt_u64_e32 vcc, v[28:29], v[26:27]
	s_nop 1
	v_cndmask_b32_e32 v26, v26, v28, vcc
	v_cndmask_b32_e32 v27, v27, v29, vcc
	v_cndmask_b32_e64 v32, v32, v26, s[12:13]
	v_cndmask_b32_e64 v33, v33, v27, s[12:13]
	v_cmp_eq_u64_e32 vcc, v[12:13], v[26:27]
	s_and_saveexec_b64 s[36:37], vcc
	v_mov_b64_e32 v[12:13], v[14:15]
	v_mov_b64_e32 v[14:15], v[16:17]
	v_mov_b64_e32 v[16:17], v[18:19]
	v_mov_b64_e32 v[18:19], v[20:21]
	v_mov_b64_e32 v[20:21], v[22:23]
	v_mov_b64_e32 v[22:23], v[24:25]
	v_mov_b64_e32 v[24:25], 0
	s_mov_b64 exec, s[36:37]
	v_mov_b32_dpp v28, v12 quad_perm:[1,0,3,2] row_mask:0xf bank_mask:0xf bound_ctrl:1
	v_mov_b32_dpp v29, v13 quad_perm:[1,0,3,2] row_mask:0xf bank_mask:0xf bound_ctrl:1
	v_cmp_gt_u64_e32 vcc, v[28:29], v[12:13]
	s_nop 1
	v_cndmask_b32_e32 v26, v12, v28, vcc
	v_cndmask_b32_e32 v27, v13, v29, vcc
	s_nop 1
	v_mov_b32_dpp v28, v26 quad_perm:[2,3,0,1] row_mask:0xf bank_mask:0xf bound_ctrl:1
	v_mov_b32_dpp v29, v27 quad_perm:[2,3,0,1] row_mask:0xf bank_mask:0xf bound_ctrl:1
	v_cmp_gt_u64_e32 vcc, v[28:29], v[26:27]
	s_nop 1
	v_cndmask_b32_e32 v26, v26, v28, vcc
	v_cndmask_b32_e32 v27, v27, v29, vcc
	s_nop 1
	v_mov_b32_dpp v28, v26 row_half_mirror row_mask:0xf bank_mask:0xf bound_ctrl:1
	v_mov_b32_dpp v29, v27 row_half_mirror row_mask:0xf bank_mask:0xf bound_ctrl:1
	v_cmp_gt_u64_e32 vcc, v[28:29], v[26:27]
	s_nop 1
	v_cndmask_b32_e32 v26, v26, v28, vcc
	v_cndmask_b32_e32 v27, v27, v29, vcc
	v_cndmask_b32_e64 v32, v32, v26, s[14:15]
	v_cndmask_b32_e64 v33, v33, v27, s[14:15]
	v_cmp_eq_u64_e32 vcc, v[12:13], v[26:27]
	s_and_saveexec_b64 s[36:37], vcc
	v_mov_b64_e32 v[12:13], v[14:15]
	v_mov_b64_e32 v[14:15], v[16:17]
	v_mov_b64_e32 v[16:17], v[18:19]
	v_mov_b64_e32 v[18:19], v[20:21]
	v_mov_b64_e32 v[20:21], v[22:23]
	v_mov_b64_e32 v[22:23], v[24:25]
	v_mov_b64_e32 v[24:25], 0
	s_mov_b64 exec, s[36:37]
	v_mov_b32_dpp v28, v12 quad_perm:[1,0,3,2] row_mask:0xf bank_mask:0xf bound_ctrl:1
	v_mov_b32_dpp v29, v13 quad_perm:[1,0,3,2] row_mask:0xf bank_mask:0xf bound_ctrl:1
	v_cmp_gt_u64_e32 vcc, v[28:29], v[12:13]
	s_nop 1
	v_cndmask_b32_e32 v26, v12, v28, vcc
	v_cndmask_b32_e32 v27, v13, v29, vcc
	s_nop 1
	v_mov_b32_dpp v28, v26 quad_perm:[2,3,0,1] row_mask:0xf bank_mask:0xf bound_ctrl:1
	v_mov_b32_dpp v29, v27 quad_perm:[2,3,0,1] row_mask:0xf bank_mask:0xf bound_ctrl:1
	v_cmp_gt_u64_e32 vcc, v[28:29], v[26:27]
	s_nop 1
	v_cndmask_b32_e32 v26, v26, v28, vcc
	v_cndmask_b32_e32 v27, v27, v29, vcc
	s_nop 1
	v_mov_b32_dpp v28, v26 row_half_mirror row_mask:0xf bank_mask:0xf bound_ctrl:1
	v_mov_b32_dpp v29, v27 row_half_mirror row_mask:0xf bank_mask:0xf bound_ctrl:1
	v_cmp_gt_u64_e32 vcc, v[28:29], v[26:27]
	s_nop 1
	v_cndmask_b32_e32 v26, v26, v28, vcc
	v_cndmask_b32_e32 v27, v27, v29, vcc
	v_cndmask_b32_e64 v32, v32, v26, s[16:17]
	v_cndmask_b32_e64 v33, v33, v27, s[16:17]
	v_cmp_eq_u64_e32 vcc, v[12:13], v[26:27]
	s_and_saveexec_b64 s[36:37], vcc
	v_mov_b64_e32 v[12:13], v[14:15]
	v_mov_b64_e32 v[14:15], v[16:17]
	v_mov_b64_e32 v[16:17], v[18:19]
	v_mov_b64_e32 v[18:19], v[20:21]
	v_mov_b64_e32 v[20:21], v[22:23]
	v_mov_b64_e32 v[22:23], v[24:25]
	v_mov_b64_e32 v[24:25], 0
	s_mov_b64 exec, s[36:37]
	v_mov_b32_dpp v28, v12 quad_perm:[1,0,3,2] row_mask:0xf bank_mask:0xf bound_ctrl:1
	v_mov_b32_dpp v29, v13 quad_perm:[1,0,3,2] row_mask:0xf bank_mask:0xf bound_ctrl:1
	v_cmp_gt_u64_e32 vcc, v[28:29], v[12:13]
	s_nop 1
	v_cndmask_b32_e32 v26, v12, v28, vcc
	v_cndmask_b32_e32 v27, v13, v29, vcc
	s_nop 1
	v_mov_b32_dpp v28, v26 quad_perm:[2,3,0,1] row_mask:0xf bank_mask:0xf bound_ctrl:1
	v_mov_b32_dpp v29, v27 quad_perm:[2,3,0,1] row_mask:0xf bank_mask:0xf bound_ctrl:1
	v_cmp_gt_u64_e32 vcc, v[28:29], v[26:27]
	s_nop 1
	v_cndmask_b32_e32 v26, v26, v28, vcc
	v_cndmask_b32_e32 v27, v27, v29, vcc
	s_nop 1
	v_mov_b32_dpp v28, v26 row_half_mirror row_mask:0xf bank_mask:0xf bound_ctrl:1
	v_mov_b32_dpp v29, v27 row_half_mirror row_mask:0xf bank_mask:0xf bound_ctrl:1
	v_cmp_gt_u64_e32 vcc, v[28:29], v[26:27]
	s_nop 1
	v_cndmask_b32_e32 v26, v26, v28, vcc
	v_cndmask_b32_e32 v27, v27, v29, vcc
	v_cndmask_b32_e64 v34, v34, v26, s[2:3]
	v_cndmask_b32_e64 v35, v35, v27, s[2:3]
	v_cmp_eq_u64_e32 vcc, v[12:13], v[26:27]
	s_and_saveexec_b64 s[36:37], vcc
	v_mov_b64_e32 v[12:13], v[14:15]
	v_mov_b64_e32 v[14:15], v[16:17]
	v_mov_b64_e32 v[16:17], v[18:19]
	v_mov_b64_e32 v[18:19], v[20:21]
	v_mov_b64_e32 v[20:21], v[22:23]
	v_mov_b64_e32 v[22:23], v[24:25]
	v_mov_b64_e32 v[24:25], 0
	s_mov_b64 exec, s[36:37]
	v_mov_b32_dpp v28, v12 quad_perm:[1,0,3,2] row_mask:0xf bank_mask:0xf bound_ctrl:1
; #define ARGMAX_STEP(CTRL) { const float ov = dppf<CTRL>(best); const int oc = dppi<CTRL>(bc);                \
;           const bool take = ov > best || (ov == best && oc < bc); best = take ? ov : best; bc = take ? oc : bc; }
; static __device__ __forceinline__ void phase_peer(const Params& p, char* smraw) {
;     ...
;       for (int round = 0; round < 16; ++round) {
;         float best = cand[0]; int bc = ccode[0];
; #pragma unroll
;         for (int m = 1; m < 7; ++m) if (cand[m] > best) { best = cand[m]; bc = ccode[m]; }
;     ...
;         ARGMAX_STEP(0xB1) ARGMAX_STEP(0x4E) ARGMAX_STEP(0x141)
;     ...
; #pragma unroll
;         for (int m = 0; m < 7; ++m) cand[m] = ccode[m] == bc ? -3.0e38f : cand[m];
;         if (round == 0) vmax = best;
;         if ((round & 7) == g) { myv[round >> 3] = best; myc[round >> 3] = bc; }
;       }
	v_mov_b32_dpp v29, v13 quad_perm:[1,0,3,2] row_mask:0xf bank_mask:0xf bound_ctrl:1
	v_cmp_gt_u64_e32 vcc, v[28:29], v[12:13]
	s_nop 1
	v_cndmask_b32_e32 v26, v12, v28, vcc
	v_cndmask_b32_e32 v27, v13, v29, vcc
	s_nop 1
	v_mov_b32_dpp v28, v26 quad_perm:[2,3,0,1] row_mask:0xf bank_mask:0xf bound_ctrl:1
	v_mov_b32_dpp v29, v27 quad_perm:[2,3,0,1] row_mask:0xf bank_mask:0xf bound_ctrl:1
	v_cmp_gt_u64_e32 vcc, v[28:29], v[26:27]
	s_nop 1
	v_cndmask_b32_e32 v26, v26, v28, vcc
	v_cndmask_b32_e32 v27, v27, v29, vcc
	s_nop 1
	v_mov_b32_dpp v28, v26 row_half_mirror row_mask:0xf bank_mask:0xf bound_ctrl:1
	v_mov_b32_dpp v29, v27 row_half_mirror row_mask:0xf bank_mask:0xf bound_ctrl:1
	v_cmp_gt_u64_e32 vcc, v[28:29], v[26:27]
	s_nop 1
	v_cndmask_b32_e32 v26, v26, v28, vcc
	v_cndmask_b32_e32 v27, v27, v29, vcc
	v_cndmask_b32_e64 v34, v34, v26, s[4:5]
	v_cndmask_b32_e64 v35, v35, v27, s[4:5]
	v_cmp_eq_u64_e32 vcc, v[12:13], v[26:27]
	s_and_saveexec_b64 s[36:37], vcc
	v_mov_b64_e32 v[12:13], v[14:15]
	v_mov_b64_e32 v[14:15], v[16:17]
	v_mov_b64_e32 v[16:17], v[18:19]
	v_mov_b64_e32 v[18:19], v[20:21]
	v_mov_b64_e32 v[20:21], v[22:23]
	v_mov_b64_e32 v[22:23], v[24:25]
	v_mov_b64_e32 v[24:25], 0
	s_mov_b64 exec, s[36:37]
	v_mov_b32_dpp v28, v12 quad_perm:[1,0,3,2] row_mask:0xf bank_mask:0xf bound_ctrl:1
	v_mov_b32_dpp v29, v13 quad_perm:[1,0,3,2] row_mask:0xf bank_mask:0xf bound_ctrl:1
	v_cmp_gt_u64_e32 vcc, v[28:29], v[12:13]
	s_nop 1
	v_cndmask_b32_e32 v26, v12, v28, vcc
	v_cndmask_b32_e32 v27, v13, v29, vcc
	s_nop 1
	v_mov_b32_dpp v28, v26 quad_perm:[2,3,0,1] row_mask:0xf bank_mask:0xf bound_ctrl:1
	v_mov_b32_dpp v29, v27 quad_perm:[2,3,0,1] row_mask:0xf bank_mask:0xf bound_ctrl:1
	v_cmp_gt_u64_e32 vcc, v[28:29], v[26:27]
	s_nop 1
	v_cndmask_b32_e32 v26, v26, v28, vcc
	v_cndmask_b32_e32 v27, v27, v29, vcc
	s_nop 1
	v_mov_b32_dpp v28, v26 row_half_mirror row_mask:0xf bank_mask:0xf bound_ctrl:1
	v_mov_b32_dpp v29, v27 row_half_mirror row_mask:0xf bank_mask:0xf bound_ctrl:1
	v_cmp_gt_u64_e32 vcc, v[28:29], v[26:27]
	s_nop 1
	v_cndmask_b32_e32 v26, v26, v28, vcc
	v_cndmask_b32_e32 v27, v27, v29, vcc
	v_cndmask_b32_e64 v34, v34, v26, s[6:7]
	v_cndmask_b32_e64 v35, v35, v27, s[6:7]
	v_cmp_eq_u64_e32 vcc, v[12:13], v[26:27]
	s_and_saveexec_b64 s[36:37], vcc
	v_mov_b64_e32 v[12:13], v[14:15]
	v_mov_b64_e32 v[14:15], v[16:17]
	v_mov_b64_e32 v[16:17], v[18:19]
	v_mov_b64_e32 v[18:19], v[20:21]
	v_mov_b64_e32 v[20:21], v[22:23]
	v_mov_b64_e32 v[22:23], v[24:25]
	v_mov_b64_e32 v[24:25], 0
	s_mov_b64 exec, s[36:37]
	v_mov_b32_dpp v28, v12 quad_perm:[1,0,3,2] row_mask:0xf bank_mask:0xf bound_ctrl:1
	v_mov_b32_dpp v29, v13 quad_perm:[1,0,3,2] row_mask:0xf bank_mask:0xf bound_ctrl:1
	v_cmp_gt_u64_e32 vcc, v[28:29], v[12:13]
	s_nop 1
	v_cndmask_b32_e32 v26, v12, v28, vcc
	v_cndmask_b32_e32 v27, v13, v29, vcc
	s_nop 1
	v_mov_b32_dpp v28, v26 quad_perm:[2,3,0,1] row_mask:0xf bank_mask:0xf bound_ctrl:1
	v_mov_b32_dpp v29, v27 quad_perm:[2,3,0,1] row_mask:0xf bank_mask:0xf bound_ctrl:1
	v_cmp_gt_u64_e32 vcc, v[28:29], v[26:27]
	s_nop 1
	v_cndmask_b32_e32 v26, v26, v28, vcc
	v_cndmask_b32_e32 v27, v27, v29, vcc
	s_nop 1
	v_mov_b32_dpp v28, v26 row_half_mirror row_mask:0xf bank_mask:0xf bound_ctrl:1
	v_mov_b32_dpp v29, v27 row_half_mirror row_mask:0xf bank_mask:0xf bound_ctrl:1
	v_cmp_gt_u64_e32 vcc, v[28:29], v[26:27]
	s_nop 1
	v_cndmask_b32_e32 v26, v26, v28, vcc
	v_cndmask_b32_e32 v27, v27, v29, vcc
	v_cndmask_b32_e64 v34, v34, v26, s[8:9]
	v_cndmask_b32_e64 v35, v35, v27, s[8:9]
	v_cmp_eq_u64_e32 vcc, v[12:13], v[26:27]
	s_and_saveexec_b64 s[36:37], vcc
	v_mov_b64_e32 v[12:13], v[14:15]
	v_mov_b64_e32 v[14:15], v[16:17]
	v_mov_b64_e32 v[16:17], v[18:19]
	v_mov_b64_e32 v[18:19], v[20:21]
	v_mov_b64_e32 v[20:21], v[22:23]
	v_mov_b64_e32 v[22:23], v[24:25]
	v_mov_b64_e32 v[24:25], 0
	s_mov_b64 exec, s[36:37]
	v_mov_b32_dpp v28, v12 quad_perm:[1,0,3,2] row_mask:0xf bank_mask:0xf bound_ctrl:1
	v_mov_b32_dpp v29, v13 quad_perm:[1,0,3,2] row_mask:0xf bank_mask:0xf bound_ctrl:1
	v_cmp_gt_u64_e32 vcc, v[28:29], v[12:13]
	s_nop 1
	v_cndmask_b32_e32 v26, v12, v28, vcc
	v_cndmask_b32_e32 v27, v13, v29, vcc
	s_nop 1
	v_mov_b32_dpp v28, v26 quad_perm:[2,3,0,1] row_mask:0xf bank_mask:0xf bound_ctrl:1
	v_mov_b32_dpp v29, v27 quad_perm:[2,3,0,1] row_mask:0xf bank_mask:0xf bound_ctrl:1
	v_cmp_gt_u64_e32 vcc, v[28:29], v[26:27]
	s_nop 1
	v_cndmask_b32_e32 v26, v26, v28, vcc
	v_cndmask_b32_e32 v27, v27, v29, vcc
	s_nop 1
	v_mov_b32_dpp v28, v26 row_half_mirror row_mask:0xf bank_mask:0xf bound_ctrl:1
	v_mov_b32_dpp v29, v27 row_half_mirror row_mask:0xf bank_mask:0xf bound_ctrl:1
	v_cmp_gt_u64_e32 vcc, v[28:29], v[26:27]
	s_nop 1
	v_cndmask_b32_e32 v26, v26, v28, vcc
	v_cndmask_b32_e32 v27, v27, v29, vcc
	v_cndmask_b32_e64 v34, v34, v26, s[10:11]
	v_cndmask_b32_e64 v35, v35, v27, s[10:11]
	v_cmp_eq_u64_e32 vcc, v[12:13], v[26:27]
	s_and_saveexec_b64 s[36:37], vcc
	v_mov_b64_e32 v[12:13], v[14:15]
	v_mov_b64_e32 v[14:15], v[16:17]
	v_mov_b64_e32 v[16:17], v[18:19]
	v_mov_b64_e32 v[18:19], v[20:21]
	v_mov_b64_e32 v[20:21], v[22:23]
	v_mov_b64_e32 v[22:23], v[24:25]
	v_mov_b64_e32 v[24:25], 0
	s_mov_b64 exec, s[36:37]
	v_mov_b32_dpp v28, v12 quad_perm:[1,0,3,2] row_mask:0xf bank_mask:0xf bound_ctrl:1
	v_mov_b32_dpp v29, v13 quad_perm:[1,0,3,2] row_mask:0xf bank_mask:0xf bound_ctrl:1
	v_cmp_gt_u64_e32 vcc, v[28:29], v[12:13]
	s_nop 1
	v_cndmask_b32_e32 v26, v12, v28, vcc
	v_cndmask_b32_e32 v27, v13, v29, vcc
	s_nop 1
	v_mov_b32_dpp v28, v26 quad_perm:[2,3,0,1] row_mask:0xf bank_mask:0xf bound_ctrl:1
	v_mov_b32_dpp v29, v27 quad_perm:[2,3,0,1] row_mask:0xf bank_mask:0xf bound_ctrl:1
; #define ARGMAX_STEP(CTRL) { const float ov = dppf<CTRL>(best); const int oc = dppi<CTRL>(bc);                \
;           const bool take = ov > best || (ov == best && oc < bc); best = take ? ov : best; bc = take ? oc : bc; }
; static __device__ __forceinline__ void phase_peer(const Params& p, char* smraw) {
;     ...
;       for (int round = 0; round < 16; ++round) {
;         float best = cand[0]; int bc = ccode[0];
; #pragma unroll
;         for (int m = 1; m < 7; ++m) if (cand[m] > best) { best = cand[m]; bc = ccode[m]; }
;     ...
;         ARGMAX_STEP(0xB1) ARGMAX_STEP(0x4E) ARGMAX_STEP(0x141)
;     ...
; #pragma unroll
;         for (int m = 0; m < 7; ++m) cand[m] = ccode[m] == bc ? -3.0e38f : cand[m];
;         if (round == 0) vmax = best;
;         if ((round & 7) == g) { myv[round >> 3] = best; myc[round >> 3] = bc; }
;       }
;       const float e0 = __expf(myv[0] - vmax), e1 = __expf(myv[1] - vmax);
;       float se = e0 + e1;
;       se += dppf<0xB1>(se); se += dppf<0x4E>(se); se += dppf<0x141>(se);
;       const float inv = 1.f / se;
;       const unsigned char* tip = TI + ((size_t)t * 16 + head * 2) * 16;
; #pragma unroll
;       for (int s = 0; s < 2; ++s) {
;         const int i0 = tip[myc[s] >> 4], i1 = tip[16 + (myc[s] & 15)];
;         sIdx[head * 16 + g + 8 * s] = i0 * 128 + i1;
;         sGate[head * 16 + g + 8 * s] = (s ? e1 : e0) * inv;
;       }
	v_cmp_gt_u64_e32 vcc, v[28:29], v[26:27]
	s_nop 1
	v_cndmask_b32_e32 v26, v26, v28, vcc
	v_cndmask_b32_e32 v27, v27, v29, vcc
	s_nop 1
	v_mov_b32_dpp v28, v26 row_half_mirror row_mask:0xf bank_mask:0xf bound_ctrl:1
	v_mov_b32_dpp v29, v27 row_half_mirror row_mask:0xf bank_mask:0xf bound_ctrl:1
	v_cmp_gt_u64_e32 vcc, v[28:29], v[26:27]
	s_nop 1
	v_cndmask_b32_e32 v26, v26, v28, vcc
	v_cndmask_b32_e32 v27, v27, v29, vcc
	v_cndmask_b32_e64 v34, v34, v26, s[12:13]
	v_cndmask_b32_e64 v35, v35, v27, s[12:13]
	v_cmp_eq_u64_e32 vcc, v[12:13], v[26:27]
	s_and_saveexec_b64 s[36:37], vcc
	v_mov_b64_e32 v[12:13], v[14:15]
	v_mov_b64_e32 v[14:15], v[16:17]
	v_mov_b64_e32 v[16:17], v[18:19]
	v_mov_b64_e32 v[18:19], v[20:21]
	v_mov_b64_e32 v[20:21], v[22:23]
	v_mov_b64_e32 v[22:23], v[24:25]
	v_mov_b64_e32 v[24:25], 0
	s_mov_b64 exec, s[36:37]
	v_mov_b32_dpp v28, v12 quad_perm:[1,0,3,2] row_mask:0xf bank_mask:0xf bound_ctrl:1
	v_mov_b32_dpp v29, v13 quad_perm:[1,0,3,2] row_mask:0xf bank_mask:0xf bound_ctrl:1
	v_cmp_gt_u64_e32 vcc, v[28:29], v[12:13]
	s_nop 1
	v_cndmask_b32_e32 v26, v12, v28, vcc
	v_cndmask_b32_e32 v27, v13, v29, vcc
	s_nop 1
	v_mov_b32_dpp v28, v26 quad_perm:[2,3,0,1] row_mask:0xf bank_mask:0xf bound_ctrl:1
	v_mov_b32_dpp v29, v27 quad_perm:[2,3,0,1] row_mask:0xf bank_mask:0xf bound_ctrl:1
	v_cmp_gt_u64_e32 vcc, v[28:29], v[26:27]
	s_nop 1
	v_cndmask_b32_e32 v26, v26, v28, vcc
	v_cndmask_b32_e32 v27, v27, v29, vcc
	s_nop 1
	v_mov_b32_dpp v28, v26 row_half_mirror row_mask:0xf bank_mask:0xf bound_ctrl:1
	v_mov_b32_dpp v29, v27 row_half_mirror row_mask:0xf bank_mask:0xf bound_ctrl:1
	v_cmp_gt_u64_e32 vcc, v[28:29], v[26:27]
	s_nop 1
	v_cndmask_b32_e32 v26, v26, v28, vcc
	v_cndmask_b32_e32 v27, v27, v29, vcc
	v_cndmask_b32_e64 v34, v34, v26, s[14:15]
	v_cndmask_b32_e64 v35, v35, v27, s[14:15]
	v_cmp_eq_u64_e32 vcc, v[12:13], v[26:27]
	s_and_saveexec_b64 s[36:37], vcc
	v_mov_b64_e32 v[12:13], v[14:15]
	v_mov_b64_e32 v[14:15], v[16:17]
	v_mov_b64_e32 v[16:17], v[18:19]
	v_mov_b64_e32 v[18:19], v[20:21]
	v_mov_b64_e32 v[20:21], v[22:23]
	v_mov_b64_e32 v[22:23], v[24:25]
	v_mov_b64_e32 v[24:25], 0
	s_mov_b64 exec, s[36:37]
	v_mov_b32_dpp v28, v12 quad_perm:[1,0,3,2] row_mask:0xf bank_mask:0xf bound_ctrl:1
	v_mov_b32_dpp v29, v13 quad_perm:[1,0,3,2] row_mask:0xf bank_mask:0xf bound_ctrl:1
	v_cmp_gt_u64_e32 vcc, v[28:29], v[12:13]
	s_nop 1
	v_cndmask_b32_e32 v26, v12, v28, vcc
	v_cndmask_b32_e32 v27, v13, v29, vcc
	s_nop 1
	v_mov_b32_dpp v28, v26 quad_perm:[2,3,0,1] row_mask:0xf bank_mask:0xf bound_ctrl:1
	v_mov_b32_dpp v29, v27 quad_perm:[2,3,0,1] row_mask:0xf bank_mask:0xf bound_ctrl:1
	v_cmp_gt_u64_e32 vcc, v[28:29], v[26:27]
	s_nop 1
	v_cndmask_b32_e32 v26, v26, v28, vcc
	v_cndmask_b32_e32 v27, v27, v29, vcc
	s_nop 1
	v_mov_b32_dpp v28, v26 row_half_mirror row_mask:0xf bank_mask:0xf bound_ctrl:1
	v_mov_b32_dpp v29, v27 row_half_mirror row_mask:0xf bank_mask:0xf bound_ctrl:1
	v_cmp_gt_u64_e32 vcc, v[28:29], v[26:27]
	s_nop 1
	v_cndmask_b32_e32 v26, v26, v28, vcc
	v_cndmask_b32_e32 v27, v27, v29, vcc
	v_cndmask_b32_e64 v34, v34, v26, s[16:17]
	v_cndmask_b32_e64 v35, v35, v27, s[16:17]
	v_sub_u32_e32 v6, 0xff, v32
	v_sub_u32_e32 v9, 0xff, v34
	v_ashrrev_i32_e32 v30, 31, v33
	v_not_b32_e32 v30, v30
	v_or_b32_e32 v30, 0x80000000, v30
	v_xor_b32_e32 v3, v33, v30
	v_ashrrev_i32_e32 v30, 31, v35
	v_not_b32_e32 v30, v30
	v_or_b32_e32 v30, 0x80000000, v30
	v_xor_b32_e32 v13, v35, v30
	v_ashrrev_i32_e32 v30, 31, v38
	v_not_b32_e32 v30, v30
	v_or_b32_e32 v30, 0x80000000, v30
	v_xor_b32_e32 v2, v38, v30
	v_lshl_add_u64 v[0:1], s[46:47], 0, v[0:1]
	v_ashrrev_i32_e32 v24, 4, v6
	v_and_b32_e32 v58, 15, v6
	v_ashrrev_i32_e32 v52, 4, v9
	v_ashrrev_i32_e32 v25, 31, v24
	v_lshl_add_u64 v[50:51], v[0:1], 0, v[58:59]
	v_ashrrev_i32_e32 v53, 31, v52
	v_and_b32_e32 v58, 15, v9
	v_lshl_add_u64 v[24:25], v[0:1], 0, v[24:25]
	v_lshl_add_u64 v[52:53], v[0:1], 0, v[52:53]
	v_lshl_add_u64 v[0:1], v[0:1], 0, v[58:59]
	global_load_ubyte v6, v[24:25], off
	global_load_ubyte v9, v[50:51], off offset:16
	global_load_ubyte v12, v[52:53], off
	s_nop 0
	global_load_ubyte v0, v[0:1], off offset:16
	v_mov_b32_e32 v1, v13
	v_sub_f32_e32 v3, v3, v2
	v_sub_f32_e32 v1, v1, v2
	v_mul_f32_e32 v3, 0x3fb8aa3b, v3
	v_mul_f32_e32 v1, 0x3fb8aa3b, v1
	v_exp_f32_e32 v3, v3
	v_exp_f32_e32 v1, v1
	v_lshlrev_b64 v[100:101], 10, v[56:57]
	s_mov_b32 s52, 0
	v_mov_b32_e32 v77, v200
	v_add_f32_e32 v2, v3, v1
	s_waitcnt vmcnt(0)
	v_lshl_add_u32 v0, v12, 7, v0
	v_add_f32_dpp v2, v2, v2 quad_perm:[1,0,3,2] row_mask:0xf bank_mask:0xf bound_ctrl:1
	s_nop 1
	v_add_f32_dpp v2, v2, v2 quad_perm:[2,3,0,1] row_mask:0xf bank_mask:0xf bound_ctrl:1
	s_nop 1
	v_add_f32_dpp v2, v2, v2 row_half_mirror row_mask:0xf bank_mask:0xf bound_ctrl:1
	v_div_scale_f32 v4, s[36:37], v2, v2, 1.0
	v_rcp_f32_e32 v5, v4
	v_div_scale_f32 v7, vcc, 1.0, v2, 1.0
	v_fma_f32 v8, -v4, v5, 1.0
	v_fmac_f32_e32 v5, v8, v5
	v_mul_f32_e32 v8, v7, v5
	v_fma_f32 v10, -v4, v8, v7
	v_fmac_f32_e32 v8, v10, v5
	v_fma_f32 v4, -v4, v8, v7
	v_div_fmas_f32 v4, v4, v5, v8
	v_div_fixup_f32 v2, v4, v2, 1.0
	v_mul_f32_e32 v3, v3, v2
	v_mul_f32_e32 v1, v1, v2
	v_lshl_add_u32 v2, v6, 7, v9
	ds_write2_b32 v187, v2, v0 offset1:8
	ds_write2_b32 v187, v3, v1 offset0:128 offset1:136
	v_lshlrev_b64 v[0:1], 11, v[56:57]
	v_lshl_add_u64 v[102:103], v[62:63], 0, v[0:1]
	s_waitcnt lgkmcnt(0)
; __device__ __forceinline__ float bflo(unsigned u) { return __uint_as_float(u << 16); }
; __device__ __forceinline__ float bfhi(unsigned u) { return __uint_as_float(u & 0xffff0000u); }
; static __device__ __forceinline__ void phase_peer(const Params& p, char* smraw) {
;     ...
;     f2_t z2[32];
;     {
;       const u16* xbh = X1B + (size_t)t * 1024 + sub * 32;
; #pragma unroll
;       for (int j = 0; j < 2; ++j)
; #pragma unroll
;         for (int q4 = 0; q4 < 4; ++q4) {
;           const u32x4 wv = *(const u32x4*)(xbh + j * 512 + q4 * 8);
; #pragma unroll
;           for (int e = 0; e < 4; ++e) z2[j * 16 + 4 * q4 + e] = f2_t{bflo(wv[e]) * rs, bfhi(wv[e]) * rs};
;         }
;     }
;     {
;       u32x4 ua[2], ub[2], uc[2], ud[2]; int ea, eb, ec, ed; float ga_, gb2, gc, gd, sua, sub_, suc, sud, sva, svb, svc, svd;
;     ...
;       GLOADU(ua, sua, sva, ea, ga_, 0); GLOADU(ub, sub_, svb, eb, gb2, 1); GLOADU(uc, suc, svc, ec, gc, 2);
	global_load_dwordx4 v[40:43], v[102:103], off
	global_load_dwordx4 v[32:35], v[102:103], off offset:16
	global_load_dwordx4 v[28:31], v[102:103], off offset:32
	global_load_dwordx4 v[24:27], v[102:103], off offset:48
	ds_read2_b32 v[0:1], v186 offset1:4
	global_load_dwordx4 v[146:149], v[102:103], off offset:1072
	global_load_dwordx4 v[136:139], v[102:103], off offset:1056
	global_load_dwordx4 v[128:131], v[102:103], off offset:1040
	global_load_dwordx4 v[120:123], v[102:103], off offset:1024
	ds_read2_b32 v[38:39], v186 offset0:8 offset1:128
	s_waitcnt lgkmcnt(1)
	v_ashrrev_i32_e32 v3, 31, v0
	v_mov_b32_e32 v2, v0
	v_ashrrev_i32_e32 v5, 31, v1
	v_mov_b32_e32 v4, v1
	s_waitcnt lgkmcnt(0)
	v_ashrrev_i32_e32 v1, 31, v38
	v_mov_b32_e32 v0, v38
	v_lshlrev_b64 v[6:7], 9, v[2:3]
	v_lshlrev_b64 v[2:3], 2, v[2:3]
	v_lshlrev_b64 v[8:9], 9, v[4:5]
	v_lshlrev_b64 v[4:5], 2, v[4:5]
	v_lshlrev_b64 v[10:11], 9, v[0:1]
	v_lshlrev_b64 v[0:1], 2, v[0:1]
	v_lshl_add_u64 v[6:7], v[64:65], 0, v[6:7]
	v_lshl_add_u64 v[12:13], s[38:39], 0, v[2:3]
	v_lshl_add_u64 v[14:15], s[40:41], 0, v[2:3]
	v_lshl_add_u64 v[16:17], v[64:65], 0, v[8:9]
	v_lshl_add_u64 v[18:19], s[38:39], 0, v[4:5]
	v_lshl_add_u64 v[20:21], s[40:41], 0, v[4:5]
	v_lshl_add_u64 v[22:23], v[64:65], 0, v[10:11]
	v_lshl_add_u64 v[44:45], s[38:39], 0, v[0:1]
	v_lshl_add_u64 v[46:47], s[40:41], 0, v[0:1]
	global_load_dwordx4 v[0:3], v[6:7], off
	s_nop 0
	global_load_dwordx4 v[4:7], v[6:7], off offset:256
	s_nop 0
	global_load_dword v38, v[12:13], off
	global_load_dword v57, v[14:15], off
	global_load_dwordx4 v[8:11], v[16:17], off
	s_nop 0
	global_load_dwordx4 v[12:15], v[16:17], off offset:256
	global_load_dword v58, v[18:19], off
	global_load_dword v71, v[20:21], off
	s_nop 0
	global_load_dwordx4 v[16:19], v[22:23], off
	s_nop 0
	global_load_dwordx4 v[20:23], v[22:23], off offset:256
	s_nop 0
	global_load_dword v73, v[44:45], off
	global_load_dword v75, v[46:47], off
	s_waitcnt vmcnt(19)
	v_lshlrev_b32_e32 v44, 16, v40
	v_and_b32_e32 v45, 0xffff0000, v40
	v_lshlrev_b32_e32 v40, 16, v41
	v_and_b32_e32 v41, 0xffff0000, v41
	v_lshlrev_b32_e32 v46, 16, v42
	v_and_b32_e32 v47, 0xffff0000, v42
	s_waitcnt vmcnt(18)
	v_lshlrev_b32_e32 v50, 16, v33
	v_and_b32_e32 v51, 0xffff0000, v33
	v_lshlrev_b32_e32 v54, 16, v35
	v_and_b32_e32 v55, 0xffff0000, v35
	s_waitcnt vmcnt(17)
	v_lshlrev_b32_e32 v104, 16, v28
	v_and_b32_e32 v105, 0xffff0000, v28
	v_lshlrev_b32_e32 v28, 16, v29
	v_and_b32_e32 v29, 0xffff0000, v29
	v_lshlrev_b32_e32 v48, 16, v32
	v_and_b32_e32 v49, 0xffff0000, v32
	v_lshlrev_b32_e32 v52, 16, v34
	v_and_b32_e32 v53, 0xffff0000, v34
	v_lshlrev_b32_e32 v106, 16, v30
	v_and_b32_e32 v107, 0xffff0000, v30
	v_pk_mul_f32 v[34:35], v[36:37], v[40:41] op_sel_hi:[0,1]
	v_pk_mul_f32 v[40:41], v[36:37], v[46:47] op_sel_hi:[0,1]
	v_pk_mul_f32 v[46:47], v[36:37], v[50:51] op_sel_hi:[0,1]
	v_pk_mul_f32 v[50:51], v[36:37], v[54:55] op_sel_hi:[0,1]
	v_pk_mul_f32 v[54:55], v[36:37], v[28:29] op_sel_hi:[0,1]
	v_lshlrev_b32_e32 v28, 16, v31
	v_and_b32_e32 v29, 0xffff0000, v31
	v_pk_mul_f32 v[32:33], v[36:37], v[44:45] op_sel_hi:[0,1]
	v_pk_mul_f32 v[44:45], v[36:37], v[48:49] op_sel_hi:[0,1]
	v_pk_mul_f32 v[48:49], v[36:37], v[52:53] op_sel_hi:[0,1]
	v_pk_mul_f32 v[52:53], v[36:37], v[104:105] op_sel_hi:[0,1]
	v_pk_mul_f32 v[104:105], v[36:37], v[106:107] op_sel_hi:[0,1]
	v_pk_mul_f32 v[106:107], v[36:37], v[28:29] op_sel_hi:[0,1]
	s_waitcnt vmcnt(16)
	v_lshlrev_b32_e32 v28, 16, v24
	v_and_b32_e32 v29, 0xffff0000, v24
	v_lshlrev_b32_e32 v24, 16, v25
	v_and_b32_e32 v25, 0xffff0000, v25
	v_pk_mul_f32 v[110:111], v[36:37], v[24:25] op_sel_hi:[0,1]
	v_lshlrev_b32_e32 v24, 16, v26
	v_and_b32_e32 v25, 0xffff0000, v26
	v_pk_mul_f32 v[112:113], v[36:37], v[24:25] op_sel_hi:[0,1]
	v_lshlrev_b32_e32 v24, 16, v27
	v_and_b32_e32 v25, 0xffff0000, v27
	v_pk_mul_f32 v[114:115], v[36:37], v[24:25] op_sel_hi:[0,1]
	s_waitcnt vmcnt(12)
	v_lshlrev_b32_e32 v24, 16, v120
	v_and_b32_e32 v25, 0xffff0000, v120
	v_pk_mul_f32 v[116:117], v[36:37], v[24:25] op_sel_hi:[0,1]
	v_lshlrev_b32_e32 v24, 16, v121
	v_and_b32_e32 v25, 0xffff0000, v121
	v_pk_mul_f32 v[118:119], v[36:37], v[24:25] op_sel_hi:[0,1]
	v_lshlrev_b32_e32 v24, 16, v122
	v_and_b32_e32 v25, 0xffff0000, v122
	v_pk_mul_f32 v[120:121], v[36:37], v[24:25] op_sel_hi:[0,1]
	v_lshlrev_b32_e32 v24, 16, v123
	v_and_b32_e32 v25, 0xffff0000, v123
	v_pk_mul_f32 v[122:123], v[36:37], v[24:25] op_sel_hi:[0,1]
	v_lshlrev_b32_e32 v24, 16, v128
	v_and_b32_e32 v25, 0xffff0000, v128
	v_pk_mul_f32 v[124:125], v[36:37], v[24:25] op_sel_hi:[0,1]
	v_lshlrev_b32_e32 v24, 16, v129
	v_and_b32_e32 v25, 0xffff0000, v129
	v_pk_mul_f32 v[126:127], v[36:37], v[24:25] op_sel_hi:[0,1]
	v_lshlrev_b32_e32 v24, 16, v130
	v_and_b32_e32 v25, 0xffff0000, v130
	v_pk_mul_f32 v[128:129], v[36:37], v[24:25] op_sel_hi:[0,1]
	v_lshlrev_b32_e32 v24, 16, v131
	v_and_b32_e32 v25, 0xffff0000, v131
	v_pk_mul_f32 v[130:131], v[36:37], v[24:25] op_sel_hi:[0,1]
	v_lshlrev_b32_e32 v24, 16, v136
	v_and_b32_e32 v25, 0xffff0000, v136
	v_pk_mul_f32 v[132:133], v[36:37], v[24:25] op_sel_hi:[0,1]
	v_lshlrev_b32_e32 v24, 16, v137
	v_and_b32_e32 v25, 0xffff0000, v137
	v_pk_mul_f32 v[134:135], v[36:37], v[24:25] op_sel_hi:[0,1]
	v_lshlrev_b32_e32 v24, 16, v138
	v_and_b32_e32 v25, 0xffff0000, v138
	v_pk_mul_f32 v[136:137], v[36:37], v[24:25] op_sel_hi:[0,1]
	v_lshlrev_b32_e32 v24, 16, v139
	v_and_b32_e32 v25, 0xffff0000, v139
	v_pk_mul_f32 v[138:139], v[36:37], v[24:25] op_sel_hi:[0,1]
	v_lshlrev_b32_e32 v24, 16, v146
	v_and_b32_e32 v25, 0xffff0000, v146
	v_pk_mul_f32 v[140:141], v[36:37], v[24:25] op_sel_hi:[0,1]
	v_lshlrev_b32_e32 v24, 16, v147
	v_and_b32_e32 v25, 0xffff0000, v147
	ds_read2_b32 v[146:147], v186 offset0:132 offset1:136
	v_pk_mul_f32 v[142:143], v[36:37], v[24:25] op_sel_hi:[0,1]
	v_lshlrev_b32_e32 v24, 16, v148
	v_and_b32_e32 v25, 0xffff0000, v148
	v_lshlrev_b32_e32 v42, 16, v43
	v_and_b32_e32 v43, 0xffff0000, v43
	v_pk_mul_f32 v[144:145], v[36:37], v[24:25] op_sel_hi:[0,1]
	v_lshlrev_b32_e32 v24, 16, v149
	v_and_b32_e32 v25, 0xffff0000, v149
	v_pk_mul_f32 v[42:43], v[36:37], v[42:43] op_sel_hi:[0,1]
	v_pk_mul_f32 v[108:109], v[36:37], v[28:29] op_sel_hi:[0,1]
	v_pk_mul_f32 v[36:37], v[36:37], v[24:25] op_sel_hi:[0,1]
	s_waitcnt lgkmcnt(0)
	v_mov_b32_e32 v149, v146
	v_mov_b32_e32 v147, 0
	v_mov_b32_e32 v149, 0
	ds_read_b32 v146, v77
	s_waitcnt lgkmcnt(0)
	v_lshlrev_b32_e32 v146, 9, v146
	v_lshl_add_u64 v[150:151], v[146:147], 0, v[64:65]
	global_load_dwordx4 v[24:27], v[150:151], off
	global_load_dwordx4 v[28:31], v[150:151], off offset:256
	ds_read_b32 v148, v77 offset:16
	s_waitcnt vmcnt(13)
	v_cvt_scalef32_pk_f32_fp4 v[156:157], v0, 1.0 op_sel:[0,1,0]
	v_cvt_scalef32_pk_f32_fp4 v[152:153], v0, 1.0
	v_pk_fma_f32 v[152:153], v[32:33], v[152:153], 0 op_sel_hi:[1,1,0]
	v_cvt_scalef32_pk_f32_fp4 v[154:155], v0, 1.0 op_sel:[1,0,0]
	v_pk_fma_f32 v[154:155], v[34:35], v[154:155], 0 op_sel_hi:[1,1,0]
	v_pk_fma_f32 v[152:153], v[40:41], v[156:157], v[152:153]
	v_cvt_scalef32_pk_f32_fp4 v[156:157], v0, 1.0 op_sel:[1,1,0]
	v_pk_fma_f32 v[154:155], v[42:43], v[156:157], v[154:155]
	v_cvt_scalef32_pk_f32_fp4 v[156:157], v1, 1.0
	v_pk_fma_f32 v[152:153], v[44:45], v[156:157], v[152:153]
	v_cvt_scalef32_pk_f32_fp4 v[156:157], v1, 1.0 op_sel:[1,0,0]
	v_pk_fma_f32 v[154:155], v[46:47], v[156:157], v[154:155]
	v_cvt_scalef32_pk_f32_fp4 v[156:157], v1, 1.0 op_sel:[0,1,0]
	v_pk_fma_f32 v[152:153], v[48:49], v[156:157], v[152:153]
	v_cvt_scalef32_pk_f32_fp4 v[156:157], v1, 1.0 op_sel:[1,1,0]
	v_pk_fma_f32 v[154:155], v[50:51], v[156:157], v[154:155]
	v_cvt_scalef32_pk_f32_fp4 v[156:157], v2, 1.0
	v_pk_fma_f32 v[152:153], v[52:53], v[156:157], v[152:153]
	v_cvt_scalef32_pk_f32_fp4 v[156:157], v2, 1.0 op_sel:[1,0,0]
	v_pk_fma_f32 v[154:155], v[54:55], v[156:157], v[154:155]
	v_cvt_scalef32_pk_f32_fp4 v[156:157], v2, 1.0 op_sel:[0,1,0]
	v_pk_fma_f32 v[152:153], v[104:105], v[156:157], v[152:153]
	v_cvt_scalef32_pk_f32_fp4 v[156:157], v2, 1.0 op_sel:[1,1,0]
	v_pk_fma_f32 v[154:155], v[106:107], v[156:157], v[154:155]
	v_cvt_scalef32_pk_f32_fp4 v[156:157], v3, 1.0
	v_pk_fma_f32 v[152:153], v[108:109], v[156:157], v[152:153]
	v_cvt_scalef32_pk_f32_fp4 v[156:157], v3, 1.0 op_sel:[1,0,0]
	v_pk_fma_f32 v[154:155], v[110:111], v[156:157], v[154:155]
	v_cvt_scalef32_pk_f32_fp4 v[156:157], v3, 1.0 op_sel:[0,1,0]
	v_pk_fma_f32 v[152:153], v[112:113], v[156:157], v[152:153]
	v_cvt_scalef32_pk_f32_fp4 v[156:157], v3, 1.0 op_sel:[1,1,0]
	v_pk_fma_f32 v[154:155], v[114:115], v[156:157], v[154:155]
	s_waitcnt vmcnt(12)
	v_cvt_scalef32_pk_f32_fp4 v[156:157], v4, 1.0
	v_pk_fma_f32 v[152:153], v[116:117], v[156:157], v[152:153]
	v_cvt_scalef32_pk_f32_fp4 v[156:157], v4, 1.0 op_sel:[1,0,0]
	v_pk_fma_f32 v[154:155], v[118:119], v[156:157], v[154:155]
	v_cvt_scalef32_pk_f32_fp4 v[156:157], v4, 1.0 op_sel:[0,1,0]
	v_pk_fma_f32 v[152:153], v[120:121], v[156:157], v[152:153]
	v_cvt_scalef32_pk_f32_fp4 v[156:157], v4, 1.0 op_sel:[1,1,0]
	v_pk_fma_f32 v[154:155], v[122:123], v[156:157], v[154:155]
	v_cvt_scalef32_pk_f32_fp4 v[156:157], v5, 1.0
	v_pk_fma_f32 v[152:153], v[124:125], v[156:157], v[152:153]
	v_cvt_scalef32_pk_f32_fp4 v[156:157], v5, 1.0 op_sel:[1,0,0]
	v_pk_fma_f32 v[154:155], v[126:127], v[156:157], v[154:155]
	v_cvt_scalef32_pk_f32_fp4 v[156:157], v5, 1.0 op_sel:[0,1,0]
	v_pk_fma_f32 v[152:153], v[128:129], v[156:157], v[152:153]
	v_cvt_scalef32_pk_f32_fp4 v[156:157], v5, 1.0 op_sel:[1,1,0]
	v_pk_fma_f32 v[154:155], v[130:131], v[156:157], v[154:155]
	v_cvt_scalef32_pk_f32_fp4 v[156:157], v6, 1.0
	v_pk_fma_f32 v[152:153], v[132:133], v[156:157], v[152:153]
	v_cvt_scalef32_pk_f32_fp4 v[156:157], v6, 1.0 op_sel:[1,0,0]
	v_pk_fma_f32 v[154:155], v[134:135], v[156:157], v[154:155]
	v_cvt_scalef32_pk_f32_fp4 v[156:157], v6, 1.0 op_sel:[0,1,0]
	v_pk_fma_f32 v[152:153], v[136:137], v[156:157], v[152:153]
	v_cvt_scalef32_pk_f32_fp4 v[156:157], v6, 1.0 op_sel:[1,1,0]
	v_pk_fma_f32 v[154:155], v[138:139], v[156:157], v[154:155]
	v_cvt_scalef32_pk_f32_fp4 v[156:157], v7, 1.0
	v_pk_fma_f32 v[152:153], v[140:141], v[156:157], v[152:153]
	v_cvt_scalef32_pk_f32_fp4 v[156:157], v7, 1.0 op_sel:[1,0,0]
	v_pk_fma_f32 v[154:155], v[142:143], v[156:157], v[154:155]
	v_cvt_scalef32_pk_f32_fp4 v[156:157], v7, 1.0 op_sel:[0,1,0]
	v_pk_fma_f32 v[152:153], v[144:145], v[156:157], v[152:153]
	v_cvt_scalef32_pk_f32_fp4 v[156:157], v7, 1.0 op_sel:[1,1,0]
	v_pk_fma_f32 v[154:155], v[36:37], v[156:157], v[154:155]
	v_add_f32_e32 v85, v152, v153
	v_add_f32_e32 v87, v154, v155
	v_add_f32_e32 v83, v85, v87
; static __device__ __forceinline__ void phase_peer(const Params& p, char* smraw) {
;     ...
;       GLOADU(ua, sua, sva, ea, ga_, 0); GLOADU(ub, sub_, svb, eb, gb2, 1); GLOADU(uc, suc, svc, ec, gc, 2);
; #pragma unroll 1
;       for (int it = 0; it < 32; it += 4) {
;         GLOADU(ud, sud, svd, ed, gd, it + 3);
;         GCOMPU(ua, sua, sva, ga_, it);
;         if (it + 4 < 32) GLOADU(ua, sua, sva, ea, ga_, it + 4);
;         GCOMPU(ub, sub_, svb, gb2, it + 1);
;         if (it + 5 < 32) GLOADU(ub, sub_, svb, eb, gb2, it + 5);
;         GCOMPU(uc, suc, svc, gc, it + 2);
;         if (it + 6 < 32) GLOADU(uc, suc, svc, ec, gc, it + 6);
;         GCOMPU(ud, sud, svd, gd, it + 3);
.LBB0_864:
	s_waitcnt lgkmcnt(0)
	v_lshlrev_b32_e32 v148, 9, v148
	v_lshl_add_u64 v[150:151], v[148:149], 0, v[64:65]
	global_load_dwordx4 v[0:3], v[150:151], off
	global_load_dwordx4 v[4:7], v[150:151], off offset:256
	ds_read_b32 v146, v77 offset:32
	s_waitcnt vmcnt(7)
	v_cvt_scalef32_pk_f32_fp4 v[156:157], v8, 1.0 op_sel:[0,1,0]
	v_cvt_scalef32_pk_f32_fp4 v[152:153], v8, 1.0
	v_pk_fma_f32 v[152:153], v[32:33], v[152:153], 0 op_sel_hi:[1,1,0]
	v_cvt_scalef32_pk_f32_fp4 v[154:155], v8, 1.0 op_sel:[1,0,0]
	v_add_f32_dpp v83, v83, v83 quad_perm:[1,0,3,2] row_mask:0xf bank_mask:0xf bound_ctrl:1
	v_pk_fma_f32 v[154:155], v[34:35], v[154:155], 0 op_sel_hi:[1,1,0]
	v_pk_fma_f32 v[152:153], v[40:41], v[156:157], v[152:153]
	v_cvt_scalef32_pk_f32_fp4 v[156:157], v8, 1.0 op_sel:[1,1,0]
	v_pk_fma_f32 v[154:155], v[42:43], v[156:157], v[154:155]
	v_add_f32_dpp v83, v83, v83 quad_perm:[2,3,0,1] row_mask:0xf bank_mask:0xf bound_ctrl:1
	v_cvt_scalef32_pk_f32_fp4 v[156:157], v9, 1.0
	v_pk_fma_f32 v[152:153], v[44:45], v[156:157], v[152:153]
	v_cvt_scalef32_pk_f32_fp4 v[156:157], v9, 1.0 op_sel:[1,0,0]
	v_pk_fma_f32 v[154:155], v[46:47], v[156:157], v[154:155]
	v_add_f32_dpp v83, v83, v83 row_half_mirror row_mask:0xf bank_mask:0xf bound_ctrl:1
	v_cvt_scalef32_pk_f32_fp4 v[156:157], v9, 1.0 op_sel:[0,1,0]
	v_pk_fma_f32 v[152:153], v[48:49], v[156:157], v[152:153]
	v_cvt_scalef32_pk_f32_fp4 v[156:157], v9, 1.0 op_sel:[1,1,0]
	v_pk_fma_f32 v[154:155], v[50:51], v[156:157], v[154:155]
	v_add_f32_dpp v83, v83, v83 row_mirror row_mask:0xf bank_mask:0xf bound_ctrl:1
	v_cvt_scalef32_pk_f32_fp4 v[156:157], v10, 1.0
	v_pk_fma_f32 v[152:153], v[52:53], v[156:157], v[152:153]
	v_cvt_scalef32_pk_f32_fp4 v[156:157], v10, 1.0 op_sel:[1,0,0]
	v_pk_fma_f32 v[154:155], v[54:55], v[156:157], v[154:155]
	s_mov_b64 exec, s[0:1]
	ds_write_b32 v77, v83 offset:976
	s_mov_b64 exec, -1
	v_cvt_scalef32_pk_f32_fp4 v[156:157], v10, 1.0 op_sel:[0,1,0]
	v_pk_fma_f32 v[152:153], v[104:105], v[156:157], v[152:153]
	v_cvt_scalef32_pk_f32_fp4 v[156:157], v10, 1.0 op_sel:[1,1,0]
	v_pk_fma_f32 v[154:155], v[106:107], v[156:157], v[154:155]
	v_cvt_scalef32_pk_f32_fp4 v[156:157], v11, 1.0
	v_pk_fma_f32 v[152:153], v[108:109], v[156:157], v[152:153]
	v_cvt_scalef32_pk_f32_fp4 v[156:157], v11, 1.0 op_sel:[1,0,0]
	v_pk_fma_f32 v[154:155], v[110:111], v[156:157], v[154:155]
	v_cvt_scalef32_pk_f32_fp4 v[156:157], v11, 1.0 op_sel:[0,1,0]
	v_pk_fma_f32 v[152:153], v[112:113], v[156:157], v[152:153]
	v_cvt_scalef32_pk_f32_fp4 v[156:157], v11, 1.0 op_sel:[1,1,0]
	v_pk_fma_f32 v[154:155], v[114:115], v[156:157], v[154:155]
	s_waitcnt vmcnt(6)
	v_cvt_scalef32_pk_f32_fp4 v[156:157], v12, 1.0
	v_pk_fma_f32 v[152:153], v[116:117], v[156:157], v[152:153]
	v_cvt_scalef32_pk_f32_fp4 v[156:157], v12, 1.0 op_sel:[1,0,0]
	v_pk_fma_f32 v[154:155], v[118:119], v[156:157], v[154:155]
	v_cvt_scalef32_pk_f32_fp4 v[156:157], v12, 1.0 op_sel:[0,1,0]
	v_pk_fma_f32 v[152:153], v[120:121], v[156:157], v[152:153]
	v_cvt_scalef32_pk_f32_fp4 v[156:157], v12, 1.0 op_sel:[1,1,0]
	v_pk_fma_f32 v[154:155], v[122:123], v[156:157], v[154:155]
	v_cvt_scalef32_pk_f32_fp4 v[156:157], v13, 1.0
	v_pk_fma_f32 v[152:153], v[124:125], v[156:157], v[152:153]
	v_cvt_scalef32_pk_f32_fp4 v[156:157], v13, 1.0 op_sel:[1,0,0]
	v_pk_fma_f32 v[154:155], v[126:127], v[156:157], v[154:155]
	v_cvt_scalef32_pk_f32_fp4 v[156:157], v13, 1.0 op_sel:[0,1,0]
	v_pk_fma_f32 v[152:153], v[128:129], v[156:157], v[152:153]
	v_cvt_scalef32_pk_f32_fp4 v[156:157], v13, 1.0 op_sel:[1,1,0]
	v_pk_fma_f32 v[154:155], v[130:131], v[156:157], v[154:155]
	v_cvt_scalef32_pk_f32_fp4 v[156:157], v14, 1.0
	v_pk_fma_f32 v[152:153], v[132:133], v[156:157], v[152:153]
	v_cvt_scalef32_pk_f32_fp4 v[156:157], v14, 1.0 op_sel:[1,0,0]
	v_pk_fma_f32 v[154:155], v[134:135], v[156:157], v[154:155]
	v_cvt_scalef32_pk_f32_fp4 v[156:157], v14, 1.0 op_sel:[0,1,0]
	v_pk_fma_f32 v[152:153], v[136:137], v[156:157], v[152:153]
	v_cvt_scalef32_pk_f32_fp4 v[156:157], v14, 1.0 op_sel:[1,1,0]
	v_pk_fma_f32 v[154:155], v[138:139], v[156:157], v[154:155]
	v_cvt_scalef32_pk_f32_fp4 v[156:157], v15, 1.0
	v_pk_fma_f32 v[152:153], v[140:141], v[156:157], v[152:153]
	v_cvt_scalef32_pk_f32_fp4 v[156:157], v15, 1.0 op_sel:[1,0,0]
	v_pk_fma_f32 v[154:155], v[142:143], v[156:157], v[154:155]
	v_cvt_scalef32_pk_f32_fp4 v[156:157], v15, 1.0 op_sel:[0,1,0]
	v_pk_fma_f32 v[152:153], v[144:145], v[156:157], v[152:153]
	v_cvt_scalef32_pk_f32_fp4 v[156:157], v15, 1.0 op_sel:[1,1,0]
	v_pk_fma_f32 v[154:155], v[36:37], v[156:157], v[154:155]
	v_add_f32_e32 v85, v152, v153
	v_add_f32_e32 v87, v154, v155
	v_add_f32_e32 v83, v85, v87
	s_waitcnt lgkmcnt(0)
	v_lshlrev_b32_e32 v146, 9, v146
	v_lshl_add_u64 v[150:151], v[146:147], 0, v[64:65]
	global_load_dwordx4 v[8:11], v[150:151], off
	global_load_dwordx4 v[12:15], v[150:151], off offset:256
	ds_read_b32 v148, v77 offset:48
	s_waitcnt vmcnt(7)
; static __device__ __forceinline__ void phase_peer(const Params& p, char* smraw) {
;     ...
;       GLOADU(ua, sua, sva, ea, ga_, 0); GLOADU(ub, sub_, svb, eb, gb2, 1); GLOADU(uc, suc, svc, ec, gc, 2);
; #pragma unroll 1
;       for (int it = 0; it < 32; it += 4) {
;         GLOADU(ud, sud, svd, ed, gd, it + 3);
;         GCOMPU(ua, sua, sva, ga_, it);
;         if (it + 4 < 32) GLOADU(ua, sua, sva, ea, ga_, it + 4);
;         GCOMPU(ub, sub_, svb, gb2, it + 1);
;         if (it + 5 < 32) GLOADU(ub, sub_, svb, eb, gb2, it + 5);
;         GCOMPU(uc, suc, svc, gc, it + 2);
;         if (it + 6 < 32) GLOADU(uc, suc, svc, ec, gc, it + 6);
;         GCOMPU(ud, sud, svd, gd, it + 3);
	v_cvt_scalef32_pk_f32_fp4 v[156:157], v16, 1.0 op_sel:[0,1,0]
	v_cvt_scalef32_pk_f32_fp4 v[152:153], v16, 1.0
	v_pk_fma_f32 v[152:153], v[32:33], v[152:153], 0 op_sel_hi:[1,1,0]
	v_cvt_scalef32_pk_f32_fp4 v[154:155], v16, 1.0 op_sel:[1,0,0]
	v_add_f32_dpp v83, v83, v83 quad_perm:[1,0,3,2] row_mask:0xf bank_mask:0xf bound_ctrl:1
	v_pk_fma_f32 v[154:155], v[34:35], v[154:155], 0 op_sel_hi:[1,1,0]
	v_pk_fma_f32 v[152:153], v[40:41], v[156:157], v[152:153]
	v_cvt_scalef32_pk_f32_fp4 v[156:157], v16, 1.0 op_sel:[1,1,0]
	v_pk_fma_f32 v[154:155], v[42:43], v[156:157], v[154:155]
	v_add_f32_dpp v83, v83, v83 quad_perm:[2,3,0,1] row_mask:0xf bank_mask:0xf bound_ctrl:1
	v_cvt_scalef32_pk_f32_fp4 v[156:157], v17, 1.0
	v_pk_fma_f32 v[152:153], v[44:45], v[156:157], v[152:153]
	v_cvt_scalef32_pk_f32_fp4 v[156:157], v17, 1.0 op_sel:[1,0,0]
	v_pk_fma_f32 v[154:155], v[46:47], v[156:157], v[154:155]
	v_add_f32_dpp v83, v83, v83 row_half_mirror row_mask:0xf bank_mask:0xf bound_ctrl:1
	v_cvt_scalef32_pk_f32_fp4 v[156:157], v17, 1.0 op_sel:[0,1,0]
	v_pk_fma_f32 v[152:153], v[48:49], v[156:157], v[152:153]
	v_cvt_scalef32_pk_f32_fp4 v[156:157], v17, 1.0 op_sel:[1,1,0]
	v_pk_fma_f32 v[154:155], v[50:51], v[156:157], v[154:155]
	v_add_f32_dpp v83, v83, v83 row_mirror row_mask:0xf bank_mask:0xf bound_ctrl:1
	v_cvt_scalef32_pk_f32_fp4 v[156:157], v18, 1.0
	v_pk_fma_f32 v[152:153], v[52:53], v[156:157], v[152:153]
	v_cvt_scalef32_pk_f32_fp4 v[156:157], v18, 1.0 op_sel:[1,0,0]
	v_pk_fma_f32 v[154:155], v[54:55], v[156:157], v[154:155]
	s_mov_b64 exec, s[0:1]
	ds_write_b32 v77, v83 offset:992
	s_mov_b64 exec, -1
	v_cvt_scalef32_pk_f32_fp4 v[156:157], v18, 1.0 op_sel:[0,1,0]
	v_pk_fma_f32 v[152:153], v[104:105], v[156:157], v[152:153]
	v_cvt_scalef32_pk_f32_fp4 v[156:157], v18, 1.0 op_sel:[1,1,0]
	v_pk_fma_f32 v[154:155], v[106:107], v[156:157], v[154:155]
	v_cvt_scalef32_pk_f32_fp4 v[156:157], v19, 1.0
	v_pk_fma_f32 v[152:153], v[108:109], v[156:157], v[152:153]
	v_cvt_scalef32_pk_f32_fp4 v[156:157], v19, 1.0 op_sel:[1,0,0]
	v_pk_fma_f32 v[154:155], v[110:111], v[156:157], v[154:155]
	v_cvt_scalef32_pk_f32_fp4 v[156:157], v19, 1.0 op_sel:[0,1,0]
	v_pk_fma_f32 v[152:153], v[112:113], v[156:157], v[152:153]
	v_cvt_scalef32_pk_f32_fp4 v[156:157], v19, 1.0 op_sel:[1,1,0]
	v_pk_fma_f32 v[154:155], v[114:115], v[156:157], v[154:155]
	s_waitcnt vmcnt(6)
	v_cvt_scalef32_pk_f32_fp4 v[156:157], v20, 1.0
	v_pk_fma_f32 v[152:153], v[116:117], v[156:157], v[152:153]
	v_cvt_scalef32_pk_f32_fp4 v[156:157], v20, 1.0 op_sel:[1,0,0]
	v_pk_fma_f32 v[154:155], v[118:119], v[156:157], v[154:155]
	v_cvt_scalef32_pk_f32_fp4 v[156:157], v20, 1.0 op_sel:[0,1,0]
	v_pk_fma_f32 v[152:153], v[120:121], v[156:157], v[152:153]
	v_cvt_scalef32_pk_f32_fp4 v[156:157], v20, 1.0 op_sel:[1,1,0]
	v_pk_fma_f32 v[154:155], v[122:123], v[156:157], v[154:155]
	v_cvt_scalef32_pk_f32_fp4 v[156:157], v21, 1.0
	v_pk_fma_f32 v[152:153], v[124:125], v[156:157], v[152:153]
	v_cvt_scalef32_pk_f32_fp4 v[156:157], v21, 1.0 op_sel:[1,0,0]
	v_pk_fma_f32 v[154:155], v[126:127], v[156:157], v[154:155]
	v_cvt_scalef32_pk_f32_fp4 v[156:157], v21, 1.0 op_sel:[0,1,0]
	v_pk_fma_f32 v[152:153], v[128:129], v[156:157], v[152:153]
	v_cvt_scalef32_pk_f32_fp4 v[156:157], v21, 1.0 op_sel:[1,1,0]
	v_pk_fma_f32 v[154:155], v[130:131], v[156:157], v[154:155]
	v_cvt_scalef32_pk_f32_fp4 v[156:157], v22, 1.0
	v_pk_fma_f32 v[152:153], v[132:133], v[156:157], v[152:153]
	v_cvt_scalef32_pk_f32_fp4 v[156:157], v22, 1.0 op_sel:[1,0,0]
	v_pk_fma_f32 v[154:155], v[134:135], v[156:157], v[154:155]
	v_cvt_scalef32_pk_f32_fp4 v[156:157], v22, 1.0 op_sel:[0,1,0]
	v_pk_fma_f32 v[152:153], v[136:137], v[156:157], v[152:153]
	v_cvt_scalef32_pk_f32_fp4 v[156:157], v22, 1.0 op_sel:[1,1,0]
	v_pk_fma_f32 v[154:155], v[138:139], v[156:157], v[154:155]
	v_cvt_scalef32_pk_f32_fp4 v[156:157], v23, 1.0
	v_pk_fma_f32 v[152:153], v[140:141], v[156:157], v[152:153]
	v_cvt_scalef32_pk_f32_fp4 v[156:157], v23, 1.0 op_sel:[1,0,0]
	v_pk_fma_f32 v[154:155], v[142:143], v[156:157], v[154:155]
	v_cvt_scalef32_pk_f32_fp4 v[156:157], v23, 1.0 op_sel:[0,1,0]
	v_pk_fma_f32 v[152:153], v[144:145], v[156:157], v[152:153]
	v_cvt_scalef32_pk_f32_fp4 v[156:157], v23, 1.0 op_sel:[1,1,0]
	v_pk_fma_f32 v[154:155], v[36:37], v[156:157], v[154:155]
	v_add_f32_e32 v85, v152, v153
	v_add_f32_e32 v87, v154, v155
	v_add_f32_e32 v83, v85, v87
	s_waitcnt lgkmcnt(0)
	v_lshlrev_b32_e32 v148, 9, v148
	v_lshl_add_u64 v[150:151], v[148:149], 0, v[64:65]
	global_load_dwordx4 v[16:19], v[150:151], off
	global_load_dwordx4 v[20:23], v[150:151], off offset:256
	ds_read_b32 v146, v77 offset:64
	s_waitcnt vmcnt(7)
; static __device__ __forceinline__ void phase_peer(const Params& p, char* smraw) {
;     ...
;       GLOADU(ua, sua, sva, ea, ga_, 0); GLOADU(ub, sub_, svb, eb, gb2, 1); GLOADU(uc, suc, svc, ec, gc, 2);
; #pragma unroll 1
;       for (int it = 0; it < 32; it += 4) {
;         GLOADU(ud, sud, svd, ed, gd, it + 3);
;         GCOMPU(ua, sua, sva, ga_, it);
;         if (it + 4 < 32) GLOADU(ua, sua, sva, ea, ga_, it + 4);
;         GCOMPU(ub, sub_, svb, gb2, it + 1);
;         if (it + 5 < 32) GLOADU(ub, sub_, svb, eb, gb2, it + 5);
;         GCOMPU(uc, suc, svc, gc, it + 2);
;         if (it + 6 < 32) GLOADU(uc, suc, svc, ec, gc, it + 6);
;         GCOMPU(ud, sud, svd, gd, it + 3);
	v_cvt_scalef32_pk_f32_fp4 v[156:157], v24, 1.0 op_sel:[0,1,0]
	v_cvt_scalef32_pk_f32_fp4 v[152:153], v24, 1.0
	v_pk_fma_f32 v[152:153], v[32:33], v[152:153], 0 op_sel_hi:[1,1,0]
	v_cvt_scalef32_pk_f32_fp4 v[154:155], v24, 1.0 op_sel:[1,0,0]
	v_add_f32_dpp v83, v83, v83 quad_perm:[1,0,3,2] row_mask:0xf bank_mask:0xf bound_ctrl:1
	v_pk_fma_f32 v[154:155], v[34:35], v[154:155], 0 op_sel_hi:[1,1,0]
	v_pk_fma_f32 v[152:153], v[40:41], v[156:157], v[152:153]
	v_cvt_scalef32_pk_f32_fp4 v[156:157], v24, 1.0 op_sel:[1,1,0]
	v_pk_fma_f32 v[154:155], v[42:43], v[156:157], v[154:155]
	v_add_f32_dpp v83, v83, v83 quad_perm:[2,3,0,1] row_mask:0xf bank_mask:0xf bound_ctrl:1
	v_cvt_scalef32_pk_f32_fp4 v[156:157], v25, 1.0
	v_pk_fma_f32 v[152:153], v[44:45], v[156:157], v[152:153]
	v_cvt_scalef32_pk_f32_fp4 v[156:157], v25, 1.0 op_sel:[1,0,0]
	v_pk_fma_f32 v[154:155], v[46:47], v[156:157], v[154:155]
	v_add_f32_dpp v83, v83, v83 row_half_mirror row_mask:0xf bank_mask:0xf bound_ctrl:1
	v_cvt_scalef32_pk_f32_fp4 v[156:157], v25, 1.0 op_sel:[0,1,0]
	v_pk_fma_f32 v[152:153], v[48:49], v[156:157], v[152:153]
	v_cvt_scalef32_pk_f32_fp4 v[156:157], v25, 1.0 op_sel:[1,1,0]
	v_pk_fma_f32 v[154:155], v[50:51], v[156:157], v[154:155]
	v_add_f32_dpp v83, v83, v83 row_mirror row_mask:0xf bank_mask:0xf bound_ctrl:1
	v_cvt_scalef32_pk_f32_fp4 v[156:157], v26, 1.0
	v_pk_fma_f32 v[152:153], v[52:53], v[156:157], v[152:153]
	v_cvt_scalef32_pk_f32_fp4 v[156:157], v26, 1.0 op_sel:[1,0,0]
	v_pk_fma_f32 v[154:155], v[54:55], v[156:157], v[154:155]
	s_mov_b64 exec, s[0:1]
	ds_write_b32 v77, v83 offset:1008
	s_mov_b64 exec, -1
	v_cvt_scalef32_pk_f32_fp4 v[156:157], v26, 1.0 op_sel:[0,1,0]
	v_pk_fma_f32 v[152:153], v[104:105], v[156:157], v[152:153]
	v_cvt_scalef32_pk_f32_fp4 v[156:157], v26, 1.0 op_sel:[1,1,0]
	v_pk_fma_f32 v[154:155], v[106:107], v[156:157], v[154:155]
	v_cvt_scalef32_pk_f32_fp4 v[156:157], v27, 1.0
	v_pk_fma_f32 v[152:153], v[108:109], v[156:157], v[152:153]
	v_cvt_scalef32_pk_f32_fp4 v[156:157], v27, 1.0 op_sel:[1,0,0]
	v_pk_fma_f32 v[154:155], v[110:111], v[156:157], v[154:155]
	v_cvt_scalef32_pk_f32_fp4 v[156:157], v27, 1.0 op_sel:[0,1,0]
	v_pk_fma_f32 v[152:153], v[112:113], v[156:157], v[152:153]
	v_cvt_scalef32_pk_f32_fp4 v[156:157], v27, 1.0 op_sel:[1,1,0]
	v_pk_fma_f32 v[154:155], v[114:115], v[156:157], v[154:155]
	s_waitcnt vmcnt(6)
	v_cvt_scalef32_pk_f32_fp4 v[156:157], v28, 1.0
	v_pk_fma_f32 v[152:153], v[116:117], v[156:157], v[152:153]
	v_cvt_scalef32_pk_f32_fp4 v[156:157], v28, 1.0 op_sel:[1,0,0]
	v_pk_fma_f32 v[154:155], v[118:119], v[156:157], v[154:155]
	v_cvt_scalef32_pk_f32_fp4 v[156:157], v28, 1.0 op_sel:[0,1,0]
	v_pk_fma_f32 v[152:153], v[120:121], v[156:157], v[152:153]
	v_cvt_scalef32_pk_f32_fp4 v[156:157], v28, 1.0 op_sel:[1,1,0]
	v_pk_fma_f32 v[154:155], v[122:123], v[156:157], v[154:155]
	v_cvt_scalef32_pk_f32_fp4 v[156:157], v29, 1.0
	v_pk_fma_f32 v[152:153], v[124:125], v[156:157], v[152:153]
	v_cvt_scalef32_pk_f32_fp4 v[156:157], v29, 1.0 op_sel:[1,0,0]
	v_pk_fma_f32 v[154:155], v[126:127], v[156:157], v[154:155]
	v_cvt_scalef32_pk_f32_fp4 v[156:157], v29, 1.0 op_sel:[0,1,0]
	v_pk_fma_f32 v[152:153], v[128:129], v[156:157], v[152:153]
	v_cvt_scalef32_pk_f32_fp4 v[156:157], v29, 1.0 op_sel:[1,1,0]
	v_pk_fma_f32 v[154:155], v[130:131], v[156:157], v[154:155]
	v_cvt_scalef32_pk_f32_fp4 v[156:157], v30, 1.0
	v_pk_fma_f32 v[152:153], v[132:133], v[156:157], v[152:153]
	v_cvt_scalef32_pk_f32_fp4 v[156:157], v30, 1.0 op_sel:[1,0,0]
	v_pk_fma_f32 v[154:155], v[134:135], v[156:157], v[154:155]
	v_cvt_scalef32_pk_f32_fp4 v[156:157], v30, 1.0 op_sel:[0,1,0]
	v_pk_fma_f32 v[152:153], v[136:137], v[156:157], v[152:153]
	v_cvt_scalef32_pk_f32_fp4 v[156:157], v30, 1.0 op_sel:[1,1,0]
	v_pk_fma_f32 v[154:155], v[138:139], v[156:157], v[154:155]
	v_cvt_scalef32_pk_f32_fp4 v[156:157], v31, 1.0
	v_pk_fma_f32 v[152:153], v[140:141], v[156:157], v[152:153]
	v_cvt_scalef32_pk_f32_fp4 v[156:157], v31, 1.0 op_sel:[1,0,0]
	v_pk_fma_f32 v[154:155], v[142:143], v[156:157], v[154:155]
	v_cvt_scalef32_pk_f32_fp4 v[156:157], v31, 1.0 op_sel:[0,1,0]
	v_pk_fma_f32 v[152:153], v[144:145], v[156:157], v[152:153]
	v_cvt_scalef32_pk_f32_fp4 v[156:157], v31, 1.0 op_sel:[1,1,0]
	v_pk_fma_f32 v[154:155], v[36:37], v[156:157], v[154:155]
	v_add_f32_e32 v85, v152, v153
	v_add_f32_e32 v87, v154, v155
	v_add_f32_e32 v83, v85, v87
	s_add_i32 s52, s52, 4
	v_add_u32_e32 v77, 64, v77
	s_waitcnt lgkmcnt(0)
	v_lshlrev_b32_e32 v146, 9, v146
	v_lshl_add_u64 v[150:151], v[146:147], 0, v[64:65]
	global_load_dwordx4 v[24:27], v[150:151], off
	global_load_dwordx4 v[28:31], v[150:151], off offset:256
	ds_read_b32 v148, v77 offset:16
	s_waitcnt vmcnt(7)
; static __device__ __forceinline__ void phase_peer(const Params& p, char* smraw) {
;     ...
;       GLOADU(ua, sua, sva, ea, ga_, 0); GLOADU(ub, sub_, svb, eb, gb2, 1); GLOADU(uc, suc, svc, ec, gc, 2);
; #pragma unroll 1
;       for (int it = 0; it < 32; it += 4) {
;         GLOADU(ud, sud, svd, ed, gd, it + 3);
;         GCOMPU(ua, sua, sva, ga_, it);
;         if (it + 4 < 32) GLOADU(ua, sua, sva, ea, ga_, it + 4);
;         GCOMPU(ub, sub_, svb, gb2, it + 1);
;         if (it + 5 < 32) GLOADU(ub, sub_, svb, eb, gb2, it + 5);
;         GCOMPU(uc, suc, svc, gc, it + 2);
;         if (it + 6 < 32) GLOADU(uc, suc, svc, ec, gc, it + 6);
;         GCOMPU(ud, sud, svd, gd, it + 3);
	v_cvt_scalef32_pk_f32_fp4 v[156:157], v0, 1.0 op_sel:[0,1,0]
	v_cvt_scalef32_pk_f32_fp4 v[152:153], v0, 1.0
	v_pk_fma_f32 v[152:153], v[32:33], v[152:153], 0 op_sel_hi:[1,1,0]
	v_cvt_scalef32_pk_f32_fp4 v[154:155], v0, 1.0 op_sel:[1,0,0]
	v_add_f32_dpp v83, v83, v83 quad_perm:[1,0,3,2] row_mask:0xf bank_mask:0xf bound_ctrl:1
	v_pk_fma_f32 v[154:155], v[34:35], v[154:155], 0 op_sel_hi:[1,1,0]
	v_pk_fma_f32 v[152:153], v[40:41], v[156:157], v[152:153]
	v_cvt_scalef32_pk_f32_fp4 v[156:157], v0, 1.0 op_sel:[1,1,0]
	v_pk_fma_f32 v[154:155], v[42:43], v[156:157], v[154:155]
	v_add_f32_dpp v83, v83, v83 quad_perm:[2,3,0,1] row_mask:0xf bank_mask:0xf bound_ctrl:1
	v_cvt_scalef32_pk_f32_fp4 v[156:157], v1, 1.0
	v_pk_fma_f32 v[152:153], v[44:45], v[156:157], v[152:153]
	v_cvt_scalef32_pk_f32_fp4 v[156:157], v1, 1.0 op_sel:[1,0,0]
	v_pk_fma_f32 v[154:155], v[46:47], v[156:157], v[154:155]
	v_add_f32_dpp v83, v83, v83 row_half_mirror row_mask:0xf bank_mask:0xf bound_ctrl:1
	v_cvt_scalef32_pk_f32_fp4 v[156:157], v1, 1.0 op_sel:[0,1,0]
	v_pk_fma_f32 v[152:153], v[48:49], v[156:157], v[152:153]
	v_cvt_scalef32_pk_f32_fp4 v[156:157], v1, 1.0 op_sel:[1,1,0]
	v_pk_fma_f32 v[154:155], v[50:51], v[156:157], v[154:155]
	v_add_f32_dpp v83, v83, v83 row_mirror row_mask:0xf bank_mask:0xf bound_ctrl:1
	v_cvt_scalef32_pk_f32_fp4 v[156:157], v2, 1.0
	v_pk_fma_f32 v[152:153], v[52:53], v[156:157], v[152:153]
	v_cvt_scalef32_pk_f32_fp4 v[156:157], v2, 1.0 op_sel:[1,0,0]
	v_pk_fma_f32 v[154:155], v[54:55], v[156:157], v[154:155]
	s_mov_b64 exec, s[0:1]
	ds_write_b32 v77, v83 offset:960
	s_mov_b64 exec, -1
	v_cvt_scalef32_pk_f32_fp4 v[156:157], v2, 1.0 op_sel:[0,1,0]
	v_pk_fma_f32 v[152:153], v[104:105], v[156:157], v[152:153]
	v_cvt_scalef32_pk_f32_fp4 v[156:157], v2, 1.0 op_sel:[1,1,0]
	v_pk_fma_f32 v[154:155], v[106:107], v[156:157], v[154:155]
	v_cvt_scalef32_pk_f32_fp4 v[156:157], v3, 1.0
	v_pk_fma_f32 v[152:153], v[108:109], v[156:157], v[152:153]
	v_cvt_scalef32_pk_f32_fp4 v[156:157], v3, 1.0 op_sel:[1,0,0]
	v_pk_fma_f32 v[154:155], v[110:111], v[156:157], v[154:155]
	v_cvt_scalef32_pk_f32_fp4 v[156:157], v3, 1.0 op_sel:[0,1,0]
	v_pk_fma_f32 v[152:153], v[112:113], v[156:157], v[152:153]
	v_cvt_scalef32_pk_f32_fp4 v[156:157], v3, 1.0 op_sel:[1,1,0]
	v_pk_fma_f32 v[154:155], v[114:115], v[156:157], v[154:155]
	s_waitcnt vmcnt(6)
	v_cvt_scalef32_pk_f32_fp4 v[156:157], v4, 1.0
	v_pk_fma_f32 v[152:153], v[116:117], v[156:157], v[152:153]
	v_cvt_scalef32_pk_f32_fp4 v[156:157], v4, 1.0 op_sel:[1,0,0]
	v_pk_fma_f32 v[154:155], v[118:119], v[156:157], v[154:155]
	v_cvt_scalef32_pk_f32_fp4 v[156:157], v4, 1.0 op_sel:[0,1,0]
	v_pk_fma_f32 v[152:153], v[120:121], v[156:157], v[152:153]
	v_cvt_scalef32_pk_f32_fp4 v[156:157], v4, 1.0 op_sel:[1,1,0]
	v_pk_fma_f32 v[154:155], v[122:123], v[156:157], v[154:155]
	v_cvt_scalef32_pk_f32_fp4 v[156:157], v5, 1.0
	v_pk_fma_f32 v[152:153], v[124:125], v[156:157], v[152:153]
	v_cvt_scalef32_pk_f32_fp4 v[156:157], v5, 1.0 op_sel:[1,0,0]
	v_pk_fma_f32 v[154:155], v[126:127], v[156:157], v[154:155]
	v_cvt_scalef32_pk_f32_fp4 v[156:157], v5, 1.0 op_sel:[0,1,0]
	v_pk_fma_f32 v[152:153], v[128:129], v[156:157], v[152:153]
	v_cvt_scalef32_pk_f32_fp4 v[156:157], v5, 1.0 op_sel:[1,1,0]
	v_pk_fma_f32 v[154:155], v[130:131], v[156:157], v[154:155]
	v_cvt_scalef32_pk_f32_fp4 v[156:157], v6, 1.0
	v_pk_fma_f32 v[152:153], v[132:133], v[156:157], v[152:153]
	v_cvt_scalef32_pk_f32_fp4 v[156:157], v6, 1.0 op_sel:[1,0,0]
	v_pk_fma_f32 v[154:155], v[134:135], v[156:157], v[154:155]
	v_cvt_scalef32_pk_f32_fp4 v[156:157], v6, 1.0 op_sel:[0,1,0]
	v_pk_fma_f32 v[152:153], v[136:137], v[156:157], v[152:153]
	v_cvt_scalef32_pk_f32_fp4 v[156:157], v6, 1.0 op_sel:[1,1,0]
	v_pk_fma_f32 v[154:155], v[138:139], v[156:157], v[154:155]
	v_cvt_scalef32_pk_f32_fp4 v[156:157], v7, 1.0
	v_pk_fma_f32 v[152:153], v[140:141], v[156:157], v[152:153]
	v_cvt_scalef32_pk_f32_fp4 v[156:157], v7, 1.0 op_sel:[1,0,0]
	v_pk_fma_f32 v[154:155], v[142:143], v[156:157], v[154:155]
	v_cvt_scalef32_pk_f32_fp4 v[156:157], v7, 1.0 op_sel:[0,1,0]
	v_pk_fma_f32 v[152:153], v[144:145], v[156:157], v[152:153]
	v_cvt_scalef32_pk_f32_fp4 v[156:157], v7, 1.0 op_sel:[1,1,0]
	v_pk_fma_f32 v[154:155], v[36:37], v[156:157], v[154:155]
	v_add_f32_e32 v85, v152, v153
	v_add_f32_e32 v87, v154, v155
	v_add_f32_e32 v83, v85, v87
	s_cmp_lt_u32 s52, 28
	s_cbranch_scc1 .LBB0_864
; static __device__ __forceinline__ void phase_peer(const Params& p, char* smraw) {
;     ...
;       GLOADU(ua, sua, sva, ea, ga_, 0); GLOADU(ub, sub_, svb, eb, gb2, 1); GLOADU(uc, suc, svc, ec, gc, 2);
; #pragma unroll 1
;       for (int it = 0; it < 32; it += 4) {
;         GLOADU(ud, sud, svd, ed, gd, it + 3);
;         GCOMPU(ua, sua, sva, ga_, it);
;         if (it + 4 < 32) GLOADU(ua, sua, sva, ea, ga_, it + 4);
;         GCOMPU(ub, sub_, svb, gb2, it + 1);
;         if (it + 5 < 32) GLOADU(ub, sub_, svb, eb, gb2, it + 5);
;         GCOMPU(uc, suc, svc, gc, it + 2);
;         if (it + 6 < 32) GLOADU(uc, suc, svc, ec, gc, it + 6);
;         GCOMPU(ud, sud, svd, gd, it + 3);
	s_waitcnt vmcnt(5)
	v_cvt_scalef32_pk_f32_fp4 v[156:157], v8, 1.0 op_sel:[0,1,0]
	v_cvt_scalef32_pk_f32_fp4 v[152:153], v8, 1.0
	v_pk_fma_f32 v[152:153], v[32:33], v[152:153], 0 op_sel_hi:[1,1,0]
	v_cvt_scalef32_pk_f32_fp4 v[154:155], v8, 1.0 op_sel:[1,0,0]
	v_add_f32_dpp v83, v83, v83 quad_perm:[1,0,3,2] row_mask:0xf bank_mask:0xf bound_ctrl:1
	v_pk_fma_f32 v[154:155], v[34:35], v[154:155], 0 op_sel_hi:[1,1,0]
	v_pk_fma_f32 v[152:153], v[40:41], v[156:157], v[152:153]
	v_cvt_scalef32_pk_f32_fp4 v[156:157], v8, 1.0 op_sel:[1,1,0]
	v_pk_fma_f32 v[154:155], v[42:43], v[156:157], v[154:155]
	v_add_f32_dpp v83, v83, v83 quad_perm:[2,3,0,1] row_mask:0xf bank_mask:0xf bound_ctrl:1
	v_cvt_scalef32_pk_f32_fp4 v[156:157], v9, 1.0
	v_pk_fma_f32 v[152:153], v[44:45], v[156:157], v[152:153]
	v_cvt_scalef32_pk_f32_fp4 v[156:157], v9, 1.0 op_sel:[1,0,0]
	v_pk_fma_f32 v[154:155], v[46:47], v[156:157], v[154:155]
	v_add_f32_dpp v83, v83, v83 row_half_mirror row_mask:0xf bank_mask:0xf bound_ctrl:1
	v_cvt_scalef32_pk_f32_fp4 v[156:157], v9, 1.0 op_sel:[0,1,0]
	v_pk_fma_f32 v[152:153], v[48:49], v[156:157], v[152:153]
	v_cvt_scalef32_pk_f32_fp4 v[156:157], v9, 1.0 op_sel:[1,1,0]
	v_pk_fma_f32 v[154:155], v[50:51], v[156:157], v[154:155]
	v_add_f32_dpp v83, v83, v83 row_mirror row_mask:0xf bank_mask:0xf bound_ctrl:1
	v_cvt_scalef32_pk_f32_fp4 v[156:157], v10, 1.0
	v_pk_fma_f32 v[152:153], v[52:53], v[156:157], v[152:153]
	v_cvt_scalef32_pk_f32_fp4 v[156:157], v10, 1.0 op_sel:[1,0,0]
	v_pk_fma_f32 v[154:155], v[54:55], v[156:157], v[154:155]
	s_mov_b64 exec, s[0:1]
	ds_write_b32 v77, v83 offset:976
	s_mov_b64 exec, -1
	v_cvt_scalef32_pk_f32_fp4 v[156:157], v10, 1.0 op_sel:[0,1,0]
	v_pk_fma_f32 v[152:153], v[104:105], v[156:157], v[152:153]
	v_cvt_scalef32_pk_f32_fp4 v[156:157], v10, 1.0 op_sel:[1,1,0]
	v_pk_fma_f32 v[154:155], v[106:107], v[156:157], v[154:155]
	v_cvt_scalef32_pk_f32_fp4 v[156:157], v11, 1.0
	v_pk_fma_f32 v[152:153], v[108:109], v[156:157], v[152:153]
	v_cvt_scalef32_pk_f32_fp4 v[156:157], v11, 1.0 op_sel:[1,0,0]
	v_pk_fma_f32 v[154:155], v[110:111], v[156:157], v[154:155]
	v_cvt_scalef32_pk_f32_fp4 v[156:157], v11, 1.0 op_sel:[0,1,0]
	v_pk_fma_f32 v[152:153], v[112:113], v[156:157], v[152:153]
	v_cvt_scalef32_pk_f32_fp4 v[156:157], v11, 1.0 op_sel:[1,1,0]
	v_pk_fma_f32 v[154:155], v[114:115], v[156:157], v[154:155]
	s_waitcnt vmcnt(4)
	v_cvt_scalef32_pk_f32_fp4 v[156:157], v12, 1.0
	v_pk_fma_f32 v[152:153], v[116:117], v[156:157], v[152:153]
	v_cvt_scalef32_pk_f32_fp4 v[156:157], v12, 1.0 op_sel:[1,0,0]
	v_pk_fma_f32 v[154:155], v[118:119], v[156:157], v[154:155]
	v_cvt_scalef32_pk_f32_fp4 v[156:157], v12, 1.0 op_sel:[0,1,0]
	v_pk_fma_f32 v[152:153], v[120:121], v[156:157], v[152:153]
	v_cvt_scalef32_pk_f32_fp4 v[156:157], v12, 1.0 op_sel:[1,1,0]
	v_pk_fma_f32 v[154:155], v[122:123], v[156:157], v[154:155]
	v_cvt_scalef32_pk_f32_fp4 v[156:157], v13, 1.0
	v_pk_fma_f32 v[152:153], v[124:125], v[156:157], v[152:153]
	v_cvt_scalef32_pk_f32_fp4 v[156:157], v13, 1.0 op_sel:[1,0,0]
	v_pk_fma_f32 v[154:155], v[126:127], v[156:157], v[154:155]
	v_cvt_scalef32_pk_f32_fp4 v[156:157], v13, 1.0 op_sel:[0,1,0]
	v_pk_fma_f32 v[152:153], v[128:129], v[156:157], v[152:153]
	v_cvt_scalef32_pk_f32_fp4 v[156:157], v13, 1.0 op_sel:[1,1,0]
	v_pk_fma_f32 v[154:155], v[130:131], v[156:157], v[154:155]
	v_cvt_scalef32_pk_f32_fp4 v[156:157], v14, 1.0
	v_pk_fma_f32 v[152:153], v[132:133], v[156:157], v[152:153]
	v_cvt_scalef32_pk_f32_fp4 v[156:157], v14, 1.0 op_sel:[1,0,0]
	v_pk_fma_f32 v[154:155], v[134:135], v[156:157], v[154:155]
	v_cvt_scalef32_pk_f32_fp4 v[156:157], v14, 1.0 op_sel:[0,1,0]
	v_pk_fma_f32 v[152:153], v[136:137], v[156:157], v[152:153]
	v_cvt_scalef32_pk_f32_fp4 v[156:157], v14, 1.0 op_sel:[1,1,0]
	v_pk_fma_f32 v[154:155], v[138:139], v[156:157], v[154:155]
	v_cvt_scalef32_pk_f32_fp4 v[156:157], v15, 1.0
	v_pk_fma_f32 v[152:153], v[140:141], v[156:157], v[152:153]
	v_cvt_scalef32_pk_f32_fp4 v[156:157], v15, 1.0 op_sel:[1,0,0]
	v_pk_fma_f32 v[154:155], v[142:143], v[156:157], v[154:155]
	v_cvt_scalef32_pk_f32_fp4 v[156:157], v15, 1.0 op_sel:[0,1,0]
	v_pk_fma_f32 v[152:153], v[144:145], v[156:157], v[152:153]
	v_cvt_scalef32_pk_f32_fp4 v[156:157], v15, 1.0 op_sel:[1,1,0]
	v_pk_fma_f32 v[154:155], v[36:37], v[156:157], v[154:155]
	v_add_f32_e32 v85, v152, v153
	v_add_f32_e32 v87, v154, v155
	v_add_f32_e32 v83, v85, v87
	s_waitcnt vmcnt(3)
	v_cvt_scalef32_pk_f32_fp4 v[156:157], v16, 1.0 op_sel:[0,1,0]
	v_cvt_scalef32_pk_f32_fp4 v[152:153], v16, 1.0
	v_pk_fma_f32 v[152:153], v[32:33], v[152:153], 0 op_sel_hi:[1,1,0]
	v_cvt_scalef32_pk_f32_fp4 v[154:155], v16, 1.0 op_sel:[1,0,0]
	v_add_f32_dpp v83, v83, v83 quad_perm:[1,0,3,2] row_mask:0xf bank_mask:0xf bound_ctrl:1
	v_pk_fma_f32 v[154:155], v[34:35], v[154:155], 0 op_sel_hi:[1,1,0]
	v_pk_fma_f32 v[152:153], v[40:41], v[156:157], v[152:153]
	v_cvt_scalef32_pk_f32_fp4 v[156:157], v16, 1.0 op_sel:[1,1,0]
	v_pk_fma_f32 v[154:155], v[42:43], v[156:157], v[154:155]
	v_add_f32_dpp v83, v83, v83 quad_perm:[2,3,0,1] row_mask:0xf bank_mask:0xf bound_ctrl:1
	v_cvt_scalef32_pk_f32_fp4 v[156:157], v17, 1.0
	v_pk_fma_f32 v[152:153], v[44:45], v[156:157], v[152:153]
	v_cvt_scalef32_pk_f32_fp4 v[156:157], v17, 1.0 op_sel:[1,0,0]
	v_pk_fma_f32 v[154:155], v[46:47], v[156:157], v[154:155]
	v_add_f32_dpp v83, v83, v83 row_half_mirror row_mask:0xf bank_mask:0xf bound_ctrl:1
	v_cvt_scalef32_pk_f32_fp4 v[156:157], v17, 1.0 op_sel:[0,1,0]
	v_pk_fma_f32 v[152:153], v[48:49], v[156:157], v[152:153]
	v_cvt_scalef32_pk_f32_fp4 v[156:157], v17, 1.0 op_sel:[1,1,0]
	v_pk_fma_f32 v[154:155], v[50:51], v[156:157], v[154:155]
	v_add_f32_dpp v83, v83, v83 row_mirror row_mask:0xf bank_mask:0xf bound_ctrl:1
	v_cvt_scalef32_pk_f32_fp4 v[156:157], v18, 1.0
	v_pk_fma_f32 v[152:153], v[52:53], v[156:157], v[152:153]
	v_cvt_scalef32_pk_f32_fp4 v[156:157], v18, 1.0 op_sel:[1,0,0]
	v_pk_fma_f32 v[154:155], v[54:55], v[156:157], v[154:155]
	s_mov_b64 exec, s[0:1]
	ds_write_b32 v77, v83 offset:992
	s_mov_b64 exec, -1
	v_cvt_scalef32_pk_f32_fp4 v[156:157], v18, 1.0 op_sel:[0,1,0]
	v_pk_fma_f32 v[152:153], v[104:105], v[156:157], v[152:153]
	v_cvt_scalef32_pk_f32_fp4 v[156:157], v18, 1.0 op_sel:[1,1,0]
	v_pk_fma_f32 v[154:155], v[106:107], v[156:157], v[154:155]
	v_cvt_scalef32_pk_f32_fp4 v[156:157], v19, 1.0
	v_pk_fma_f32 v[152:153], v[108:109], v[156:157], v[152:153]
	v_cvt_scalef32_pk_f32_fp4 v[156:157], v19, 1.0 op_sel:[1,0,0]
	v_pk_fma_f32 v[154:155], v[110:111], v[156:157], v[154:155]
	v_cvt_scalef32_pk_f32_fp4 v[156:157], v19, 1.0 op_sel:[0,1,0]
	v_pk_fma_f32 v[152:153], v[112:113], v[156:157], v[152:153]
	v_cvt_scalef32_pk_f32_fp4 v[156:157], v19, 1.0 op_sel:[1,1,0]
	v_pk_fma_f32 v[154:155], v[114:115], v[156:157], v[154:155]
	s_waitcnt vmcnt(2)
; static __device__ __forceinline__ void phase_peer(const Params& p, char* smraw) {
;     ...
;       GLOADU(ua, sua, sva, ea, ga_, 0); GLOADU(ub, sub_, svb, eb, gb2, 1); GLOADU(uc, suc, svc, ec, gc, 2);
; #pragma unroll 1
;       for (int it = 0; it < 32; it += 4) {
;         GLOADU(ud, sud, svd, ed, gd, it + 3);
;         GCOMPU(ua, sua, sva, ga_, it);
;         if (it + 4 < 32) GLOADU(ua, sua, sva, ea, ga_, it + 4);
;         GCOMPU(ub, sub_, svb, gb2, it + 1);
;         if (it + 5 < 32) GLOADU(ub, sub_, svb, eb, gb2, it + 5);
;         GCOMPU(uc, suc, svc, gc, it + 2);
;         if (it + 6 < 32) GLOADU(uc, suc, svc, ec, gc, it + 6);
;         GCOMPU(ud, sud, svd, gd, it + 3);
	v_cvt_scalef32_pk_f32_fp4 v[156:157], v20, 1.0
	v_pk_fma_f32 v[152:153], v[116:117], v[156:157], v[152:153]
	v_cvt_scalef32_pk_f32_fp4 v[156:157], v20, 1.0 op_sel:[1,0,0]
	v_pk_fma_f32 v[154:155], v[118:119], v[156:157], v[154:155]
	v_cvt_scalef32_pk_f32_fp4 v[156:157], v20, 1.0 op_sel:[0,1,0]
	v_pk_fma_f32 v[152:153], v[120:121], v[156:157], v[152:153]
	v_cvt_scalef32_pk_f32_fp4 v[156:157], v20, 1.0 op_sel:[1,1,0]
	v_pk_fma_f32 v[154:155], v[122:123], v[156:157], v[154:155]
	v_cvt_scalef32_pk_f32_fp4 v[156:157], v21, 1.0
	v_pk_fma_f32 v[152:153], v[124:125], v[156:157], v[152:153]
	v_cvt_scalef32_pk_f32_fp4 v[156:157], v21, 1.0 op_sel:[1,0,0]
	v_pk_fma_f32 v[154:155], v[126:127], v[156:157], v[154:155]
	v_cvt_scalef32_pk_f32_fp4 v[156:157], v21, 1.0 op_sel:[0,1,0]
	v_pk_fma_f32 v[152:153], v[128:129], v[156:157], v[152:153]
	v_cvt_scalef32_pk_f32_fp4 v[156:157], v21, 1.0 op_sel:[1,1,0]
	v_pk_fma_f32 v[154:155], v[130:131], v[156:157], v[154:155]
	v_cvt_scalef32_pk_f32_fp4 v[156:157], v22, 1.0
	v_pk_fma_f32 v[152:153], v[132:133], v[156:157], v[152:153]
	v_cvt_scalef32_pk_f32_fp4 v[156:157], v22, 1.0 op_sel:[1,0,0]
	v_pk_fma_f32 v[154:155], v[134:135], v[156:157], v[154:155]
	v_cvt_scalef32_pk_f32_fp4 v[156:157], v22, 1.0 op_sel:[0,1,0]
	v_pk_fma_f32 v[152:153], v[136:137], v[156:157], v[152:153]
	v_cvt_scalef32_pk_f32_fp4 v[156:157], v22, 1.0 op_sel:[1,1,0]
	v_pk_fma_f32 v[154:155], v[138:139], v[156:157], v[154:155]
	v_cvt_scalef32_pk_f32_fp4 v[156:157], v23, 1.0
	v_pk_fma_f32 v[152:153], v[140:141], v[156:157], v[152:153]
	v_cvt_scalef32_pk_f32_fp4 v[156:157], v23, 1.0 op_sel:[1,0,0]
	v_pk_fma_f32 v[154:155], v[142:143], v[156:157], v[154:155]
	v_cvt_scalef32_pk_f32_fp4 v[156:157], v23, 1.0 op_sel:[0,1,0]
	v_pk_fma_f32 v[152:153], v[144:145], v[156:157], v[152:153]
	v_cvt_scalef32_pk_f32_fp4 v[156:157], v23, 1.0 op_sel:[1,1,0]
	v_pk_fma_f32 v[154:155], v[36:37], v[156:157], v[154:155]
	v_add_f32_e32 v85, v152, v153
	v_add_f32_e32 v87, v154, v155
	v_add_f32_e32 v83, v85, v87
	s_waitcnt vmcnt(1)
	v_cvt_scalef32_pk_f32_fp4 v[156:157], v24, 1.0 op_sel:[0,1,0]
	v_cvt_scalef32_pk_f32_fp4 v[152:153], v24, 1.0
	v_pk_fma_f32 v[152:153], v[32:33], v[152:153], 0 op_sel_hi:[1,1,0]
	v_cvt_scalef32_pk_f32_fp4 v[154:155], v24, 1.0 op_sel:[1,0,0]
	v_add_f32_dpp v83, v83, v83 quad_perm:[1,0,3,2] row_mask:0xf bank_mask:0xf bound_ctrl:1
	v_pk_fma_f32 v[154:155], v[34:35], v[154:155], 0 op_sel_hi:[1,1,0]
	v_pk_fma_f32 v[152:153], v[40:41], v[156:157], v[152:153]
	v_cvt_scalef32_pk_f32_fp4 v[156:157], v24, 1.0 op_sel:[1,1,0]
	v_pk_fma_f32 v[154:155], v[42:43], v[156:157], v[154:155]
	v_add_f32_dpp v83, v83, v83 quad_perm:[2,3,0,1] row_mask:0xf bank_mask:0xf bound_ctrl:1
	v_cvt_scalef32_pk_f32_fp4 v[156:157], v25, 1.0
	v_pk_fma_f32 v[152:153], v[44:45], v[156:157], v[152:153]
	v_cvt_scalef32_pk_f32_fp4 v[156:157], v25, 1.0 op_sel:[1,0,0]
	v_pk_fma_f32 v[154:155], v[46:47], v[156:157], v[154:155]
	v_add_f32_dpp v83, v83, v83 row_half_mirror row_mask:0xf bank_mask:0xf bound_ctrl:1
	v_cvt_scalef32_pk_f32_fp4 v[156:157], v25, 1.0 op_sel:[0,1,0]
	v_pk_fma_f32 v[152:153], v[48:49], v[156:157], v[152:153]
	v_cvt_scalef32_pk_f32_fp4 v[156:157], v25, 1.0 op_sel:[1,1,0]
	v_pk_fma_f32 v[154:155], v[50:51], v[156:157], v[154:155]
	v_add_f32_dpp v83, v83, v83 row_mirror row_mask:0xf bank_mask:0xf bound_ctrl:1
	v_cvt_scalef32_pk_f32_fp4 v[156:157], v26, 1.0
	v_pk_fma_f32 v[152:153], v[52:53], v[156:157], v[152:153]
	v_cvt_scalef32_pk_f32_fp4 v[156:157], v26, 1.0 op_sel:[1,0,0]
	v_pk_fma_f32 v[154:155], v[54:55], v[156:157], v[154:155]
	s_mov_b64 exec, s[0:1]
	ds_write_b32 v77, v83 offset:1008
	s_mov_b64 exec, -1
	v_cvt_scalef32_pk_f32_fp4 v[156:157], v26, 1.0 op_sel:[0,1,0]
	v_pk_fma_f32 v[152:153], v[104:105], v[156:157], v[152:153]
	v_cvt_scalef32_pk_f32_fp4 v[156:157], v26, 1.0 op_sel:[1,1,0]
	v_pk_fma_f32 v[154:155], v[106:107], v[156:157], v[154:155]
	v_cvt_scalef32_pk_f32_fp4 v[156:157], v27, 1.0
	v_pk_fma_f32 v[152:153], v[108:109], v[156:157], v[152:153]
	v_cvt_scalef32_pk_f32_fp4 v[156:157], v27, 1.0 op_sel:[1,0,0]
	v_pk_fma_f32 v[154:155], v[110:111], v[156:157], v[154:155]
	v_cvt_scalef32_pk_f32_fp4 v[156:157], v27, 1.0 op_sel:[0,1,0]
	v_pk_fma_f32 v[152:153], v[112:113], v[156:157], v[152:153]
	v_cvt_scalef32_pk_f32_fp4 v[156:157], v27, 1.0 op_sel:[1,1,0]
	v_pk_fma_f32 v[154:155], v[114:115], v[156:157], v[154:155]
	s_waitcnt vmcnt(0)
	v_cvt_scalef32_pk_f32_fp4 v[156:157], v28, 1.0
	v_pk_fma_f32 v[152:153], v[116:117], v[156:157], v[152:153]
	v_cvt_scalef32_pk_f32_fp4 v[156:157], v28, 1.0 op_sel:[1,0,0]
	v_pk_fma_f32 v[154:155], v[118:119], v[156:157], v[154:155]
	v_cvt_scalef32_pk_f32_fp4 v[156:157], v28, 1.0 op_sel:[0,1,0]
	v_pk_fma_f32 v[152:153], v[120:121], v[156:157], v[152:153]
	v_cvt_scalef32_pk_f32_fp4 v[156:157], v28, 1.0 op_sel:[1,1,0]
	v_pk_fma_f32 v[154:155], v[122:123], v[156:157], v[154:155]
	v_cvt_scalef32_pk_f32_fp4 v[156:157], v29, 1.0
	v_pk_fma_f32 v[152:153], v[124:125], v[156:157], v[152:153]
	v_cvt_scalef32_pk_f32_fp4 v[156:157], v29, 1.0 op_sel:[1,0,0]
	v_pk_fma_f32 v[154:155], v[126:127], v[156:157], v[154:155]
	v_cvt_scalef32_pk_f32_fp4 v[156:157], v29, 1.0 op_sel:[0,1,0]
	v_pk_fma_f32 v[152:153], v[128:129], v[156:157], v[152:153]
	v_cvt_scalef32_pk_f32_fp4 v[156:157], v29, 1.0 op_sel:[1,1,0]
	v_pk_fma_f32 v[154:155], v[130:131], v[156:157], v[154:155]
	v_cvt_scalef32_pk_f32_fp4 v[156:157], v30, 1.0
	v_pk_fma_f32 v[152:153], v[132:133], v[156:157], v[152:153]
	v_cvt_scalef32_pk_f32_fp4 v[156:157], v30, 1.0 op_sel:[1,0,0]
	v_pk_fma_f32 v[154:155], v[134:135], v[156:157], v[154:155]
	v_cvt_scalef32_pk_f32_fp4 v[156:157], v30, 1.0 op_sel:[0,1,0]
	v_pk_fma_f32 v[152:153], v[136:137], v[156:157], v[152:153]
	v_cvt_scalef32_pk_f32_fp4 v[156:157], v30, 1.0 op_sel:[1,1,0]
	v_pk_fma_f32 v[154:155], v[138:139], v[156:157], v[154:155]
	v_cvt_scalef32_pk_f32_fp4 v[156:157], v31, 1.0
	v_pk_fma_f32 v[152:153], v[140:141], v[156:157], v[152:153]
	v_cvt_scalef32_pk_f32_fp4 v[156:157], v31, 1.0 op_sel:[1,0,0]
	v_pk_fma_f32 v[154:155], v[142:143], v[156:157], v[154:155]
	v_cvt_scalef32_pk_f32_fp4 v[156:157], v31, 1.0 op_sel:[0,1,0]
	v_pk_fma_f32 v[152:153], v[144:145], v[156:157], v[152:153]
	v_cvt_scalef32_pk_f32_fp4 v[156:157], v31, 1.0 op_sel:[1,1,0]
	v_pk_fma_f32 v[154:155], v[36:37], v[156:157], v[154:155]
	v_add_f32_e32 v85, v152, v153
	v_add_f32_e32 v87, v154, v155
	v_add_f32_e32 v83, v85, v87
	s_nop 1
	v_add_f32_dpp v83, v83, v83 quad_perm:[1,0,3,2] row_mask:0xf bank_mask:0xf bound_ctrl:1
	s_nop 1
	v_add_f32_dpp v83, v83, v83 quad_perm:[2,3,0,1] row_mask:0xf bank_mask:0xf bound_ctrl:1
	s_nop 1
	v_add_f32_dpp v83, v83, v83 row_half_mirror row_mask:0xf bank_mask:0xf bound_ctrl:1
	s_nop 1
	v_add_f32_dpp v83, v83, v83 row_mirror row_mask:0xf bank_mask:0xf bound_ctrl:1
	s_mov_b64 exec, s[0:1]
	ds_write_b32 v77, v83 offset:1024
	s_mov_b64 exec, -1
.LBB0_894:
	s_waitcnt lgkmcnt(0)
	v_mbcnt_lo_u32_b32 v6, -1, 0
	v_mbcnt_hi_u32_b32 v6, -1, v6
	v_and_b32_e32 v1, -16, v186
	v_lshl_add_u32 v6, v6, 2, v1
	ds_read_b32 v83, v6 offset:1024
	ds_read_b32 v2, v6 offset:512
	ds_read_b32 v7, v6
	ds_read_b32 v24, v6 offset:1280
	ds_read_b32 v4, v6 offset:768
	ds_read_b32 v8, v6 offset:256
	s_waitcnt lgkmcnt(0)
	v_lshlrev_b32_e32 v7, 2, v7
	v_lshlrev_b32_e32 v8, 2, v8
	global_load_dword v9, v7, s[38:39]
	global_load_dword v3, v7, s[40:41]
	global_load_dword v10, v8, s[38:39]
	global_load_dword v5, v8, s[40:41]
	s_waitcnt vmcnt(0)
	v_mul_f32_e32 v83, v9, v83
	v_mul_f32_e32 v24, v10, v24
	v_mul_f32_e32 v85, 0x3f3504f3, v83
	v_cmp_nlt_f32_e64 s[36:37], |v85|, 1.0
	s_and_saveexec_b64 s[50:51], s[36:37]
	s_xor_b64 s[36:37], exec, s[50:51]
	s_cbranch_execz .Lpg1_small
	v_fma_f32 v87, |v85|, s42, v204
	v_fma_f32 v87, |v85|, v87, s43
	v_fma_f32 v87, |v85|, v87, s88
	v_fma_f32 v87, |v85|, v87, s89
	v_fma_f32 v87, |v85|, v87, s90
	v_fma_f32 v87, |v85|, v87, s91
	v_fma_f32 v87, |v85|, v87, |v85|
	v_mul_f32_e32 v89, 0xbfb8aa3b, v87
	v_fma_f32 v91, v87, s92, -v89
	v_rndne_f32_e32 v93, v89
	v_fmac_f32_e32 v91, 0xb2a5705f, v87
	v_sub_f32_e32 v89, v89, v93
	v_add_f32_e32 v89, v89, v91
	v_cvt_i32_f32_e32 v91, v93
	v_exp_f32_e32 v89, v89
	v_cmp_nlt_f32_e32 vcc, s93, v87
	v_ldexp_f32 v89, v89, v91
	s_nop 0
	v_cndmask_b32_e32 v89, 0, v89, vcc
	v_cmp_ngt_f32_e32 vcc, s94, v87
	s_nop 1
	v_cndmask_b32_e32 v87, v205, v89, vcc
	v_sub_f32_e32 v87, 1.0, v87

; static __device__ __forceinline__ void phase_peer(const Params& p, char* smraw) {
;     ...
;     f2_t o2[32];
; #pragma unroll
;     for (int i = 0; i < 32; ++i) o2[i] = f2_t{0.f, 0.f};
;     {
;       u32x4 va[2], vb[2], vc[2], vd[2]; float aa, ab, ac, ad;
;     ...
;       GLOADV(va, aa, 0); GLOADV(vb, ab, 1); GLOADV(vc, ac, 2);
.Lpg2_join:
	s_or_b64 exec, exec, s[36:37]
	v_bfi_b32 v85, s95, v87, v85
	v_mul_f32_e32 v24, 0.5, v24
	v_add_f32_e32 v85, 1.0, v85
	v_mul_f32_e32 v24, v24, v85
	v_mul_f32_e32 v24, v4, v24
	v_mul_f32_e32 v24, v5, v24
	ds_write_b32 v6, v24 offset:1280
	s_mov_b32 s50, 0
	v_mov_b64_e32 v[104:105], 0
	v_mov_b64_e32 v[106:107], 0
	v_mov_b64_e32 v[108:109], 0
	v_mov_b64_e32 v[110:111], 0
	v_mov_b64_e32 v[112:113], 0
	v_mov_b64_e32 v[114:115], 0
	v_mov_b64_e32 v[116:117], 0
	v_mov_b64_e32 v[118:119], 0
	v_mov_b64_e32 v[120:121], 0
	v_mov_b64_e32 v[122:123], 0
	v_mov_b64_e32 v[124:125], 0
	v_mov_b64_e32 v[126:127], 0
	v_mov_b64_e32 v[128:129], 0
	v_mov_b64_e32 v[130:131], 0
	v_mov_b64_e32 v[132:133], 0
	v_mov_b64_e32 v[134:135], 0
	v_mov_b64_e32 v[136:137], 0
	v_mov_b64_e32 v[138:139], 0
	v_mov_b64_e32 v[140:141], 0
	v_mov_b64_e32 v[142:143], 0
	v_mov_b64_e32 v[144:145], 0
	v_mov_b64_e32 v[146:147], 0
	v_mov_b64_e32 v[148:149], 0
	v_mov_b64_e32 v[150:151], 0
	v_mov_b64_e32 v[152:153], 0
	v_mov_b64_e32 v[154:155], 0
	v_mov_b64_e32 v[156:157], 0
	v_mov_b64_e32 v[158:159], 0
	v_mov_b64_e32 v[160:161], 0
	v_mov_b64_e32 v[162:163], 0
	v_mov_b64_e32 v[164:165], 0
	v_mov_b64_e32 v[166:167], 0
	v_mov_b32_e32 v77, v200
	v_mov_b32_e32 v33, 0
	v_mov_b32_e32 v35, 0
	v_mov_b32_e32 v47, 0
	ds_read_b32 v46, v186
	ds_read_b32 v32, v186 offset:16
	ds_read_b32 v34, v186 offset:32
	s_waitcnt lgkmcnt(0)
	v_lshlrev_b32_e32 v46, 9, v46
	v_lshl_add_u64 v[36:37], v[46:47], 0, v[66:67]
	global_load_dwordx4 v[0:3], v[36:37], off
	global_load_dwordx4 v[4:7], v[36:37], off offset:256
	v_lshlrev_b32_e32 v32, 9, v32
	v_lshl_add_u64 v[36:37], v[32:33], 0, v[66:67]
	global_load_dwordx4 v[8:11], v[36:37], off
	global_load_dwordx4 v[12:15], v[36:37], off offset:256
	v_lshlrev_b32_e32 v34, 9, v34
	v_lshl_add_u64 v[36:37], v[34:35], 0, v[66:67]
	global_load_dwordx4 v[16:19], v[36:37], off
	global_load_dwordx4 v[20:23], v[36:37], off offset:256
	ds_read_b32 v32, v77
	ds_read_b32 v38, v77 offset:976
	s_waitcnt lgkmcnt(0)
	v_lshlrev_b32_e32 v32, 9, v32
	v_lshl_add_u64 v[36:37], v[32:33], 0, v[66:67]
	global_load_dwordx4 v[24:27], v[36:37], off
	global_load_dwordx4 v[28:31], v[36:37], off offset:256
	ds_read_b32 v34, v77 offset:16
	ds_read_b32 v40, v77 offset:992
	s_waitcnt vmcnt(7)
	v_cvt_scalef32_pk_f32_fp4 v[42:43], v0, 1.0
	v_pk_fma_f32 v[166:167], v[38:39], v[42:43], v[166:167] op_sel_hi:[0,1,1]
	v_cvt_scalef32_pk_f32_fp4 v[44:45], v0, 1.0 op_sel:[1,0,0]
	v_pk_fma_f32 v[164:165], v[38:39], v[44:45], v[164:165] op_sel_hi:[0,1,1]
	v_cvt_scalef32_pk_f32_fp4 v[42:43], v0, 1.0 op_sel:[0,1,0]
	v_pk_fma_f32 v[162:163], v[38:39], v[42:43], v[162:163] op_sel_hi:[0,1,1]
	v_cvt_scalef32_pk_f32_fp4 v[44:45], v0, 1.0 op_sel:[1,1,0]
	v_pk_fma_f32 v[160:161], v[38:39], v[44:45], v[160:161] op_sel_hi:[0,1,1]
	v_cvt_scalef32_pk_f32_fp4 v[42:43], v1, 1.0
	v_pk_fma_f32 v[158:159], v[38:39], v[42:43], v[158:159] op_sel_hi:[0,1,1]
	v_cvt_scalef32_pk_f32_fp4 v[44:45], v1, 1.0 op_sel:[1,0,0]
	v_pk_fma_f32 v[156:157], v[38:39], v[44:45], v[156:157] op_sel_hi:[0,1,1]
	v_cvt_scalef32_pk_f32_fp4 v[42:43], v1, 1.0 op_sel:[0,1,0]
	v_pk_fma_f32 v[154:155], v[38:39], v[42:43], v[154:155] op_sel_hi:[0,1,1]
	v_cvt_scalef32_pk_f32_fp4 v[44:45], v1, 1.0 op_sel:[1,1,0]
	v_pk_fma_f32 v[152:153], v[38:39], v[44:45], v[152:153] op_sel_hi:[0,1,1]
	v_cvt_scalef32_pk_f32_fp4 v[42:43], v2, 1.0
	v_pk_fma_f32 v[150:151], v[38:39], v[42:43], v[150:151] op_sel_hi:[0,1,1]
	v_cvt_scalef32_pk_f32_fp4 v[44:45], v2, 1.0 op_sel:[1,0,0]
	v_pk_fma_f32 v[148:149], v[38:39], v[44:45], v[148:149] op_sel_hi:[0,1,1]
	v_cvt_scalef32_pk_f32_fp4 v[42:43], v2, 1.0 op_sel:[0,1,0]
	v_pk_fma_f32 v[146:147], v[38:39], v[42:43], v[146:147] op_sel_hi:[0,1,1]
	v_cvt_scalef32_pk_f32_fp4 v[44:45], v2, 1.0 op_sel:[1,1,0]
	v_pk_fma_f32 v[144:145], v[38:39], v[44:45], v[144:145] op_sel_hi:[0,1,1]
	v_cvt_scalef32_pk_f32_fp4 v[42:43], v3, 1.0
	v_pk_fma_f32 v[142:143], v[38:39], v[42:43], v[142:143] op_sel_hi:[0,1,1]
	v_cvt_scalef32_pk_f32_fp4 v[44:45], v3, 1.0 op_sel:[1,0,0]
	v_pk_fma_f32 v[140:141], v[38:39], v[44:45], v[140:141] op_sel_hi:[0,1,1]
	v_cvt_scalef32_pk_f32_fp4 v[42:43], v3, 1.0 op_sel:[0,1,0]
	v_pk_fma_f32 v[138:139], v[38:39], v[42:43], v[138:139] op_sel_hi:[0,1,1]
	v_cvt_scalef32_pk_f32_fp4 v[44:45], v3, 1.0 op_sel:[1,1,0]
	v_pk_fma_f32 v[136:137], v[38:39], v[44:45], v[136:137] op_sel_hi:[0,1,1]
	s_waitcnt vmcnt(6)
	v_cvt_scalef32_pk_f32_fp4 v[42:43], v4, 1.0
	v_pk_fma_f32 v[134:135], v[38:39], v[42:43], v[134:135] op_sel_hi:[0,1,1]
	v_cvt_scalef32_pk_f32_fp4 v[44:45], v4, 1.0 op_sel:[1,0,0]
	v_pk_fma_f32 v[132:133], v[38:39], v[44:45], v[132:133] op_sel_hi:[0,1,1]
	v_cvt_scalef32_pk_f32_fp4 v[42:43], v4, 1.0 op_sel:[0,1,0]
	v_pk_fma_f32 v[130:131], v[38:39], v[42:43], v[130:131] op_sel_hi:[0,1,1]
	v_cvt_scalef32_pk_f32_fp4 v[44:45], v4, 1.0 op_sel:[1,1,0]
	v_pk_fma_f32 v[128:129], v[38:39], v[44:45], v[128:129] op_sel_hi:[0,1,1]
	v_cvt_scalef32_pk_f32_fp4 v[42:43], v5, 1.0
	v_pk_fma_f32 v[126:127], v[38:39], v[42:43], v[126:127] op_sel_hi:[0,1,1]
	v_cvt_scalef32_pk_f32_fp4 v[44:45], v5, 1.0 op_sel:[1,0,0]
	v_pk_fma_f32 v[124:125], v[38:39], v[44:45], v[124:125] op_sel_hi:[0,1,1]
	v_cvt_scalef32_pk_f32_fp4 v[42:43], v5, 1.0 op_sel:[0,1,0]
	v_pk_fma_f32 v[122:123], v[38:39], v[42:43], v[122:123] op_sel_hi:[0,1,1]
	v_cvt_scalef32_pk_f32_fp4 v[44:45], v5, 1.0 op_sel:[1,1,0]
	v_pk_fma_f32 v[120:121], v[38:39], v[44:45], v[120:121] op_sel_hi:[0,1,1]
	v_cvt_scalef32_pk_f32_fp4 v[42:43], v6, 1.0
	v_pk_fma_f32 v[118:119], v[38:39], v[42:43], v[118:119] op_sel_hi:[0,1,1]
	v_cvt_scalef32_pk_f32_fp4 v[44:45], v6, 1.0 op_sel:[1,0,0]
	v_pk_fma_f32 v[116:117], v[38:39], v[44:45], v[116:117] op_sel_hi:[0,1,1]
	v_cvt_scalef32_pk_f32_fp4 v[42:43], v6, 1.0 op_sel:[0,1,0]
	v_pk_fma_f32 v[114:115], v[38:39], v[42:43], v[114:115] op_sel_hi:[0,1,1]
	v_cvt_scalef32_pk_f32_fp4 v[44:45], v6, 1.0 op_sel:[1,1,0]
	v_pk_fma_f32 v[112:113], v[38:39], v[44:45], v[112:113] op_sel_hi:[0,1,1]
	v_cvt_scalef32_pk_f32_fp4 v[42:43], v7, 1.0
	v_pk_fma_f32 v[110:111], v[38:39], v[42:43], v[110:111] op_sel_hi:[0,1,1]
	v_cvt_scalef32_pk_f32_fp4 v[44:45], v7, 1.0 op_sel:[1,0,0]
	v_pk_fma_f32 v[108:109], v[38:39], v[44:45], v[108:109] op_sel_hi:[0,1,1]
	v_cvt_scalef32_pk_f32_fp4 v[42:43], v7, 1.0 op_sel:[0,1,0]
	v_pk_fma_f32 v[106:107], v[38:39], v[42:43], v[106:107] op_sel_hi:[0,1,1]
	v_cvt_scalef32_pk_f32_fp4 v[44:45], v7, 1.0 op_sel:[1,1,0]
	v_pk_fma_f32 v[104:105], v[38:39], v[44:45], v[104:105] op_sel_hi:[0,1,1]
; static __device__ __forceinline__ void phase_peer(const Params& p, char* smraw) {
;     ...
;       GLOADV(va, aa, 0); GLOADV(vb, ab, 1); GLOADV(vc, ac, 2);
; #pragma unroll 1
;       for (int it = 0; it < 32; it += 4) {
;         GLOADV(vd, ad, it + 3);
;         GCOMPV(va, aa);
;         if (it + 4 < 32) GLOADV(va, aa, it + 4);
;         GCOMPV(vb, ab);
;         if (it + 5 < 32) GLOADV(vb, ab, it + 5);
;         GCOMPV(vc, ac);
;         if (it + 6 < 32) GLOADV(vc, ac, it + 6);
;         GCOMPV(vd, ad);
;       }
.Lpb_loop:
	s_waitcnt lgkmcnt(0)
	v_lshlrev_b32_e32 v34, 9, v34
	v_lshl_add_u64 v[36:37], v[34:35], 0, v[66:67]
	global_load_dwordx4 v[0:3], v[36:37], off
	global_load_dwordx4 v[4:7], v[36:37], off offset:256
	ds_read_b32 v32, v77 offset:32
	ds_read_b32 v38, v77 offset:1008
	s_waitcnt vmcnt(7)
	v_cvt_scalef32_pk_f32_fp4 v[42:43], v8, 1.0
	v_pk_fma_f32 v[166:167], v[40:41], v[42:43], v[166:167] op_sel_hi:[0,1,1]
	v_cvt_scalef32_pk_f32_fp4 v[44:45], v8, 1.0 op_sel:[1,0,0]
	v_pk_fma_f32 v[164:165], v[40:41], v[44:45], v[164:165] op_sel_hi:[0,1,1]
	v_cvt_scalef32_pk_f32_fp4 v[42:43], v8, 1.0 op_sel:[0,1,0]
	v_pk_fma_f32 v[162:163], v[40:41], v[42:43], v[162:163] op_sel_hi:[0,1,1]
	v_cvt_scalef32_pk_f32_fp4 v[44:45], v8, 1.0 op_sel:[1,1,0]
	v_pk_fma_f32 v[160:161], v[40:41], v[44:45], v[160:161] op_sel_hi:[0,1,1]
	v_cvt_scalef32_pk_f32_fp4 v[42:43], v9, 1.0
	v_pk_fma_f32 v[158:159], v[40:41], v[42:43], v[158:159] op_sel_hi:[0,1,1]
	v_cvt_scalef32_pk_f32_fp4 v[44:45], v9, 1.0 op_sel:[1,0,0]
	v_pk_fma_f32 v[156:157], v[40:41], v[44:45], v[156:157] op_sel_hi:[0,1,1]
	v_cvt_scalef32_pk_f32_fp4 v[42:43], v9, 1.0 op_sel:[0,1,0]
	v_pk_fma_f32 v[154:155], v[40:41], v[42:43], v[154:155] op_sel_hi:[0,1,1]
	v_cvt_scalef32_pk_f32_fp4 v[44:45], v9, 1.0 op_sel:[1,1,0]
	v_pk_fma_f32 v[152:153], v[40:41], v[44:45], v[152:153] op_sel_hi:[0,1,1]
	v_cvt_scalef32_pk_f32_fp4 v[42:43], v10, 1.0
	v_pk_fma_f32 v[150:151], v[40:41], v[42:43], v[150:151] op_sel_hi:[0,1,1]
	v_cvt_scalef32_pk_f32_fp4 v[44:45], v10, 1.0 op_sel:[1,0,0]
	v_pk_fma_f32 v[148:149], v[40:41], v[44:45], v[148:149] op_sel_hi:[0,1,1]
	v_cvt_scalef32_pk_f32_fp4 v[42:43], v10, 1.0 op_sel:[0,1,0]
	v_pk_fma_f32 v[146:147], v[40:41], v[42:43], v[146:147] op_sel_hi:[0,1,1]
	v_cvt_scalef32_pk_f32_fp4 v[44:45], v10, 1.0 op_sel:[1,1,0]
	v_pk_fma_f32 v[144:145], v[40:41], v[44:45], v[144:145] op_sel_hi:[0,1,1]
	v_cvt_scalef32_pk_f32_fp4 v[42:43], v11, 1.0
	v_pk_fma_f32 v[142:143], v[40:41], v[42:43], v[142:143] op_sel_hi:[0,1,1]
	v_cvt_scalef32_pk_f32_fp4 v[44:45], v11, 1.0 op_sel:[1,0,0]
	v_pk_fma_f32 v[140:141], v[40:41], v[44:45], v[140:141] op_sel_hi:[0,1,1]
	v_cvt_scalef32_pk_f32_fp4 v[42:43], v11, 1.0 op_sel:[0,1,0]
	v_pk_fma_f32 v[138:139], v[40:41], v[42:43], v[138:139] op_sel_hi:[0,1,1]
	v_cvt_scalef32_pk_f32_fp4 v[44:45], v11, 1.0 op_sel:[1,1,0]
	v_pk_fma_f32 v[136:137], v[40:41], v[44:45], v[136:137] op_sel_hi:[0,1,1]
	s_waitcnt vmcnt(6)
	v_cvt_scalef32_pk_f32_fp4 v[42:43], v12, 1.0
	v_pk_fma_f32 v[134:135], v[40:41], v[42:43], v[134:135] op_sel_hi:[0,1,1]
	v_cvt_scalef32_pk_f32_fp4 v[44:45], v12, 1.0 op_sel:[1,0,0]
	v_pk_fma_f32 v[132:133], v[40:41], v[44:45], v[132:133] op_sel_hi:[0,1,1]
	v_cvt_scalef32_pk_f32_fp4 v[42:43], v12, 1.0 op_sel:[0,1,0]
	v_pk_fma_f32 v[130:131], v[40:41], v[42:43], v[130:131] op_sel_hi:[0,1,1]
	v_cvt_scalef32_pk_f32_fp4 v[44:45], v12, 1.0 op_sel:[1,1,0]
	v_pk_fma_f32 v[128:129], v[40:41], v[44:45], v[128:129] op_sel_hi:[0,1,1]
	v_cvt_scalef32_pk_f32_fp4 v[42:43], v13, 1.0
	v_pk_fma_f32 v[126:127], v[40:41], v[42:43], v[126:127] op_sel_hi:[0,1,1]
	v_cvt_scalef32_pk_f32_fp4 v[44:45], v13, 1.0 op_sel:[1,0,0]
	v_pk_fma_f32 v[124:125], v[40:41], v[44:45], v[124:125] op_sel_hi:[0,1,1]
	v_cvt_scalef32_pk_f32_fp4 v[42:43], v13, 1.0 op_sel:[0,1,0]
	v_pk_fma_f32 v[122:123], v[40:41], v[42:43], v[122:123] op_sel_hi:[0,1,1]
	v_cvt_scalef32_pk_f32_fp4 v[44:45], v13, 1.0 op_sel:[1,1,0]
	v_pk_fma_f32 v[120:121], v[40:41], v[44:45], v[120:121] op_sel_hi:[0,1,1]
	v_cvt_scalef32_pk_f32_fp4 v[42:43], v14, 1.0
	v_pk_fma_f32 v[118:119], v[40:41], v[42:43], v[118:119] op_sel_hi:[0,1,1]
	v_cvt_scalef32_pk_f32_fp4 v[44:45], v14, 1.0 op_sel:[1,0,0]
	v_pk_fma_f32 v[116:117], v[40:41], v[44:45], v[116:117] op_sel_hi:[0,1,1]
	v_cvt_scalef32_pk_f32_fp4 v[42:43], v14, 1.0 op_sel:[0,1,0]
	v_pk_fma_f32 v[114:115], v[40:41], v[42:43], v[114:115] op_sel_hi:[0,1,1]
	v_cvt_scalef32_pk_f32_fp4 v[44:45], v14, 1.0 op_sel:[1,1,0]
	v_pk_fma_f32 v[112:113], v[40:41], v[44:45], v[112:113] op_sel_hi:[0,1,1]
	v_cvt_scalef32_pk_f32_fp4 v[42:43], v15, 1.0
	v_pk_fma_f32 v[110:111], v[40:41], v[42:43], v[110:111] op_sel_hi:[0,1,1]
	v_cvt_scalef32_pk_f32_fp4 v[44:45], v15, 1.0 op_sel:[1,0,0]
	v_pk_fma_f32 v[108:109], v[40:41], v[44:45], v[108:109] op_sel_hi:[0,1,1]
	v_cvt_scalef32_pk_f32_fp4 v[42:43], v15, 1.0 op_sel:[0,1,0]
	v_pk_fma_f32 v[106:107], v[40:41], v[42:43], v[106:107] op_sel_hi:[0,1,1]
	v_cvt_scalef32_pk_f32_fp4 v[44:45], v15, 1.0 op_sel:[1,1,0]
	v_pk_fma_f32 v[104:105], v[40:41], v[44:45], v[104:105] op_sel_hi:[0,1,1]
	s_waitcnt lgkmcnt(0)
	v_lshlrev_b32_e32 v32, 9, v32
	v_lshl_add_u64 v[36:37], v[32:33], 0, v[66:67]
	global_load_dwordx4 v[8:11], v[36:37], off
	global_load_dwordx4 v[12:15], v[36:37], off offset:256
	ds_read_b32 v34, v77 offset:48
	ds_read_b32 v40, v77 offset:1024
	s_waitcnt vmcnt(7)
; static __device__ __forceinline__ void phase_peer(const Params& p, char* smraw) {
;     ...
;       GLOADV(va, aa, 0); GLOADV(vb, ab, 1); GLOADV(vc, ac, 2);
; #pragma unroll 1
;       for (int it = 0; it < 32; it += 4) {
;         GLOADV(vd, ad, it + 3);
;         GCOMPV(va, aa);
;         if (it + 4 < 32) GLOADV(va, aa, it + 4);
;         GCOMPV(vb, ab);
;         if (it + 5 < 32) GLOADV(vb, ab, it + 5);
;         GCOMPV(vc, ac);
;         if (it + 6 < 32) GLOADV(vc, ac, it + 6);
;         GCOMPV(vd, ad);
;       }
	v_cvt_scalef32_pk_f32_fp4 v[42:43], v16, 1.0
	v_pk_fma_f32 v[166:167], v[38:39], v[42:43], v[166:167] op_sel_hi:[0,1,1]
	v_cvt_scalef32_pk_f32_fp4 v[44:45], v16, 1.0 op_sel:[1,0,0]
	v_pk_fma_f32 v[164:165], v[38:39], v[44:45], v[164:165] op_sel_hi:[0,1,1]
	v_cvt_scalef32_pk_f32_fp4 v[42:43], v16, 1.0 op_sel:[0,1,0]
	v_pk_fma_f32 v[162:163], v[38:39], v[42:43], v[162:163] op_sel_hi:[0,1,1]
	v_cvt_scalef32_pk_f32_fp4 v[44:45], v16, 1.0 op_sel:[1,1,0]
	v_pk_fma_f32 v[160:161], v[38:39], v[44:45], v[160:161] op_sel_hi:[0,1,1]
	v_cvt_scalef32_pk_f32_fp4 v[42:43], v17, 1.0
	v_pk_fma_f32 v[158:159], v[38:39], v[42:43], v[158:159] op_sel_hi:[0,1,1]
	v_cvt_scalef32_pk_f32_fp4 v[44:45], v17, 1.0 op_sel:[1,0,0]
	v_pk_fma_f32 v[156:157], v[38:39], v[44:45], v[156:157] op_sel_hi:[0,1,1]
	v_cvt_scalef32_pk_f32_fp4 v[42:43], v17, 1.0 op_sel:[0,1,0]
	v_pk_fma_f32 v[154:155], v[38:39], v[42:43], v[154:155] op_sel_hi:[0,1,1]
	v_cvt_scalef32_pk_f32_fp4 v[44:45], v17, 1.0 op_sel:[1,1,0]
	v_pk_fma_f32 v[152:153], v[38:39], v[44:45], v[152:153] op_sel_hi:[0,1,1]
	v_cvt_scalef32_pk_f32_fp4 v[42:43], v18, 1.0
	v_pk_fma_f32 v[150:151], v[38:39], v[42:43], v[150:151] op_sel_hi:[0,1,1]
	v_cvt_scalef32_pk_f32_fp4 v[44:45], v18, 1.0 op_sel:[1,0,0]
	v_pk_fma_f32 v[148:149], v[38:39], v[44:45], v[148:149] op_sel_hi:[0,1,1]
	v_cvt_scalef32_pk_f32_fp4 v[42:43], v18, 1.0 op_sel:[0,1,0]
	v_pk_fma_f32 v[146:147], v[38:39], v[42:43], v[146:147] op_sel_hi:[0,1,1]
	v_cvt_scalef32_pk_f32_fp4 v[44:45], v18, 1.0 op_sel:[1,1,0]
	v_pk_fma_f32 v[144:145], v[38:39], v[44:45], v[144:145] op_sel_hi:[0,1,1]
	v_cvt_scalef32_pk_f32_fp4 v[42:43], v19, 1.0
	v_pk_fma_f32 v[142:143], v[38:39], v[42:43], v[142:143] op_sel_hi:[0,1,1]
	v_cvt_scalef32_pk_f32_fp4 v[44:45], v19, 1.0 op_sel:[1,0,0]
	v_pk_fma_f32 v[140:141], v[38:39], v[44:45], v[140:141] op_sel_hi:[0,1,1]
	v_cvt_scalef32_pk_f32_fp4 v[42:43], v19, 1.0 op_sel:[0,1,0]
	v_pk_fma_f32 v[138:139], v[38:39], v[42:43], v[138:139] op_sel_hi:[0,1,1]
	v_cvt_scalef32_pk_f32_fp4 v[44:45], v19, 1.0 op_sel:[1,1,0]
	v_pk_fma_f32 v[136:137], v[38:39], v[44:45], v[136:137] op_sel_hi:[0,1,1]
	s_waitcnt vmcnt(6)
	v_cvt_scalef32_pk_f32_fp4 v[42:43], v20, 1.0
	v_pk_fma_f32 v[134:135], v[38:39], v[42:43], v[134:135] op_sel_hi:[0,1,1]
	v_cvt_scalef32_pk_f32_fp4 v[44:45], v20, 1.0 op_sel:[1,0,0]
	v_pk_fma_f32 v[132:133], v[38:39], v[44:45], v[132:133] op_sel_hi:[0,1,1]
	v_cvt_scalef32_pk_f32_fp4 v[42:43], v20, 1.0 op_sel:[0,1,0]
	v_pk_fma_f32 v[130:131], v[38:39], v[42:43], v[130:131] op_sel_hi:[0,1,1]
	v_cvt_scalef32_pk_f32_fp4 v[44:45], v20, 1.0 op_sel:[1,1,0]
	v_pk_fma_f32 v[128:129], v[38:39], v[44:45], v[128:129] op_sel_hi:[0,1,1]
	v_cvt_scalef32_pk_f32_fp4 v[42:43], v21, 1.0
	v_pk_fma_f32 v[126:127], v[38:39], v[42:43], v[126:127] op_sel_hi:[0,1,1]
	v_cvt_scalef32_pk_f32_fp4 v[44:45], v21, 1.0 op_sel:[1,0,0]
	v_pk_fma_f32 v[124:125], v[38:39], v[44:45], v[124:125] op_sel_hi:[0,1,1]
	v_cvt_scalef32_pk_f32_fp4 v[42:43], v21, 1.0 op_sel:[0,1,0]
	v_pk_fma_f32 v[122:123], v[38:39], v[42:43], v[122:123] op_sel_hi:[0,1,1]
	v_cvt_scalef32_pk_f32_fp4 v[44:45], v21, 1.0 op_sel:[1,1,0]
	v_pk_fma_f32 v[120:121], v[38:39], v[44:45], v[120:121] op_sel_hi:[0,1,1]
	v_cvt_scalef32_pk_f32_fp4 v[42:43], v22, 1.0
	v_pk_fma_f32 v[118:119], v[38:39], v[42:43], v[118:119] op_sel_hi:[0,1,1]
	v_cvt_scalef32_pk_f32_fp4 v[44:45], v22, 1.0 op_sel:[1,0,0]
	v_pk_fma_f32 v[116:117], v[38:39], v[44:45], v[116:117] op_sel_hi:[0,1,1]
	v_cvt_scalef32_pk_f32_fp4 v[42:43], v22, 1.0 op_sel:[0,1,0]
	v_pk_fma_f32 v[114:115], v[38:39], v[42:43], v[114:115] op_sel_hi:[0,1,1]
	v_cvt_scalef32_pk_f32_fp4 v[44:45], v22, 1.0 op_sel:[1,1,0]
	v_pk_fma_f32 v[112:113], v[38:39], v[44:45], v[112:113] op_sel_hi:[0,1,1]
	v_cvt_scalef32_pk_f32_fp4 v[42:43], v23, 1.0
	v_pk_fma_f32 v[110:111], v[38:39], v[42:43], v[110:111] op_sel_hi:[0,1,1]
	v_cvt_scalef32_pk_f32_fp4 v[44:45], v23, 1.0 op_sel:[1,0,0]
	v_pk_fma_f32 v[108:109], v[38:39], v[44:45], v[108:109] op_sel_hi:[0,1,1]
	v_cvt_scalef32_pk_f32_fp4 v[42:43], v23, 1.0 op_sel:[0,1,0]
	v_pk_fma_f32 v[106:107], v[38:39], v[42:43], v[106:107] op_sel_hi:[0,1,1]
	v_cvt_scalef32_pk_f32_fp4 v[44:45], v23, 1.0 op_sel:[1,1,0]
	v_pk_fma_f32 v[104:105], v[38:39], v[44:45], v[104:105] op_sel_hi:[0,1,1]
	s_waitcnt lgkmcnt(0)
	v_lshlrev_b32_e32 v34, 9, v34
	v_lshl_add_u64 v[36:37], v[34:35], 0, v[66:67]
	global_load_dwordx4 v[16:19], v[36:37], off
	global_load_dwordx4 v[20:23], v[36:37], off offset:256
	ds_read_b32 v32, v77 offset:64
	ds_read_b32 v38, v77 offset:1040
	s_waitcnt vmcnt(7)
	v_cvt_scalef32_pk_f32_fp4 v[42:43], v24, 1.0
	v_pk_fma_f32 v[166:167], v[40:41], v[42:43], v[166:167] op_sel_hi:[0,1,1]
	v_cvt_scalef32_pk_f32_fp4 v[44:45], v24, 1.0 op_sel:[1,0,0]
	v_pk_fma_f32 v[164:165], v[40:41], v[44:45], v[164:165] op_sel_hi:[0,1,1]
	v_cvt_scalef32_pk_f32_fp4 v[42:43], v24, 1.0 op_sel:[0,1,0]
	v_pk_fma_f32 v[162:163], v[40:41], v[42:43], v[162:163] op_sel_hi:[0,1,1]
	v_cvt_scalef32_pk_f32_fp4 v[44:45], v24, 1.0 op_sel:[1,1,0]
	v_pk_fma_f32 v[160:161], v[40:41], v[44:45], v[160:161] op_sel_hi:[0,1,1]
	v_cvt_scalef32_pk_f32_fp4 v[42:43], v25, 1.0
	v_pk_fma_f32 v[158:159], v[40:41], v[42:43], v[158:159] op_sel_hi:[0,1,1]
	v_cvt_scalef32_pk_f32_fp4 v[44:45], v25, 1.0 op_sel:[1,0,0]
	v_pk_fma_f32 v[156:157], v[40:41], v[44:45], v[156:157] op_sel_hi:[0,1,1]
	v_cvt_scalef32_pk_f32_fp4 v[42:43], v25, 1.0 op_sel:[0,1,0]
	v_pk_fma_f32 v[154:155], v[40:41], v[42:43], v[154:155] op_sel_hi:[0,1,1]
	v_cvt_scalef32_pk_f32_fp4 v[44:45], v25, 1.0 op_sel:[1,1,0]
	v_pk_fma_f32 v[152:153], v[40:41], v[44:45], v[152:153] op_sel_hi:[0,1,1]
	v_cvt_scalef32_pk_f32_fp4 v[42:43], v26, 1.0
	v_pk_fma_f32 v[150:151], v[40:41], v[42:43], v[150:151] op_sel_hi:[0,1,1]
	v_cvt_scalef32_pk_f32_fp4 v[44:45], v26, 1.0 op_sel:[1,0,0]
	v_pk_fma_f32 v[148:149], v[40:41], v[44:45], v[148:149] op_sel_hi:[0,1,1]
	v_cvt_scalef32_pk_f32_fp4 v[42:43], v26, 1.0 op_sel:[0,1,0]
	v_pk_fma_f32 v[146:147], v[40:41], v[42:43], v[146:147] op_sel_hi:[0,1,1]
	v_cvt_scalef32_pk_f32_fp4 v[44:45], v26, 1.0 op_sel:[1,1,0]
	v_pk_fma_f32 v[144:145], v[40:41], v[44:45], v[144:145] op_sel_hi:[0,1,1]
	v_cvt_scalef32_pk_f32_fp4 v[42:43], v27, 1.0
	v_pk_fma_f32 v[142:143], v[40:41], v[42:43], v[142:143] op_sel_hi:[0,1,1]
	v_cvt_scalef32_pk_f32_fp4 v[44:45], v27, 1.0 op_sel:[1,0,0]
	v_pk_fma_f32 v[140:141], v[40:41], v[44:45], v[140:141] op_sel_hi:[0,1,1]
	v_cvt_scalef32_pk_f32_fp4 v[42:43], v27, 1.0 op_sel:[0,1,0]
	v_pk_fma_f32 v[138:139], v[40:41], v[42:43], v[138:139] op_sel_hi:[0,1,1]
	v_cvt_scalef32_pk_f32_fp4 v[44:45], v27, 1.0 op_sel:[1,1,0]
	v_pk_fma_f32 v[136:137], v[40:41], v[44:45], v[136:137] op_sel_hi:[0,1,1]
	s_waitcnt vmcnt(6)
; static __device__ __forceinline__ void phase_peer(const Params& p, char* smraw) {
;     ...
;       GLOADV(va, aa, 0); GLOADV(vb, ab, 1); GLOADV(vc, ac, 2);
; #pragma unroll 1
;       for (int it = 0; it < 32; it += 4) {
;         GLOADV(vd, ad, it + 3);
;         GCOMPV(va, aa);
;         if (it + 4 < 32) GLOADV(va, aa, it + 4);
;         GCOMPV(vb, ab);
;         if (it + 5 < 32) GLOADV(vb, ab, it + 5);
;         GCOMPV(vc, ac);
;         if (it + 6 < 32) GLOADV(vc, ac, it + 6);
;         GCOMPV(vd, ad);
;       }
	v_cvt_scalef32_pk_f32_fp4 v[42:43], v28, 1.0
	v_pk_fma_f32 v[134:135], v[40:41], v[42:43], v[134:135] op_sel_hi:[0,1,1]
	v_cvt_scalef32_pk_f32_fp4 v[44:45], v28, 1.0 op_sel:[1,0,0]
	v_pk_fma_f32 v[132:133], v[40:41], v[44:45], v[132:133] op_sel_hi:[0,1,1]
	v_cvt_scalef32_pk_f32_fp4 v[42:43], v28, 1.0 op_sel:[0,1,0]
	v_pk_fma_f32 v[130:131], v[40:41], v[42:43], v[130:131] op_sel_hi:[0,1,1]
	v_cvt_scalef32_pk_f32_fp4 v[44:45], v28, 1.0 op_sel:[1,1,0]
	v_pk_fma_f32 v[128:129], v[40:41], v[44:45], v[128:129] op_sel_hi:[0,1,1]
	v_cvt_scalef32_pk_f32_fp4 v[42:43], v29, 1.0
	v_pk_fma_f32 v[126:127], v[40:41], v[42:43], v[126:127] op_sel_hi:[0,1,1]
	v_cvt_scalef32_pk_f32_fp4 v[44:45], v29, 1.0 op_sel:[1,0,0]
	v_pk_fma_f32 v[124:125], v[40:41], v[44:45], v[124:125] op_sel_hi:[0,1,1]
	v_cvt_scalef32_pk_f32_fp4 v[42:43], v29, 1.0 op_sel:[0,1,0]
	v_pk_fma_f32 v[122:123], v[40:41], v[42:43], v[122:123] op_sel_hi:[0,1,1]
	v_cvt_scalef32_pk_f32_fp4 v[44:45], v29, 1.0 op_sel:[1,1,0]
	v_pk_fma_f32 v[120:121], v[40:41], v[44:45], v[120:121] op_sel_hi:[0,1,1]
	v_cvt_scalef32_pk_f32_fp4 v[42:43], v30, 1.0
	v_pk_fma_f32 v[118:119], v[40:41], v[42:43], v[118:119] op_sel_hi:[0,1,1]
	v_cvt_scalef32_pk_f32_fp4 v[44:45], v30, 1.0 op_sel:[1,0,0]
	v_pk_fma_f32 v[116:117], v[40:41], v[44:45], v[116:117] op_sel_hi:[0,1,1]
	v_cvt_scalef32_pk_f32_fp4 v[42:43], v30, 1.0 op_sel:[0,1,0]
	v_pk_fma_f32 v[114:115], v[40:41], v[42:43], v[114:115] op_sel_hi:[0,1,1]
	v_cvt_scalef32_pk_f32_fp4 v[44:45], v30, 1.0 op_sel:[1,1,0]
	v_pk_fma_f32 v[112:113], v[40:41], v[44:45], v[112:113] op_sel_hi:[0,1,1]
	v_cvt_scalef32_pk_f32_fp4 v[42:43], v31, 1.0
	v_pk_fma_f32 v[110:111], v[40:41], v[42:43], v[110:111] op_sel_hi:[0,1,1]
	v_cvt_scalef32_pk_f32_fp4 v[44:45], v31, 1.0 op_sel:[1,0,0]
	v_pk_fma_f32 v[108:109], v[40:41], v[44:45], v[108:109] op_sel_hi:[0,1,1]
	v_cvt_scalef32_pk_f32_fp4 v[42:43], v31, 1.0 op_sel:[0,1,0]
	v_pk_fma_f32 v[106:107], v[40:41], v[42:43], v[106:107] op_sel_hi:[0,1,1]
	v_cvt_scalef32_pk_f32_fp4 v[44:45], v31, 1.0 op_sel:[1,1,0]
	v_pk_fma_f32 v[104:105], v[40:41], v[44:45], v[104:105] op_sel_hi:[0,1,1]
	s_add_i32 s50, s50, 4
	v_add_u32_e32 v77, 64, v77
	s_waitcnt lgkmcnt(0)
	v_lshlrev_b32_e32 v32, 9, v32
	v_lshl_add_u64 v[36:37], v[32:33], 0, v[66:67]
	global_load_dwordx4 v[24:27], v[36:37], off
	global_load_dwordx4 v[28:31], v[36:37], off offset:256
	ds_read_b32 v34, v77 offset:16
	ds_read_b32 v40, v77 offset:992
	s_waitcnt vmcnt(7)
	v_cvt_scalef32_pk_f32_fp4 v[42:43], v0, 1.0
	v_pk_fma_f32 v[166:167], v[38:39], v[42:43], v[166:167] op_sel_hi:[0,1,1]
	v_cvt_scalef32_pk_f32_fp4 v[44:45], v0, 1.0 op_sel:[1,0,0]
	v_pk_fma_f32 v[164:165], v[38:39], v[44:45], v[164:165] op_sel_hi:[0,1,1]
	v_cvt_scalef32_pk_f32_fp4 v[42:43], v0, 1.0 op_sel:[0,1,0]
	v_pk_fma_f32 v[162:163], v[38:39], v[42:43], v[162:163] op_sel_hi:[0,1,1]
	v_cvt_scalef32_pk_f32_fp4 v[44:45], v0, 1.0 op_sel:[1,1,0]
	v_pk_fma_f32 v[160:161], v[38:39], v[44:45], v[160:161] op_sel_hi:[0,1,1]
	v_cvt_scalef32_pk_f32_fp4 v[42:43], v1, 1.0
	v_pk_fma_f32 v[158:159], v[38:39], v[42:43], v[158:159] op_sel_hi:[0,1,1]
	v_cvt_scalef32_pk_f32_fp4 v[44:45], v1, 1.0 op_sel:[1,0,0]
	v_pk_fma_f32 v[156:157], v[38:39], v[44:45], v[156:157] op_sel_hi:[0,1,1]
	v_cvt_scalef32_pk_f32_fp4 v[42:43], v1, 1.0 op_sel:[0,1,0]
	v_pk_fma_f32 v[154:155], v[38:39], v[42:43], v[154:155] op_sel_hi:[0,1,1]
	v_cvt_scalef32_pk_f32_fp4 v[44:45], v1, 1.0 op_sel:[1,1,0]
	v_pk_fma_f32 v[152:153], v[38:39], v[44:45], v[152:153] op_sel_hi:[0,1,1]
	v_cvt_scalef32_pk_f32_fp4 v[42:43], v2, 1.0
	v_pk_fma_f32 v[150:151], v[38:39], v[42:43], v[150:151] op_sel_hi:[0,1,1]
	v_cvt_scalef32_pk_f32_fp4 v[44:45], v2, 1.0 op_sel:[1,0,0]
	v_pk_fma_f32 v[148:149], v[38:39], v[44:45], v[148:149] op_sel_hi:[0,1,1]
	v_cvt_scalef32_pk_f32_fp4 v[42:43], v2, 1.0 op_sel:[0,1,0]
	v_pk_fma_f32 v[146:147], v[38:39], v[42:43], v[146:147] op_sel_hi:[0,1,1]
	v_cvt_scalef32_pk_f32_fp4 v[44:45], v2, 1.0 op_sel:[1,1,0]
	v_pk_fma_f32 v[144:145], v[38:39], v[44:45], v[144:145] op_sel_hi:[0,1,1]
	v_cvt_scalef32_pk_f32_fp4 v[42:43], v3, 1.0
	v_pk_fma_f32 v[142:143], v[38:39], v[42:43], v[142:143] op_sel_hi:[0,1,1]
	v_cvt_scalef32_pk_f32_fp4 v[44:45], v3, 1.0 op_sel:[1,0,0]
	v_pk_fma_f32 v[140:141], v[38:39], v[44:45], v[140:141] op_sel_hi:[0,1,1]
	v_cvt_scalef32_pk_f32_fp4 v[42:43], v3, 1.0 op_sel:[0,1,0]
	v_pk_fma_f32 v[138:139], v[38:39], v[42:43], v[138:139] op_sel_hi:[0,1,1]
	v_cvt_scalef32_pk_f32_fp4 v[44:45], v3, 1.0 op_sel:[1,1,0]
	v_pk_fma_f32 v[136:137], v[38:39], v[44:45], v[136:137] op_sel_hi:[0,1,1]
	s_waitcnt vmcnt(6)
	v_cvt_scalef32_pk_f32_fp4 v[42:43], v4, 1.0
	v_pk_fma_f32 v[134:135], v[38:39], v[42:43], v[134:135] op_sel_hi:[0,1,1]
	v_cvt_scalef32_pk_f32_fp4 v[44:45], v4, 1.0 op_sel:[1,0,0]
	v_pk_fma_f32 v[132:133], v[38:39], v[44:45], v[132:133] op_sel_hi:[0,1,1]
	v_cvt_scalef32_pk_f32_fp4 v[42:43], v4, 1.0 op_sel:[0,1,0]
	v_pk_fma_f32 v[130:131], v[38:39], v[42:43], v[130:131] op_sel_hi:[0,1,1]
	v_cvt_scalef32_pk_f32_fp4 v[44:45], v4, 1.0 op_sel:[1,1,0]
	v_pk_fma_f32 v[128:129], v[38:39], v[44:45], v[128:129] op_sel_hi:[0,1,1]
	v_cvt_scalef32_pk_f32_fp4 v[42:43], v5, 1.0
	v_pk_fma_f32 v[126:127], v[38:39], v[42:43], v[126:127] op_sel_hi:[0,1,1]
	v_cvt_scalef32_pk_f32_fp4 v[44:45], v5, 1.0 op_sel:[1,0,0]
	v_pk_fma_f32 v[124:125], v[38:39], v[44:45], v[124:125] op_sel_hi:[0,1,1]
	v_cvt_scalef32_pk_f32_fp4 v[42:43], v5, 1.0 op_sel:[0,1,0]
	v_pk_fma_f32 v[122:123], v[38:39], v[42:43], v[122:123] op_sel_hi:[0,1,1]
	v_cvt_scalef32_pk_f32_fp4 v[44:45], v5, 1.0 op_sel:[1,1,0]
	v_pk_fma_f32 v[120:121], v[38:39], v[44:45], v[120:121] op_sel_hi:[0,1,1]
	v_cvt_scalef32_pk_f32_fp4 v[42:43], v6, 1.0
	v_pk_fma_f32 v[118:119], v[38:39], v[42:43], v[118:119] op_sel_hi:[0,1,1]
	v_cvt_scalef32_pk_f32_fp4 v[44:45], v6, 1.0 op_sel:[1,0,0]
	v_pk_fma_f32 v[116:117], v[38:39], v[44:45], v[116:117] op_sel_hi:[0,1,1]
	v_cvt_scalef32_pk_f32_fp4 v[42:43], v6, 1.0 op_sel:[0,1,0]
	v_pk_fma_f32 v[114:115], v[38:39], v[42:43], v[114:115] op_sel_hi:[0,1,1]
	v_cvt_scalef32_pk_f32_fp4 v[44:45], v6, 1.0 op_sel:[1,1,0]
	v_pk_fma_f32 v[112:113], v[38:39], v[44:45], v[112:113] op_sel_hi:[0,1,1]
	v_cvt_scalef32_pk_f32_fp4 v[42:43], v7, 1.0
	v_pk_fma_f32 v[110:111], v[38:39], v[42:43], v[110:111] op_sel_hi:[0,1,1]
	v_cvt_scalef32_pk_f32_fp4 v[44:45], v7, 1.0 op_sel:[1,0,0]
	v_pk_fma_f32 v[108:109], v[38:39], v[44:45], v[108:109] op_sel_hi:[0,1,1]
	v_cvt_scalef32_pk_f32_fp4 v[42:43], v7, 1.0 op_sel:[0,1,0]
	v_pk_fma_f32 v[106:107], v[38:39], v[42:43], v[106:107] op_sel_hi:[0,1,1]
	v_cvt_scalef32_pk_f32_fp4 v[44:45], v7, 1.0 op_sel:[1,1,0]
	v_pk_fma_f32 v[104:105], v[38:39], v[44:45], v[104:105] op_sel_hi:[0,1,1]
	s_cmp_lt_u32 s50, 28
	s_cbranch_scc1 .Lpb_loop
; static __device__ __forceinline__ void phase_peer(const Params& p, char* smraw) {
;     ...
;       GLOADV(va, aa, 0); GLOADV(vb, ab, 1); GLOADV(vc, ac, 2);
; #pragma unroll 1
;       for (int it = 0; it < 32; it += 4) {
;         GLOADV(vd, ad, it + 3);
;         GCOMPV(va, aa);
;         if (it + 4 < 32) GLOADV(va, aa, it + 4);
;         GCOMPV(vb, ab);
;         if (it + 5 < 32) GLOADV(vb, ab, it + 5);
;         GCOMPV(vc, ac);
;         if (it + 6 < 32) GLOADV(vc, ac, it + 6);
;         GCOMPV(vd, ad);
;       }
	s_waitcnt lgkmcnt(0)
	ds_read_b32 v38, v77 offset:1008
	s_waitcnt vmcnt(5)
	v_cvt_scalef32_pk_f32_fp4 v[42:43], v8, 1.0
	v_pk_fma_f32 v[166:167], v[40:41], v[42:43], v[166:167] op_sel_hi:[0,1,1]
	v_cvt_scalef32_pk_f32_fp4 v[44:45], v8, 1.0 op_sel:[1,0,0]
	v_pk_fma_f32 v[164:165], v[40:41], v[44:45], v[164:165] op_sel_hi:[0,1,1]
	v_cvt_scalef32_pk_f32_fp4 v[42:43], v8, 1.0 op_sel:[0,1,0]
	v_pk_fma_f32 v[162:163], v[40:41], v[42:43], v[162:163] op_sel_hi:[0,1,1]
	v_cvt_scalef32_pk_f32_fp4 v[44:45], v8, 1.0 op_sel:[1,1,0]
	v_pk_fma_f32 v[160:161], v[40:41], v[44:45], v[160:161] op_sel_hi:[0,1,1]
	v_cvt_scalef32_pk_f32_fp4 v[42:43], v9, 1.0
	v_pk_fma_f32 v[158:159], v[40:41], v[42:43], v[158:159] op_sel_hi:[0,1,1]
	v_cvt_scalef32_pk_f32_fp4 v[44:45], v9, 1.0 op_sel:[1,0,0]
	v_pk_fma_f32 v[156:157], v[40:41], v[44:45], v[156:157] op_sel_hi:[0,1,1]
	v_cvt_scalef32_pk_f32_fp4 v[42:43], v9, 1.0 op_sel:[0,1,0]
	v_pk_fma_f32 v[154:155], v[40:41], v[42:43], v[154:155] op_sel_hi:[0,1,1]
	v_cvt_scalef32_pk_f32_fp4 v[44:45], v9, 1.0 op_sel:[1,1,0]
	v_pk_fma_f32 v[152:153], v[40:41], v[44:45], v[152:153] op_sel_hi:[0,1,1]
	v_cvt_scalef32_pk_f32_fp4 v[42:43], v10, 1.0
	v_pk_fma_f32 v[150:151], v[40:41], v[42:43], v[150:151] op_sel_hi:[0,1,1]
	v_cvt_scalef32_pk_f32_fp4 v[44:45], v10, 1.0 op_sel:[1,0,0]
	v_pk_fma_f32 v[148:149], v[40:41], v[44:45], v[148:149] op_sel_hi:[0,1,1]
	v_cvt_scalef32_pk_f32_fp4 v[42:43], v10, 1.0 op_sel:[0,1,0]
	v_pk_fma_f32 v[146:147], v[40:41], v[42:43], v[146:147] op_sel_hi:[0,1,1]
	v_cvt_scalef32_pk_f32_fp4 v[44:45], v10, 1.0 op_sel:[1,1,0]
	v_pk_fma_f32 v[144:145], v[40:41], v[44:45], v[144:145] op_sel_hi:[0,1,1]
	v_cvt_scalef32_pk_f32_fp4 v[42:43], v11, 1.0
	v_pk_fma_f32 v[142:143], v[40:41], v[42:43], v[142:143] op_sel_hi:[0,1,1]
	v_cvt_scalef32_pk_f32_fp4 v[44:45], v11, 1.0 op_sel:[1,0,0]
	v_pk_fma_f32 v[140:141], v[40:41], v[44:45], v[140:141] op_sel_hi:[0,1,1]
	v_cvt_scalef32_pk_f32_fp4 v[42:43], v11, 1.0 op_sel:[0,1,0]
	v_pk_fma_f32 v[138:139], v[40:41], v[42:43], v[138:139] op_sel_hi:[0,1,1]
	v_cvt_scalef32_pk_f32_fp4 v[44:45], v11, 1.0 op_sel:[1,1,0]
	v_pk_fma_f32 v[136:137], v[40:41], v[44:45], v[136:137] op_sel_hi:[0,1,1]
	s_waitcnt vmcnt(4)
	v_cvt_scalef32_pk_f32_fp4 v[42:43], v12, 1.0
	v_pk_fma_f32 v[134:135], v[40:41], v[42:43], v[134:135] op_sel_hi:[0,1,1]
	v_cvt_scalef32_pk_f32_fp4 v[44:45], v12, 1.0 op_sel:[1,0,0]
	v_pk_fma_f32 v[132:133], v[40:41], v[44:45], v[132:133] op_sel_hi:[0,1,1]
	v_cvt_scalef32_pk_f32_fp4 v[42:43], v12, 1.0 op_sel:[0,1,0]
	v_pk_fma_f32 v[130:131], v[40:41], v[42:43], v[130:131] op_sel_hi:[0,1,1]
	v_cvt_scalef32_pk_f32_fp4 v[44:45], v12, 1.0 op_sel:[1,1,0]
	v_pk_fma_f32 v[128:129], v[40:41], v[44:45], v[128:129] op_sel_hi:[0,1,1]
	v_cvt_scalef32_pk_f32_fp4 v[42:43], v13, 1.0
	v_pk_fma_f32 v[126:127], v[40:41], v[42:43], v[126:127] op_sel_hi:[0,1,1]
	v_cvt_scalef32_pk_f32_fp4 v[44:45], v13, 1.0 op_sel:[1,0,0]
	v_pk_fma_f32 v[124:125], v[40:41], v[44:45], v[124:125] op_sel_hi:[0,1,1]
	v_cvt_scalef32_pk_f32_fp4 v[42:43], v13, 1.0 op_sel:[0,1,0]
	v_pk_fma_f32 v[122:123], v[40:41], v[42:43], v[122:123] op_sel_hi:[0,1,1]
	v_cvt_scalef32_pk_f32_fp4 v[44:45], v13, 1.0 op_sel:[1,1,0]
	v_pk_fma_f32 v[120:121], v[40:41], v[44:45], v[120:121] op_sel_hi:[0,1,1]
	v_cvt_scalef32_pk_f32_fp4 v[42:43], v14, 1.0
	v_pk_fma_f32 v[118:119], v[40:41], v[42:43], v[118:119] op_sel_hi:[0,1,1]
	v_cvt_scalef32_pk_f32_fp4 v[44:45], v14, 1.0 op_sel:[1,0,0]
	v_pk_fma_f32 v[116:117], v[40:41], v[44:45], v[116:117] op_sel_hi:[0,1,1]
	v_cvt_scalef32_pk_f32_fp4 v[42:43], v14, 1.0 op_sel:[0,1,0]
	v_pk_fma_f32 v[114:115], v[40:41], v[42:43], v[114:115] op_sel_hi:[0,1,1]
	v_cvt_scalef32_pk_f32_fp4 v[44:45], v14, 1.0 op_sel:[1,1,0]
	v_pk_fma_f32 v[112:113], v[40:41], v[44:45], v[112:113] op_sel_hi:[0,1,1]
	v_cvt_scalef32_pk_f32_fp4 v[42:43], v15, 1.0
	v_pk_fma_f32 v[110:111], v[40:41], v[42:43], v[110:111] op_sel_hi:[0,1,1]
	v_cvt_scalef32_pk_f32_fp4 v[44:45], v15, 1.0 op_sel:[1,0,0]
	v_pk_fma_f32 v[108:109], v[40:41], v[44:45], v[108:109] op_sel_hi:[0,1,1]
	v_cvt_scalef32_pk_f32_fp4 v[42:43], v15, 1.0 op_sel:[0,1,0]
	v_pk_fma_f32 v[106:107], v[40:41], v[42:43], v[106:107] op_sel_hi:[0,1,1]
	v_cvt_scalef32_pk_f32_fp4 v[44:45], v15, 1.0 op_sel:[1,1,0]
	v_pk_fma_f32 v[104:105], v[40:41], v[44:45], v[104:105] op_sel_hi:[0,1,1]
	s_waitcnt lgkmcnt(0)
	ds_read_b32 v40, v77 offset:1024
	s_waitcnt vmcnt(3)
	v_cvt_scalef32_pk_f32_fp4 v[42:43], v16, 1.0
	v_pk_fma_f32 v[166:167], v[38:39], v[42:43], v[166:167] op_sel_hi:[0,1,1]
	v_cvt_scalef32_pk_f32_fp4 v[44:45], v16, 1.0 op_sel:[1,0,0]
	v_pk_fma_f32 v[164:165], v[38:39], v[44:45], v[164:165] op_sel_hi:[0,1,1]
	v_cvt_scalef32_pk_f32_fp4 v[42:43], v16, 1.0 op_sel:[0,1,0]
	v_pk_fma_f32 v[162:163], v[38:39], v[42:43], v[162:163] op_sel_hi:[0,1,1]
	v_cvt_scalef32_pk_f32_fp4 v[44:45], v16, 1.0 op_sel:[1,1,0]
	v_pk_fma_f32 v[160:161], v[38:39], v[44:45], v[160:161] op_sel_hi:[0,1,1]
	v_cvt_scalef32_pk_f32_fp4 v[42:43], v17, 1.0
	v_pk_fma_f32 v[158:159], v[38:39], v[42:43], v[158:159] op_sel_hi:[0,1,1]
	v_cvt_scalef32_pk_f32_fp4 v[44:45], v17, 1.0 op_sel:[1,0,0]
	v_pk_fma_f32 v[156:157], v[38:39], v[44:45], v[156:157] op_sel_hi:[0,1,1]
	v_cvt_scalef32_pk_f32_fp4 v[42:43], v17, 1.0 op_sel:[0,1,0]
	v_pk_fma_f32 v[154:155], v[38:39], v[42:43], v[154:155] op_sel_hi:[0,1,1]
	v_cvt_scalef32_pk_f32_fp4 v[44:45], v17, 1.0 op_sel:[1,1,0]
	v_pk_fma_f32 v[152:153], v[38:39], v[44:45], v[152:153] op_sel_hi:[0,1,1]
	v_cvt_scalef32_pk_f32_fp4 v[42:43], v18, 1.0
	v_pk_fma_f32 v[150:151], v[38:39], v[42:43], v[150:151] op_sel_hi:[0,1,1]
	v_cvt_scalef32_pk_f32_fp4 v[44:45], v18, 1.0 op_sel:[1,0,0]
	v_pk_fma_f32 v[148:149], v[38:39], v[44:45], v[148:149] op_sel_hi:[0,1,1]
	v_cvt_scalef32_pk_f32_fp4 v[42:43], v18, 1.0 op_sel:[0,1,0]
	v_pk_fma_f32 v[146:147], v[38:39], v[42:43], v[146:147] op_sel_hi:[0,1,1]
	v_cvt_scalef32_pk_f32_fp4 v[44:45], v18, 1.0 op_sel:[1,1,0]
	v_pk_fma_f32 v[144:145], v[38:39], v[44:45], v[144:145] op_sel_hi:[0,1,1]
	v_cvt_scalef32_pk_f32_fp4 v[42:43], v19, 1.0
	v_pk_fma_f32 v[142:143], v[38:39], v[42:43], v[142:143] op_sel_hi:[0,1,1]
	v_cvt_scalef32_pk_f32_fp4 v[44:45], v19, 1.0 op_sel:[1,0,0]
	v_pk_fma_f32 v[140:141], v[38:39], v[44:45], v[140:141] op_sel_hi:[0,1,1]
	v_cvt_scalef32_pk_f32_fp4 v[42:43], v19, 1.0 op_sel:[0,1,0]
	v_pk_fma_f32 v[138:139], v[38:39], v[42:43], v[138:139] op_sel_hi:[0,1,1]
	v_cvt_scalef32_pk_f32_fp4 v[44:45], v19, 1.0 op_sel:[1,1,0]
	v_pk_fma_f32 v[136:137], v[38:39], v[44:45], v[136:137] op_sel_hi:[0,1,1]
	s_waitcnt vmcnt(2)
; static __device__ __forceinline__ void phase_peer(const Params& p, char* smraw) {
;     ...
;       GLOADV(va, aa, 0); GLOADV(vb, ab, 1); GLOADV(vc, ac, 2);
; #pragma unroll 1
;       for (int it = 0; it < 32; it += 4) {
;         GLOADV(vd, ad, it + 3);
;         GCOMPV(va, aa);
;         if (it + 4 < 32) GLOADV(va, aa, it + 4);
;         GCOMPV(vb, ab);
;         if (it + 5 < 32) GLOADV(vb, ab, it + 5);
;         GCOMPV(vc, ac);
;         if (it + 6 < 32) GLOADV(vc, ac, it + 6);
;         GCOMPV(vd, ad);
;       }
	v_cvt_scalef32_pk_f32_fp4 v[42:43], v20, 1.0
	v_pk_fma_f32 v[134:135], v[38:39], v[42:43], v[134:135] op_sel_hi:[0,1,1]
	v_cvt_scalef32_pk_f32_fp4 v[44:45], v20, 1.0 op_sel:[1,0,0]
	v_pk_fma_f32 v[132:133], v[38:39], v[44:45], v[132:133] op_sel_hi:[0,1,1]
	v_cvt_scalef32_pk_f32_fp4 v[42:43], v20, 1.0 op_sel:[0,1,0]
	v_pk_fma_f32 v[130:131], v[38:39], v[42:43], v[130:131] op_sel_hi:[0,1,1]
	v_cvt_scalef32_pk_f32_fp4 v[44:45], v20, 1.0 op_sel:[1,1,0]
	v_pk_fma_f32 v[128:129], v[38:39], v[44:45], v[128:129] op_sel_hi:[0,1,1]
	v_cvt_scalef32_pk_f32_fp4 v[42:43], v21, 1.0
	v_pk_fma_f32 v[126:127], v[38:39], v[42:43], v[126:127] op_sel_hi:[0,1,1]
	v_cvt_scalef32_pk_f32_fp4 v[44:45], v21, 1.0 op_sel:[1,0,0]
	v_pk_fma_f32 v[124:125], v[38:39], v[44:45], v[124:125] op_sel_hi:[0,1,1]
	v_cvt_scalef32_pk_f32_fp4 v[42:43], v21, 1.0 op_sel:[0,1,0]
	v_pk_fma_f32 v[122:123], v[38:39], v[42:43], v[122:123] op_sel_hi:[0,1,1]
	v_cvt_scalef32_pk_f32_fp4 v[44:45], v21, 1.0 op_sel:[1,1,0]
	v_pk_fma_f32 v[120:121], v[38:39], v[44:45], v[120:121] op_sel_hi:[0,1,1]
	v_cvt_scalef32_pk_f32_fp4 v[42:43], v22, 1.0
	v_pk_fma_f32 v[118:119], v[38:39], v[42:43], v[118:119] op_sel_hi:[0,1,1]
	v_cvt_scalef32_pk_f32_fp4 v[44:45], v22, 1.0 op_sel:[1,0,0]
	v_pk_fma_f32 v[116:117], v[38:39], v[44:45], v[116:117] op_sel_hi:[0,1,1]
	v_cvt_scalef32_pk_f32_fp4 v[42:43], v22, 1.0 op_sel:[0,1,0]
	v_pk_fma_f32 v[114:115], v[38:39], v[42:43], v[114:115] op_sel_hi:[0,1,1]
	v_cvt_scalef32_pk_f32_fp4 v[44:45], v22, 1.0 op_sel:[1,1,0]
	v_pk_fma_f32 v[112:113], v[38:39], v[44:45], v[112:113] op_sel_hi:[0,1,1]
	v_cvt_scalef32_pk_f32_fp4 v[42:43], v23, 1.0
	v_pk_fma_f32 v[110:111], v[38:39], v[42:43], v[110:111] op_sel_hi:[0,1,1]
	v_cvt_scalef32_pk_f32_fp4 v[44:45], v23, 1.0 op_sel:[1,0,0]
	v_pk_fma_f32 v[108:109], v[38:39], v[44:45], v[108:109] op_sel_hi:[0,1,1]
	v_cvt_scalef32_pk_f32_fp4 v[42:43], v23, 1.0 op_sel:[0,1,0]
	v_pk_fma_f32 v[106:107], v[38:39], v[42:43], v[106:107] op_sel_hi:[0,1,1]
	v_cvt_scalef32_pk_f32_fp4 v[44:45], v23, 1.0 op_sel:[1,1,0]
	v_pk_fma_f32 v[104:105], v[38:39], v[44:45], v[104:105] op_sel_hi:[0,1,1]
	s_waitcnt lgkmcnt(0)
	s_waitcnt vmcnt(1)
	v_cvt_scalef32_pk_f32_fp4 v[42:43], v24, 1.0
	v_pk_fma_f32 v[166:167], v[40:41], v[42:43], v[166:167] op_sel_hi:[0,1,1]
	v_cvt_scalef32_pk_f32_fp4 v[44:45], v24, 1.0 op_sel:[1,0,0]
	v_pk_fma_f32 v[164:165], v[40:41], v[44:45], v[164:165] op_sel_hi:[0,1,1]
	v_cvt_scalef32_pk_f32_fp4 v[42:43], v24, 1.0 op_sel:[0,1,0]
	v_pk_fma_f32 v[162:163], v[40:41], v[42:43], v[162:163] op_sel_hi:[0,1,1]
	v_cvt_scalef32_pk_f32_fp4 v[44:45], v24, 1.0 op_sel:[1,1,0]
	v_pk_fma_f32 v[160:161], v[40:41], v[44:45], v[160:161] op_sel_hi:[0,1,1]
	v_cvt_scalef32_pk_f32_fp4 v[42:43], v25, 1.0
	v_pk_fma_f32 v[158:159], v[40:41], v[42:43], v[158:159] op_sel_hi:[0,1,1]
	v_cvt_scalef32_pk_f32_fp4 v[44:45], v25, 1.0 op_sel:[1,0,0]
	v_pk_fma_f32 v[156:157], v[40:41], v[44:45], v[156:157] op_sel_hi:[0,1,1]
	v_cvt_scalef32_pk_f32_fp4 v[42:43], v25, 1.0 op_sel:[0,1,0]
	v_pk_fma_f32 v[154:155], v[40:41], v[42:43], v[154:155] op_sel_hi:[0,1,1]
	v_cvt_scalef32_pk_f32_fp4 v[44:45], v25, 1.0 op_sel:[1,1,0]
	v_pk_fma_f32 v[152:153], v[40:41], v[44:45], v[152:153] op_sel_hi:[0,1,1]
	v_cvt_scalef32_pk_f32_fp4 v[42:43], v26, 1.0
	v_pk_fma_f32 v[150:151], v[40:41], v[42:43], v[150:151] op_sel_hi:[0,1,1]
	v_cvt_scalef32_pk_f32_fp4 v[44:45], v26, 1.0 op_sel:[1,0,0]
	v_pk_fma_f32 v[148:149], v[40:41], v[44:45], v[148:149] op_sel_hi:[0,1,1]
	v_cvt_scalef32_pk_f32_fp4 v[42:43], v26, 1.0 op_sel:[0,1,0]
	v_pk_fma_f32 v[146:147], v[40:41], v[42:43], v[146:147] op_sel_hi:[0,1,1]
	v_cvt_scalef32_pk_f32_fp4 v[44:45], v26, 1.0 op_sel:[1,1,0]
	v_pk_fma_f32 v[144:145], v[40:41], v[44:45], v[144:145] op_sel_hi:[0,1,1]
	v_cvt_scalef32_pk_f32_fp4 v[42:43], v27, 1.0
	v_pk_fma_f32 v[142:143], v[40:41], v[42:43], v[142:143] op_sel_hi:[0,1,1]
	v_cvt_scalef32_pk_f32_fp4 v[44:45], v27, 1.0 op_sel:[1,0,0]
	v_pk_fma_f32 v[140:141], v[40:41], v[44:45], v[140:141] op_sel_hi:[0,1,1]
	v_cvt_scalef32_pk_f32_fp4 v[42:43], v27, 1.0 op_sel:[0,1,0]
	v_pk_fma_f32 v[138:139], v[40:41], v[42:43], v[138:139] op_sel_hi:[0,1,1]
	v_cvt_scalef32_pk_f32_fp4 v[44:45], v27, 1.0 op_sel:[1,1,0]
	v_pk_fma_f32 v[136:137], v[40:41], v[44:45], v[136:137] op_sel_hi:[0,1,1]
	s_waitcnt vmcnt(0)
	v_cvt_scalef32_pk_f32_fp4 v[42:43], v28, 1.0
	v_pk_fma_f32 v[134:135], v[40:41], v[42:43], v[134:135] op_sel_hi:[0,1,1]
	v_cvt_scalef32_pk_f32_fp4 v[44:45], v28, 1.0 op_sel:[1,0,0]
	v_pk_fma_f32 v[132:133], v[40:41], v[44:45], v[132:133] op_sel_hi:[0,1,1]
	v_cvt_scalef32_pk_f32_fp4 v[42:43], v28, 1.0 op_sel:[0,1,0]
	v_pk_fma_f32 v[130:131], v[40:41], v[42:43], v[130:131] op_sel_hi:[0,1,1]
	v_cvt_scalef32_pk_f32_fp4 v[44:45], v28, 1.0 op_sel:[1,1,0]
	v_pk_fma_f32 v[128:129], v[40:41], v[44:45], v[128:129] op_sel_hi:[0,1,1]
	v_cvt_scalef32_pk_f32_fp4 v[42:43], v29, 1.0
	v_pk_fma_f32 v[126:127], v[40:41], v[42:43], v[126:127] op_sel_hi:[0,1,1]
	v_cvt_scalef32_pk_f32_fp4 v[44:45], v29, 1.0 op_sel:[1,0,0]
	v_pk_fma_f32 v[124:125], v[40:41], v[44:45], v[124:125] op_sel_hi:[0,1,1]
	v_cvt_scalef32_pk_f32_fp4 v[42:43], v29, 1.0 op_sel:[0,1,0]
	v_pk_fma_f32 v[122:123], v[40:41], v[42:43], v[122:123] op_sel_hi:[0,1,1]
	v_cvt_scalef32_pk_f32_fp4 v[44:45], v29, 1.0 op_sel:[1,1,0]
	v_pk_fma_f32 v[120:121], v[40:41], v[44:45], v[120:121] op_sel_hi:[0,1,1]
	v_cvt_scalef32_pk_f32_fp4 v[42:43], v30, 1.0
	v_pk_fma_f32 v[118:119], v[40:41], v[42:43], v[118:119] op_sel_hi:[0,1,1]
	v_cvt_scalef32_pk_f32_fp4 v[44:45], v30, 1.0 op_sel:[1,0,0]
	v_pk_fma_f32 v[116:117], v[40:41], v[44:45], v[116:117] op_sel_hi:[0,1,1]
	v_cvt_scalef32_pk_f32_fp4 v[42:43], v30, 1.0 op_sel:[0,1,0]
	v_pk_fma_f32 v[114:115], v[40:41], v[42:43], v[114:115] op_sel_hi:[0,1,1]
	v_cvt_scalef32_pk_f32_fp4 v[44:45], v30, 1.0 op_sel:[1,1,0]
	v_pk_fma_f32 v[112:113], v[40:41], v[44:45], v[112:113] op_sel_hi:[0,1,1]
	v_cvt_scalef32_pk_f32_fp4 v[42:43], v31, 1.0
	v_pk_fma_f32 v[110:111], v[40:41], v[42:43], v[110:111] op_sel_hi:[0,1,1]
	v_cvt_scalef32_pk_f32_fp4 v[44:45], v31, 1.0 op_sel:[1,0,0]
	v_pk_fma_f32 v[108:109], v[40:41], v[44:45], v[108:109] op_sel_hi:[0,1,1]
	v_cvt_scalef32_pk_f32_fp4 v[42:43], v31, 1.0 op_sel:[0,1,0]
	v_pk_fma_f32 v[106:107], v[40:41], v[42:43], v[106:107] op_sel_hi:[0,1,1]
	v_cvt_scalef32_pk_f32_fp4 v[44:45], v31, 1.0 op_sel:[1,1,0]
	v_pk_fma_f32 v[104:105], v[40:41], v[44:45], v[104:105] op_sel_hi:[0,1,1]
